# combo3 + cvt8 pass A issues each 16-load group one group earlier (32 weight loads in flight per wave)
# baseline (speedup 1.0000x reference)
.LBB0_41:
	s_ashr_i32 s51, s50, 31
	s_and_b64 s[0:1], s[52:53], exec
	s_cselect_b32 s1, s57, 0xd000000
	s_cselect_b32 s28, s6, s18
	s_mul_hi_i32 s54, s1, s50
	s_mul_i32 s1, s1, s50
	s_cselect_b32 s20, s7, s19
	s_cselect_b32 s69, s5, s11
	s_cselect_b32 s70, s4, s10
	s_cselect_b32 s0, s60, 0x3400
	s_add_u32 s1, s28, s1
	s_addc_u32 s20, s20, s54
	s_lshl_b64 s[54:55], s[50:51], 14
	s_add_u32 s28, s70, s54
	s_addc_u32 s51, s69, s55
	s_mul_hi_u32 s55, s0, s22
	s_mul_i32 s54, s0, s22
	s_lshl_b64 s[54:55], s[54:55], 2
	s_add_u32 s54, s1, s54
	s_addc_u32 s55, s20, s55
	s_add_u32 s70, s28, s36
	s_addc_u32 s71, s51, s37
	v_ashrrev_i32_e32 v3, 31, v2
	v_lshl_add_u64 v[12:13], v[2:3], 2, s[70:71]
	v_and_b32_e32 v3, 0x7fffe0, v2
	global_load_dword v26, v[12:13], off
	v_mul_u32_u24_e32 v3, s0, v3
	v_add_lshl_u32 v0, v0, v3, 2
	v_lshl_add_u64 v[6:7], s[54:55], 0, v[0:1]
	s_lshl_b32 s20, s0, 2
	v_lshl_add_u64 v[14:15], v[6:7], 0, s[20:21]
	global_load_dword v3, v[6:7], off
	global_load_dword v11, v[14:15], off
	s_lshl_b32 s20, s0, 3
	v_lshl_add_u64 v[14:15], v[6:7], 0, s[20:21]
	s_mul_i32 s20, s0, 12
	global_load_dword v20, v[14:15], off
	v_lshl_add_u64 v[14:15], v[6:7], 0, s[20:21]
	global_load_dword v21, v[14:15], off
	s_lshl_b32 s20, s0, 4
	v_lshl_add_u64 v[14:15], v[6:7], 0, s[20:21]
	global_load_dword v22, v[14:15], off
	s_mul_i32 s20, s0, 20
	v_lshl_add_u64 v[14:15], v[6:7], 0, s[20:21]
	global_load_dword v23, v[14:15], off
	s_mul_i32 s20, s0, 24
	v_lshl_add_u64 v[14:15], v[6:7], 0, s[20:21]
	global_load_dword v24, v[14:15], off
	s_mul_i32 s20, s0, 28
	v_lshl_add_u64 v[14:15], v[6:7], 0, s[20:21]
	global_load_dword v25, v[14:15], off
	s_lshl_b32 s20, s0, 5
	v_lshl_add_u64 v[14:15], v[6:7], 0, s[20:21]
	s_mul_i32 s20, s0, 36
	v_lshl_add_u64 v[16:17], v[6:7], 0, s[20:21]
	s_mul_i32 s20, s0, 40
	global_load_dword v27, v[14:15], off
	global_load_dword v28, v[16:17], off
	global_load_dword v34, v[12:13], off offset:256
	global_load_dword v56, v[12:13], off offset:512
	global_load_dword v72, v[12:13], off offset:768
	global_load_dword v89, v[12:13], off offset:1024
	global_load_dword v74, v[12:13], off offset:1280
	global_load_dword v5, v[12:13], off offset:1536
	global_load_dword v0, v[12:13], off offset:1792
	v_lshl_add_u64 v[12:13], v[6:7], 0, s[20:21]
	s_mul_i32 s20, s0, 44
	global_load_dword v29, v[12:13], off
	v_lshl_add_u64 v[12:13], v[6:7], 0, s[20:21]
	global_load_dword v30, v[12:13], off
	s_mul_i32 s20, s0, 48
	v_lshl_add_u64 v[12:13], v[6:7], 0, s[20:21]
	s_mul_i32 s20, s0, 52
	v_lshl_add_u64 v[14:15], v[6:7], 0, s[20:21]
	s_mul_i32 s20, s0, 56
	v_lshl_add_u64 v[16:17], v[6:7], 0, s[20:21]
	s_mul_i32 s20, s0, 60
	v_lshl_add_u64 v[18:19], v[6:7], 0, s[20:21]
	global_load_dword v12, v[12:13], off
	s_nop 0
	global_load_dword v13, v[14:15], off
	s_nop 0
	global_load_dword v14, v[16:17], off
	global_load_dword v15, v[18:19], off
	v_cmp_gt_u32_e32 vcc, 32, v2
	s_mov_b32 s101, 0
	s_mul_i32 s100, s0, 0x40
	v_lshl_add_u64 v[154:155], v[6:7], 0, s[100:101]
	global_load_dword v176, v[154:155], off
	s_mul_i32 s100, s0, 0x44
	v_lshl_add_u64 v[154:155], v[6:7], 0, s[100:101]
	global_load_dword v177, v[154:155], off
	s_mul_i32 s100, s0, 0x48
	v_lshl_add_u64 v[154:155], v[6:7], 0, s[100:101]
	global_load_dword v178, v[154:155], off
	s_mul_i32 s100, s0, 0x4c
	v_lshl_add_u64 v[154:155], v[6:7], 0, s[100:101]
	global_load_dword v179, v[154:155], off
	s_mul_i32 s100, s0, 0x50
	v_lshl_add_u64 v[154:155], v[6:7], 0, s[100:101]
	global_load_dword v180, v[154:155], off
	s_mul_i32 s100, s0, 0x54
	v_lshl_add_u64 v[154:155], v[6:7], 0, s[100:101]
	global_load_dword v181, v[154:155], off
	s_mul_i32 s100, s0, 0x58
	v_lshl_add_u64 v[154:155], v[6:7], 0, s[100:101]
	global_load_dword v182, v[154:155], off
	s_mul_i32 s100, s0, 0x5c
	v_lshl_add_u64 v[154:155], v[6:7], 0, s[100:101]
	global_load_dword v183, v[154:155], off
	s_mul_i32 s100, s0, 0x60
	v_lshl_add_u64 v[154:155], v[6:7], 0, s[100:101]
	global_load_dword v184, v[154:155], off
	s_mul_i32 s100, s0, 0x64
	v_lshl_add_u64 v[154:155], v[6:7], 0, s[100:101]
	global_load_dword v185, v[154:155], off
	s_mul_i32 s100, s0, 0x68
	v_lshl_add_u64 v[154:155], v[6:7], 0, s[100:101]
	global_load_dword v186, v[154:155], off
	s_mul_i32 s100, s0, 0x6c
	v_lshl_add_u64 v[154:155], v[6:7], 0, s[100:101]
	global_load_dword v187, v[154:155], off
	s_mul_i32 s100, s0, 0x70
	v_lshl_add_u64 v[154:155], v[6:7], 0, s[100:101]
	global_load_dword v188, v[154:155], off
	s_mul_i32 s100, s0, 0x74
	v_lshl_add_u64 v[154:155], v[6:7], 0, s[100:101]
	global_load_dword v189, v[154:155], off
	s_mul_i32 s100, s0, 0x78
	v_lshl_add_u64 v[154:155], v[6:7], 0, s[100:101]
	global_load_dword v190, v[154:155], off
	s_mul_i32 s100, s0, 0x7c
	v_lshl_add_u64 v[154:155], v[6:7], 0, s[100:101]
	global_load_dword v191, v[154:155], off
	s_waitcnt vmcnt(16) lgkmcnt(0)
	v_readlane_b32 s1, v26, 0
	v_readlane_b32 s20, v26, 32
	v_readlane_b32 s28, v26, 1
	v_readlane_b32 s51, v26, 33
	v_mov_b32_e32 v16, s20
	v_mov_b32_e32 v17, s1
	v_mov_b32_e32 v18, s51
	v_mov_b32_e32 v19, s28
	v_readlane_b32 s54, v26, 2
	v_readlane_b32 s55, v26, 34
	v_cndmask_b32_e32 v16, v16, v17, vcc
	v_cndmask_b32_e32 v17, v18, v19, vcc
	v_mul_f32_e32 v3, v3, v16
	v_mul_f32_e32 v11, v11, v17
	v_mov_b32_e32 v16, s55
	v_mov_b32_e32 v17, s54
	v_readlane_b32 s1, v26, 3
	v_readlane_b32 s20, v26, 35
	v_cndmask_b32_e32 v16, v16, v17, vcc
	v_mov_b32_e32 v18, s1
	v_mov_b32_e32 v17, s20
	v_cndmask_b32_e32 v17, v17, v18, vcc
	v_readlane_b32 s1, v26, 4
	v_readlane_b32 s20, v26, 36
	v_mul_f32_e32 v18, v21, v17
	v_mov_b32_e32 v19, s1
	v_mov_b32_e32 v17, s20
	v_cndmask_b32_e32 v17, v17, v19, vcc
	v_readlane_b32 s1, v26, 5
	v_readlane_b32 s20, v26, 37
	v_mul_f32_e32 v16, v20, v16
	v_mul_f32_e32 v19, v22, v17
	v_mov_b32_e32 v17, s20
	v_mov_b32_e32 v20, s1
	v_cndmask_b32_e32 v17, v17, v20, vcc
	v_readlane_b32 s1, v26, 6
	v_readlane_b32 s20, v26, 38
	v_mul_f32_e32 v20, v23, v17
	v_mov_b32_e32 v21, s1
	v_mov_b32_e32 v17, s20
	v_cndmask_b32_e32 v17, v17, v21, vcc
	v_readlane_b32 s1, v26, 7
	v_readlane_b32 s20, v26, 39
	v_mul_f32_e32 v21, v24, v17
	v_mov_b32_e32 v22, s1
	v_mov_b32_e32 v17, s20
	v_cndmask_b32_e32 v17, v17, v22, vcc
	v_readlane_b32 s1, v26, 8
	v_readlane_b32 s20, v26, 40
	v_mul_f32_e32 v22, v25, v17
	v_mov_b32_e32 v23, s1
	v_mov_b32_e32 v17, s20
	v_cndmask_b32_e32 v17, v17, v23, vcc
	v_readlane_b32 s1, v26, 9
	v_readlane_b32 s20, v26, 41
	v_mul_f32_e32 v23, v27, v17
	v_mov_b32_e32 v24, s1
	v_mov_b32_e32 v17, s20
	v_cndmask_b32_e32 v17, v17, v24, vcc
	v_readlane_b32 s1, v26, 10
	v_readlane_b32 s20, v26, 42
	v_mul_f32_e32 v24, v28, v17
	v_mov_b32_e32 v25, s1
	v_mov_b32_e32 v17, s20
	v_cndmask_b32_e32 v17, v17, v25, vcc
	v_readlane_b32 s1, v26, 11
	v_readlane_b32 s20, v26, 43
	v_mul_f32_e32 v25, v29, v17
	v_mov_b32_e32 v27, s1
	v_mov_b32_e32 v17, s20
	v_cndmask_b32_e32 v17, v17, v27, vcc
	v_readlane_b32 s1, v26, 12
	v_readlane_b32 s20, v26, 44
	v_mul_f32_e32 v27, v30, v17
	v_mov_b32_e32 v28, s1
	v_mov_b32_e32 v17, s20
	v_cndmask_b32_e32 v17, v17, v28, vcc
	v_readlane_b32 s1, v26, 13
	v_readlane_b32 s20, v26, 45
	v_mul_f32_e32 v28, v12, v17
	v_mov_b32_e32 v17, s1
	v_mov_b32_e32 v12, s20
	v_cndmask_b32_e32 v12, v12, v17, vcc
	v_readlane_b32 s1, v26, 14
	v_readlane_b32 s20, v26, 46
	v_mul_f32_e32 v29, v13, v12
	v_mov_b32_e32 v13, s1
	v_mov_b32_e32 v12, s20
	v_cndmask_b32_e32 v12, v12, v13, vcc
	v_readlane_b32 s1, v26, 15
	v_readlane_b32 s20, v26, 47
	v_mul_f32_e32 v30, v14, v12
	v_mov_b32_e32 v13, s1
	v_mov_b32_e32 v12, s20
	v_cvt_pk_bf16_f32 v17, v3, v11
	v_cndmask_b32_e32 v12, v12, v13, vcc
	v_lshlrev_b32_e32 v3, 16, v17
	v_and_b32_e32 v11, 0xffff0000, v17
	v_max_f32_e64 v11, |v11|, |v11|
	v_max_f32_e64 v3, |v3|, |v3|
	v_mul_f32_e32 v31, v15, v12
	v_max_f32_e32 v3, v3, v11
	v_cvt_pk_bf16_f32 v16, v16, v18
	v_cvt_pk_bf16_f32 v15, v19, v20
	s_lshl_b32 s20, s0, 6
	v_lshlrev_b32_e32 v11, 16, v16
	v_and_b32_e32 v12, 0xffff0000, v16
	v_max_f32_e64 v12, |v12|, |v12|
	v_max_f32_e64 v11, |v11|, |v11|
	v_max_f32_e32 v11, v11, v12
	v_max3_f32 v32, v3, 0, v11
	v_lshlrev_b32_e32 v3, 16, v15
	v_and_b32_e32 v11, 0xffff0000, v15
	v_max_f32_e64 v20, |v11|, |v11|
	v_max_f32_e64 v33, |v3|, |v3|
	v_cvt_pk_bf16_f32 v14, v21, v22
	v_cvt_pk_bf16_f32 v13, v23, v24
	v_cvt_pk_bf16_f32 v12, v25, v27
	v_cvt_pk_bf16_f32 v11, v28, v29
	v_cvt_pk_bf16_f32 v3, v30, v31
	v_lshl_add_u64 v[18:19], v[6:7], 0, s[20:21]
	s_mul_i32 s20, s0, 0x44
	v_lshlrev_b32_e32 v21, 16, v14
	v_and_b32_e32 v22, 0xffff0000, v14
	v_lshl_add_u64 v[18:19], v[6:7], 0, s[20:21]
	v_max_f32_e64 v18, |v22|, |v22|
	v_max_f32_e64 v19, |v21|, |v21|
	s_mul_i32 s20, s0, 0x48
	v_max_f32_e32 v20, v33, v20
	v_max_f32_e32 v21, v19, v18
	v_lshl_add_u64 v[18:19], v[6:7], 0, s[20:21]
	s_mul_i32 s20, s0, 0x4c
	v_max3_f32 v20, v32, v20, v21
	v_lshlrev_b32_e32 v21, 16, v13
	v_and_b32_e32 v22, 0xffff0000, v13
	v_lshl_add_u64 v[18:19], v[6:7], 0, s[20:21]
	v_max_f32_e64 v18, |v22|, |v22|
	v_max_f32_e64 v19, |v21|, |v21|
	s_mul_i32 s20, s0, 0x50
	v_max_f32_e32 v21, v19, v18
	v_lshl_add_u64 v[18:19], v[6:7], 0, s[20:21]
	v_and_b32_e32 v18, 0xffff0000, v12
	s_mul_i32 s20, s0, 0x54
	v_lshlrev_b32_e32 v22, 16, v12
	v_max_f32_e64 v23, |v18|, |v18|
	v_lshl_add_u64 v[18:19], v[6:7], 0, s[20:21]
	v_max_f32_e64 v18, |v22|, |v22|
	v_max_f32_e32 v18, v18, v23
	s_mul_i32 s20, s0, 0x58
	v_max3_f32 v20, v20, v21, v18
	v_lshl_add_u64 v[18:19], v[6:7], 0, s[20:21]
	v_and_b32_e32 v18, 0xffff0000, v11
	s_mul_i32 s20, s0, 0x5c
	v_lshlrev_b32_e32 v21, 16, v11
	v_max_f32_e64 v22, |v18|, |v18|
	v_lshl_add_u64 v[18:19], v[6:7], 0, s[20:21]
	v_max_f32_e64 v18, |v21|, |v21|
	s_mul_i32 s20, s0, 0x60
	v_max_f32_e32 v21, v18, v22
	v_lshl_add_u64 v[18:19], v[6:7], 0, s[20:21]
	v_lshlrev_b32_e32 v22, 16, v3
	v_and_b32_e32 v18, 0xffff0000, v3
	s_mul_i32 s20, s0, 0x64
	v_max_f32_e64 v23, |v18|, |v18|
	v_max_f32_e64 v22, |v22|, |v22|
	v_lshl_add_u64 v[18:19], v[6:7], 0, s[20:21]
	v_max_f32_e32 v18, v22, v23
	s_mul_i32 s20, s0, 0x68
	v_max3_f32 v38, v20, v21, v18
	v_lshl_add_u64 v[18:19], v[6:7], 0, s[20:21]
	s_mul_i32 s20, s0, 0x6c
	v_lshl_add_u64 v[18:19], v[6:7], 0, s[20:21]
	s_mul_i32 s20, s0, 0x70
	v_lshl_add_u64 v[18:19], v[6:7], 0, s[20:21]
	s_mul_i32 s20, s0, 0x74
	v_lshl_add_u64 v[20:21], v[6:7], 0, s[20:21]
	s_mul_i32 s20, s0, 0x78
	v_lshl_add_u64 v[22:23], v[6:7], 0, s[20:21]
	s_mul_i32 s20, s0, 0x7c
	v_lshl_add_u64 v[24:25], v[6:7], 0, s[20:21]
	s_nop 0
	s_nop 0
	v_readlane_b32 s1, v26, 16
	v_readlane_b32 s20, v26, 48
	s_nop 0
	v_mov_b32_e32 v23, s1
	v_mov_b32_e32 v22, s20
	v_readlane_b32 s1, v26, 17
	v_readlane_b32 s20, v26, 49
	v_cndmask_b32_e32 v22, v22, v23, vcc
	v_mov_b32_e32 v24, s1
	v_mov_b32_e32 v23, s20
	v_readlane_b32 s1, v26, 18
	v_readlane_b32 s20, v26, 50
	v_cndmask_b32_e32 v23, v23, v24, vcc
	v_mov_b32_e32 v25, s1
	v_mov_b32_e32 v24, s20
	v_readlane_b32 s1, v26, 19
	v_readlane_b32 s20, v26, 51
	s_mov_b32 s101, 0
	s_mul_i32 s100, s0, 0x100
	v_lshl_add_u64 v[154:155], v[6:7], 0, s[100:101]
	global_load_dword v160, v[154:155], off
	s_mul_i32 s100, s0, 0x104
	v_lshl_add_u64 v[154:155], v[6:7], 0, s[100:101]
	global_load_dword v161, v[154:155], off
	s_mul_i32 s100, s0, 0x108
	v_lshl_add_u64 v[154:155], v[6:7], 0, s[100:101]
	global_load_dword v162, v[154:155], off
	s_mul_i32 s100, s0, 0x10c
	v_lshl_add_u64 v[154:155], v[6:7], 0, s[100:101]
	global_load_dword v163, v[154:155], off
	s_mul_i32 s100, s0, 0x110
	v_lshl_add_u64 v[154:155], v[6:7], 0, s[100:101]
	global_load_dword v164, v[154:155], off
	s_mul_i32 s100, s0, 0x114
	v_lshl_add_u64 v[154:155], v[6:7], 0, s[100:101]
	global_load_dword v165, v[154:155], off
	s_mul_i32 s100, s0, 0x118
	v_lshl_add_u64 v[154:155], v[6:7], 0, s[100:101]
	global_load_dword v166, v[154:155], off
	s_mul_i32 s100, s0, 0x11c
	v_lshl_add_u64 v[154:155], v[6:7], 0, s[100:101]
	global_load_dword v167, v[154:155], off
	s_mul_i32 s100, s0, 0x120
	v_lshl_add_u64 v[154:155], v[6:7], 0, s[100:101]
	global_load_dword v168, v[154:155], off
	s_mul_i32 s100, s0, 0x124
	v_lshl_add_u64 v[154:155], v[6:7], 0, s[100:101]
	global_load_dword v169, v[154:155], off
	s_mul_i32 s100, s0, 0x128
	v_lshl_add_u64 v[154:155], v[6:7], 0, s[100:101]
	global_load_dword v170, v[154:155], off
	s_mul_i32 s100, s0, 0x12c
	v_lshl_add_u64 v[154:155], v[6:7], 0, s[100:101]
	global_load_dword v171, v[154:155], off
	s_mul_i32 s100, s0, 0x130
	v_lshl_add_u64 v[154:155], v[6:7], 0, s[100:101]
	global_load_dword v172, v[154:155], off
	s_mul_i32 s100, s0, 0x134
	v_lshl_add_u64 v[154:155], v[6:7], 0, s[100:101]
	global_load_dword v173, v[154:155], off
	s_mul_i32 s100, s0, 0x138
	v_lshl_add_u64 v[154:155], v[6:7], 0, s[100:101]
	global_load_dword v174, v[154:155], off
	s_mul_i32 s100, s0, 0x13c
	v_lshl_add_u64 v[154:155], v[6:7], 0, s[100:101]
	global_load_dword v175, v[154:155], off
	s_waitcnt vmcnt(16) lgkmcnt(0)
	v_mul_f32_e32 v22, v176, v22
	v_cndmask_b32_e32 v24, v24, v25, vcc
	v_mov_b32_e32 v25, s20
	v_mov_b32_e32 v27, s1
	v_cndmask_b32_e32 v25, v25, v27, vcc
	v_readlane_b32 s1, v26, 20
	v_readlane_b32 s20, v26, 52
	v_mul_f32_e32 v23, v177, v23
	v_mov_b32_e32 v28, s1
	v_mul_f32_e32 v27, v179, v25
	v_mov_b32_e32 v25, s20
	v_cndmask_b32_e32 v25, v25, v28, vcc
	v_readlane_b32 s1, v26, 21
	v_readlane_b32 s20, v26, 53
	v_mul_f32_e32 v24, v178, v24
	v_mul_f32_e32 v28, v180, v25
	v_mov_b32_e32 v25, s20
	v_mov_b32_e32 v29, s1
	v_cndmask_b32_e32 v25, v25, v29, vcc
	v_readlane_b32 s1, v26, 22
	v_readlane_b32 s20, v26, 54
	v_mul_f32_e32 v29, v181, v25
	v_mov_b32_e32 v30, s1
	v_mov_b32_e32 v25, s20
	v_cndmask_b32_e32 v25, v25, v30, vcc
	v_readlane_b32 s1, v26, 23
	v_readlane_b32 s20, v26, 55
	v_mul_f32_e32 v30, v182, v25
	v_mov_b32_e32 v31, s1
	v_mov_b32_e32 v25, s20
	v_cndmask_b32_e32 v25, v25, v31, vcc
	v_readlane_b32 s1, v26, 24
	v_readlane_b32 s20, v26, 56
	v_mul_f32_e32 v31, v183, v25
	v_mov_b32_e32 v32, s1
	v_mov_b32_e32 v25, s20
	v_cndmask_b32_e32 v25, v25, v32, vcc
	v_readlane_b32 s1, v26, 25
	v_readlane_b32 s20, v26, 57
	v_mul_f32_e32 v32, v184, v25
	v_mov_b32_e32 v33, s1
	v_mov_b32_e32 v25, s20
	v_cndmask_b32_e32 v25, v25, v33, vcc
	v_readlane_b32 s1, v26, 26
	v_readlane_b32 s20, v26, 58
	v_mul_f32_e32 v33, v185, v25
	v_mov_b32_e32 v35, s1
	v_mov_b32_e32 v25, s20
	v_cndmask_b32_e32 v25, v25, v35, vcc
	v_readlane_b32 s1, v26, 27
	v_readlane_b32 s20, v26, 59
	v_mul_f32_e32 v35, v186, v25
	v_mov_b32_e32 v36, s1
	v_mov_b32_e32 v25, s20
	v_cndmask_b32_e32 v25, v25, v36, vcc
	v_readlane_b32 s1, v26, 28
	v_readlane_b32 s20, v26, 60
	v_mul_f32_e32 v36, v187, v25
	v_mov_b32_e32 v37, s1
	v_mov_b32_e32 v25, s20
	v_cndmask_b32_e32 v25, v25, v37, vcc
	v_readlane_b32 s1, v26, 29
	v_readlane_b32 s20, v26, 61
	v_mul_f32_e32 v18, v188, v25
	v_mov_b32_e32 v37, s1
	v_mov_b32_e32 v25, s20
	v_cndmask_b32_e32 v25, v25, v37, vcc
	v_readlane_b32 s1, v26, 30
	v_readlane_b32 s20, v26, 62
	v_mul_f32_e32 v19, v189, v25
	v_mov_b32_e32 v37, s1
	v_mov_b32_e32 v25, s20
	v_cndmask_b32_e32 v25, v25, v37, vcc
	v_readlane_b32 s1, v26, 31
	v_readlane_b32 s20, v26, 63
	v_mul_f32_e32 v37, v190, v25
	v_mov_b32_e32 v25, s1
	v_mov_b32_e32 v20, s20
	v_cndmask_b32_e32 v20, v20, v25, vcc
	v_mul_f32_e32 v26, v191, v20
	v_cvt_pk_bf16_f32 v25, v22, v23
	v_cvt_pk_bf16_f32 v24, v24, v27
	v_cvt_pk_bf16_f32 v23, v28, v29
	s_lshl_b32 s20, s0, 8
	v_lshlrev_b32_e32 v20, 16, v25
	v_and_b32_e32 v21, 0xffff0000, v25
	v_max_f32_e64 v21, |v21|, |v21|
	v_max_f32_e64 v20, |v20|, |v20|
	v_max_f32_e32 v20, v20, v21
	v_lshlrev_b32_e32 v21, 16, v24
	v_and_b32_e32 v22, 0xffff0000, v24
	v_max_f32_e64 v22, |v22|, |v22|
	v_max_f32_e64 v21, |v21|, |v21|
	v_max_f32_e32 v21, v21, v22
	v_max3_f32 v38, v38, v20, v21
	v_lshlrev_b32_e32 v20, 16, v23
	v_and_b32_e32 v21, 0xffff0000, v23
	v_max_f32_e64 v28, |v21|, |v21|
	v_max_f32_e64 v29, |v20|, |v20|
	v_cvt_pk_bf16_f32 v22, v30, v31
	v_cvt_pk_bf16_f32 v21, v32, v33
	v_cvt_pk_bf16_f32 v20, v35, v36
	v_cvt_pk_bf16_f32 v19, v18, v19
	v_cvt_pk_bf16_f32 v18, v37, v26
	v_lshl_add_u64 v[26:27], v[6:7], 0, s[20:21]
	s_mul_i32 s20, s0, 0x104
	v_max_f32_e32 v28, v29, v28
	v_lshlrev_b32_e32 v29, 16, v22
	v_and_b32_e32 v30, 0xffff0000, v22
	v_lshl_add_u64 v[26:27], v[6:7], 0, s[20:21]
	v_max_f32_e64 v26, |v30|, |v30|
	v_max_f32_e64 v27, |v29|, |v29|
	s_mul_i32 s20, s0, 0x108
	v_max_f32_e32 v29, v27, v26
	v_lshl_add_u64 v[26:27], v[6:7], 0, s[20:21]
	s_mul_i32 s20, s0, 0x10c
	v_max3_f32 v28, v38, v28, v29
	v_lshlrev_b32_e32 v29, 16, v21
	v_and_b32_e32 v30, 0xffff0000, v21
	v_lshl_add_u64 v[26:27], v[6:7], 0, s[20:21]
	v_max_f32_e64 v26, |v30|, |v30|
	v_max_f32_e64 v27, |v29|, |v29|
	s_mul_i32 s20, s0, 0x110
	v_max_f32_e32 v29, v27, v26
	v_lshl_add_u64 v[26:27], v[6:7], 0, s[20:21]
	v_and_b32_e32 v26, 0xffff0000, v20
	s_mul_i32 s20, s0, 0x114
	v_lshlrev_b32_e32 v30, 16, v20
	v_max_f32_e64 v31, |v26|, |v26|
	v_lshl_add_u64 v[26:27], v[6:7], 0, s[20:21]
	v_max_f32_e64 v26, |v30|, |v30|
	v_max_f32_e32 v26, v26, v31
	s_mul_i32 s20, s0, 0x118
	v_max3_f32 v28, v28, v29, v26
	v_lshl_add_u64 v[26:27], v[6:7], 0, s[20:21]
	v_and_b32_e32 v26, 0xffff0000, v19
	s_mul_i32 s20, s0, 0x11c
	v_lshlrev_b32_e32 v29, 16, v19
	v_max_f32_e64 v30, |v26|, |v26|
	v_lshl_add_u64 v[26:27], v[6:7], 0, s[20:21]
	v_max_f32_e64 v26, |v29|, |v29|
	s_mul_i32 s20, s0, 0x120
	v_max_f32_e32 v29, v26, v30
	v_lshl_add_u64 v[26:27], v[6:7], 0, s[20:21]
	v_lshlrev_b32_e32 v30, 16, v18
	v_and_b32_e32 v26, 0xffff0000, v18
	s_mul_i32 s20, s0, 0x124
	v_max_f32_e64 v31, |v26|, |v26|
	v_max_f32_e64 v30, |v30|, |v30|
	v_lshl_add_u64 v[26:27], v[6:7], 0, s[20:21]
	v_max_f32_e32 v26, v30, v31
	s_mul_i32 s20, s0, 0x128
	v_max3_f32 v45, v28, v29, v26
	v_lshl_add_u64 v[26:27], v[6:7], 0, s[20:21]
	s_mul_i32 s20, s0, 0x12c
	v_lshl_add_u64 v[26:27], v[6:7], 0, s[20:21]
	s_mul_i32 s20, s0, 0x130
	v_lshl_add_u64 v[26:27], v[6:7], 0, s[20:21]
	s_mul_i32 s20, s0, 0x134
	v_lshl_add_u64 v[28:29], v[6:7], 0, s[20:21]
	s_mul_i32 s20, s0, 0x138
	v_lshl_add_u64 v[30:31], v[6:7], 0, s[20:21]
	s_mul_i32 s20, s0, 0x13c
	v_lshl_add_u64 v[32:33], v[6:7], 0, s[20:21]
	s_nop 0
	s_nop 0
	v_readlane_b32 s1, v34, 0
	v_readlane_b32 s20, v34, 32
	s_nop 0
	v_mov_b32_e32 v31, s1
	v_mov_b32_e32 v30, s20
	v_readlane_b32 s1, v34, 1
	v_readlane_b32 s20, v34, 33
	v_cndmask_b32_e32 v30, v30, v31, vcc
	v_mov_b32_e32 v32, s1
	v_mov_b32_e32 v31, s20
	v_readlane_b32 s1, v34, 2
	v_readlane_b32 s20, v34, 34
	v_cndmask_b32_e32 v31, v31, v32, vcc
	v_mov_b32_e32 v33, s1
	v_mov_b32_e32 v32, s20
	v_readlane_b32 s1, v34, 3
	v_readlane_b32 s20, v34, 35
	s_mov_b32 s101, 0
	s_mul_i32 s100, s0, 0x140
	v_lshl_add_u64 v[154:155], v[6:7], 0, s[100:101]
	global_load_dword v176, v[154:155], off
	s_mul_i32 s100, s0, 0x144
	v_lshl_add_u64 v[154:155], v[6:7], 0, s[100:101]
	global_load_dword v177, v[154:155], off
	s_mul_i32 s100, s0, 0x148
	v_lshl_add_u64 v[154:155], v[6:7], 0, s[100:101]
	global_load_dword v178, v[154:155], off
	s_mul_i32 s100, s0, 0x14c
	v_lshl_add_u64 v[154:155], v[6:7], 0, s[100:101]
	global_load_dword v179, v[154:155], off
	s_mul_i32 s100, s0, 0x150
	v_lshl_add_u64 v[154:155], v[6:7], 0, s[100:101]
	global_load_dword v180, v[154:155], off
	s_mul_i32 s100, s0, 0x154
	v_lshl_add_u64 v[154:155], v[6:7], 0, s[100:101]
	global_load_dword v181, v[154:155], off
	s_mul_i32 s100, s0, 0x158
	v_lshl_add_u64 v[154:155], v[6:7], 0, s[100:101]
	global_load_dword v182, v[154:155], off
	s_mul_i32 s100, s0, 0x15c
	v_lshl_add_u64 v[154:155], v[6:7], 0, s[100:101]
	global_load_dword v183, v[154:155], off
	s_mul_i32 s100, s0, 0x160
	v_lshl_add_u64 v[154:155], v[6:7], 0, s[100:101]
	global_load_dword v184, v[154:155], off
	s_mul_i32 s100, s0, 0x164
	v_lshl_add_u64 v[154:155], v[6:7], 0, s[100:101]
	global_load_dword v185, v[154:155], off
	s_mul_i32 s100, s0, 0x168
	v_lshl_add_u64 v[154:155], v[6:7], 0, s[100:101]
	global_load_dword v186, v[154:155], off
	s_mul_i32 s100, s0, 0x16c
	v_lshl_add_u64 v[154:155], v[6:7], 0, s[100:101]
	global_load_dword v187, v[154:155], off
	s_mul_i32 s100, s0, 0x170
	v_lshl_add_u64 v[154:155], v[6:7], 0, s[100:101]
	global_load_dword v188, v[154:155], off
	s_mul_i32 s100, s0, 0x174
	v_lshl_add_u64 v[154:155], v[6:7], 0, s[100:101]
	global_load_dword v189, v[154:155], off
	s_mul_i32 s100, s0, 0x178
	v_lshl_add_u64 v[154:155], v[6:7], 0, s[100:101]
	global_load_dword v190, v[154:155], off
	s_mul_i32 s100, s0, 0x17c
	v_lshl_add_u64 v[154:155], v[6:7], 0, s[100:101]
	global_load_dword v191, v[154:155], off
	s_waitcnt vmcnt(16) lgkmcnt(0)
	v_mul_f32_e32 v30, v160, v30
	v_cndmask_b32_e32 v32, v32, v33, vcc
	v_mov_b32_e32 v33, s20
	v_mov_b32_e32 v35, s1
	v_cndmask_b32_e32 v33, v33, v35, vcc
	v_readlane_b32 s1, v34, 4
	v_readlane_b32 s20, v34, 36
	v_mul_f32_e32 v31, v161, v31
	v_mov_b32_e32 v36, s1
	v_mul_f32_e32 v35, v163, v33
	v_mov_b32_e32 v33, s20
	v_cndmask_b32_e32 v33, v33, v36, vcc
	v_readlane_b32 s1, v34, 5
	v_readlane_b32 s20, v34, 37
	v_mul_f32_e32 v32, v162, v32
	v_mul_f32_e32 v36, v164, v33
	v_mov_b32_e32 v33, s20
	v_mov_b32_e32 v37, s1
	v_cndmask_b32_e32 v33, v33, v37, vcc
	v_readlane_b32 s1, v34, 6
	v_readlane_b32 s20, v34, 38
	v_mul_f32_e32 v37, v165, v33
	v_mov_b32_e32 v38, s1
	v_mov_b32_e32 v33, s20
	v_cndmask_b32_e32 v33, v33, v38, vcc
	v_readlane_b32 s1, v34, 7
	v_readlane_b32 s20, v34, 39
	v_mul_f32_e32 v38, v166, v33
	v_mov_b32_e32 v39, s1
	v_mov_b32_e32 v33, s20
	v_cndmask_b32_e32 v33, v33, v39, vcc
	v_readlane_b32 s1, v34, 8
	v_readlane_b32 s20, v34, 40
	v_mul_f32_e32 v39, v167, v33
	v_mov_b32_e32 v40, s1
	v_mov_b32_e32 v33, s20
	v_cndmask_b32_e32 v33, v33, v40, vcc
	v_readlane_b32 s1, v34, 9
	v_readlane_b32 s20, v34, 41
	v_mul_f32_e32 v40, v168, v33
	v_mov_b32_e32 v41, s1
	v_mov_b32_e32 v33, s20
	v_cndmask_b32_e32 v33, v33, v41, vcc
	v_readlane_b32 s1, v34, 10
	v_readlane_b32 s20, v34, 42
	v_mul_f32_e32 v41, v169, v33
	v_mov_b32_e32 v42, s1
	v_mov_b32_e32 v33, s20
	v_cndmask_b32_e32 v33, v33, v42, vcc
	v_readlane_b32 s1, v34, 11
	v_readlane_b32 s20, v34, 43
	v_mul_f32_e32 v42, v170, v33
	v_mov_b32_e32 v43, s1
	v_mov_b32_e32 v33, s20
	v_cndmask_b32_e32 v33, v33, v43, vcc
	v_readlane_b32 s1, v34, 12
	v_readlane_b32 s20, v34, 44
	v_mul_f32_e32 v43, v171, v33
	v_mov_b32_e32 v44, s1
	v_mov_b32_e32 v33, s20
	v_cndmask_b32_e32 v33, v33, v44, vcc
	v_readlane_b32 s1, v34, 13
	v_readlane_b32 s20, v34, 45
	v_mul_f32_e32 v26, v172, v33
	v_mov_b32_e32 v44, s1
	v_mov_b32_e32 v33, s20
	v_cndmask_b32_e32 v33, v33, v44, vcc
	v_readlane_b32 s1, v34, 14
	v_readlane_b32 s20, v34, 46
	v_mul_f32_e32 v27, v173, v33
	v_mov_b32_e32 v44, s1
	v_mov_b32_e32 v33, s20
	v_cndmask_b32_e32 v33, v33, v44, vcc
	v_readlane_b32 s1, v34, 15
	v_readlane_b32 s20, v34, 47
	v_mul_f32_e32 v44, v174, v33
	v_mov_b32_e32 v33, s1
	v_mov_b32_e32 v28, s20
	v_cndmask_b32_e32 v28, v28, v33, vcc
	v_mul_f32_e32 v46, v175, v28
	v_cvt_pk_bf16_f32 v33, v30, v31
	v_cvt_pk_bf16_f32 v32, v32, v35
	v_cvt_pk_bf16_f32 v31, v36, v37
	s_mul_i32 s20, s0, 0x140
	v_lshlrev_b32_e32 v28, 16, v33
	v_and_b32_e32 v29, 0xffff0000, v33
	v_max_f32_e64 v29, |v29|, |v29|
	v_max_f32_e64 v28, |v28|, |v28|
	v_max_f32_e32 v28, v28, v29
	v_lshlrev_b32_e32 v29, 16, v32
	v_and_b32_e32 v30, 0xffff0000, v32
	v_max_f32_e64 v30, |v30|, |v30|
	v_max_f32_e64 v29, |v29|, |v29|
	v_max_f32_e32 v29, v29, v30
	v_max3_f32 v35, v45, v28, v29
	v_lshlrev_b32_e32 v28, 16, v31
	v_and_b32_e32 v29, 0xffff0000, v31
	v_max_f32_e64 v45, |v29|, |v29|
	v_max_f32_e64 v47, |v28|, |v28|
	v_cvt_pk_bf16_f32 v30, v38, v39
	v_cvt_pk_bf16_f32 v29, v40, v41
	v_cvt_pk_bf16_f32 v28, v42, v43
	v_cvt_pk_bf16_f32 v27, v26, v27
	v_cvt_pk_bf16_f32 v26, v44, v46
	v_lshl_add_u64 v[36:37], v[6:7], 0, s[20:21]
	s_mul_i32 s20, s0, 0x144
	v_lshlrev_b32_e32 v39, 16, v30
	v_and_b32_e32 v40, 0xffff0000, v30
	v_lshl_add_u64 v[36:37], v[6:7], 0, s[20:21]
	v_max_f32_e32 v38, v47, v45
	v_max_f32_e64 v36, |v40|, |v40|
	v_max_f32_e64 v37, |v39|, |v39|
	s_mul_i32 s20, s0, 0x148
	v_max_f32_e32 v39, v37, v36
	v_lshl_add_u64 v[36:37], v[6:7], 0, s[20:21]
	s_mul_i32 s20, s0, 0x14c
	v_max3_f32 v35, v35, v38, v39
	v_lshlrev_b32_e32 v38, 16, v29
	v_and_b32_e32 v39, 0xffff0000, v29
	v_lshl_add_u64 v[36:37], v[6:7], 0, s[20:21]
	v_max_f32_e64 v36, |v39|, |v39|
	v_max_f32_e64 v37, |v38|, |v38|
	s_mul_i32 s20, s0, 0x150
	v_max_f32_e32 v38, v37, v36
	v_lshl_add_u64 v[36:37], v[6:7], 0, s[20:21]
	v_and_b32_e32 v36, 0xffff0000, v28
	s_mul_i32 s20, s0, 0x154
	v_lshlrev_b32_e32 v39, 16, v28
	v_max_f32_e64 v40, |v36|, |v36|
	v_lshl_add_u64 v[36:37], v[6:7], 0, s[20:21]
	v_max_f32_e64 v36, |v39|, |v39|
	v_max_f32_e32 v36, v36, v40
	s_mul_i32 s20, s0, 0x158
	v_max3_f32 v35, v35, v38, v36
	v_lshl_add_u64 v[36:37], v[6:7], 0, s[20:21]
	v_and_b32_e32 v36, 0xffff0000, v27
	s_mul_i32 s20, s0, 0x15c
	v_lshlrev_b32_e32 v38, 16, v27
	v_max_f32_e64 v39, |v36|, |v36|
	v_lshl_add_u64 v[36:37], v[6:7], 0, s[20:21]
	v_max_f32_e64 v36, |v38|, |v38|
	s_mul_i32 s20, s0, 0x160
	v_max_f32_e32 v38, v36, v39
	v_lshl_add_u64 v[36:37], v[6:7], 0, s[20:21]
	v_lshlrev_b32_e32 v39, 16, v26
	v_and_b32_e32 v36, 0xffff0000, v26
	s_mul_i32 s20, s0, 0x164
	v_max_f32_e64 v40, |v36|, |v36|
	v_max_f32_e64 v39, |v39|, |v39|
	v_lshl_add_u64 v[36:37], v[6:7], 0, s[20:21]
	v_max_f32_e32 v36, v39, v40
	s_mul_i32 s20, s0, 0x168
	v_max3_f32 v35, v35, v38, v36
	v_lshl_add_u64 v[36:37], v[6:7], 0, s[20:21]
	s_mul_i32 s20, s0, 0x16c
	v_lshl_add_u64 v[36:37], v[6:7], 0, s[20:21]
	s_mul_i32 s20, s0, 0x170
	v_lshl_add_u64 v[36:37], v[6:7], 0, s[20:21]
	s_mul_i32 s20, s0, 0x174
	v_lshl_add_u64 v[38:39], v[6:7], 0, s[20:21]
	s_mul_i32 s20, s0, 0x178
	v_lshl_add_u64 v[40:41], v[6:7], 0, s[20:21]
	s_mul_i32 s20, s0, 0x17c
	v_lshl_add_u64 v[42:43], v[6:7], 0, s[20:21]
	s_nop 0
	s_nop 0
	v_readlane_b32 s1, v34, 16
	v_readlane_b32 s20, v34, 48
	s_nop 0
	v_mov_b32_e32 v41, s1
	v_mov_b32_e32 v40, s20
	v_readlane_b32 s1, v34, 17
	v_readlane_b32 s20, v34, 49
	v_cndmask_b32_e32 v40, v40, v41, vcc
	v_mov_b32_e32 v42, s1
	v_mov_b32_e32 v41, s20
	v_readlane_b32 s1, v34, 18
	v_readlane_b32 s20, v34, 50
	v_cndmask_b32_e32 v41, v41, v42, vcc
	v_mov_b32_e32 v43, s1
	v_mov_b32_e32 v42, s20
	v_readlane_b32 s1, v34, 19
	v_readlane_b32 s20, v34, 51
	s_mov_b32 s101, 0
	s_mul_i32 s100, s0, 0x200
	v_lshl_add_u64 v[154:155], v[6:7], 0, s[100:101]
	global_load_dword v160, v[154:155], off
	s_mul_i32 s100, s0, 0x204
	v_lshl_add_u64 v[154:155], v[6:7], 0, s[100:101]
	global_load_dword v161, v[154:155], off
	s_mul_i32 s100, s0, 0x208
	v_lshl_add_u64 v[154:155], v[6:7], 0, s[100:101]
	global_load_dword v162, v[154:155], off
	s_mul_i32 s100, s0, 0x20c
	v_lshl_add_u64 v[154:155], v[6:7], 0, s[100:101]
	global_load_dword v163, v[154:155], off
	s_mul_i32 s100, s0, 0x210
	v_lshl_add_u64 v[154:155], v[6:7], 0, s[100:101]
	global_load_dword v164, v[154:155], off
	s_mul_i32 s100, s0, 0x214
	v_lshl_add_u64 v[154:155], v[6:7], 0, s[100:101]
	global_load_dword v165, v[154:155], off
	s_mul_i32 s100, s0, 0x218
	v_lshl_add_u64 v[154:155], v[6:7], 0, s[100:101]
	global_load_dword v166, v[154:155], off
	s_mul_i32 s100, s0, 0x21c
	v_lshl_add_u64 v[154:155], v[6:7], 0, s[100:101]
	global_load_dword v167, v[154:155], off
	s_mul_i32 s100, s0, 0x220
	v_lshl_add_u64 v[154:155], v[6:7], 0, s[100:101]
	global_load_dword v168, v[154:155], off
	s_mul_i32 s100, s0, 0x224
	v_lshl_add_u64 v[154:155], v[6:7], 0, s[100:101]
	global_load_dword v169, v[154:155], off
	s_mul_i32 s100, s0, 0x228
	v_lshl_add_u64 v[154:155], v[6:7], 0, s[100:101]
	global_load_dword v170, v[154:155], off
	s_mul_i32 s100, s0, 0x22c
	v_lshl_add_u64 v[154:155], v[6:7], 0, s[100:101]
	global_load_dword v171, v[154:155], off
	s_mul_i32 s100, s0, 0x230
	v_lshl_add_u64 v[154:155], v[6:7], 0, s[100:101]
	global_load_dword v172, v[154:155], off
	s_mul_i32 s100, s0, 0x234
	v_lshl_add_u64 v[154:155], v[6:7], 0, s[100:101]
	global_load_dword v173, v[154:155], off
	s_mul_i32 s100, s0, 0x238
	v_lshl_add_u64 v[154:155], v[6:7], 0, s[100:101]
	global_load_dword v174, v[154:155], off
	s_mul_i32 s100, s0, 0x23c
	v_lshl_add_u64 v[154:155], v[6:7], 0, s[100:101]
	global_load_dword v175, v[154:155], off
	s_waitcnt vmcnt(16) lgkmcnt(0)
	v_mul_f32_e32 v40, v176, v40
	v_cndmask_b32_e32 v42, v42, v43, vcc
	v_mov_b32_e32 v43, s20
	v_mov_b32_e32 v44, s1
	v_readlane_b32 s1, v34, 20
	v_readlane_b32 s20, v34, 52
	v_mul_f32_e32 v41, v177, v41
	v_cndmask_b32_e32 v43, v43, v44, vcc
	v_mov_b32_e32 v44, s20
	v_mov_b32_e32 v45, s1
	v_readlane_b32 s1, v34, 21
	v_readlane_b32 s20, v34, 53
	v_mul_f32_e32 v42, v178, v42
	v_cndmask_b32_e32 v44, v44, v45, vcc
	v_mov_b32_e32 v45, s20
	v_mov_b32_e32 v46, s1
	v_readlane_b32 s1, v34, 22
	v_readlane_b32 s20, v34, 54
	v_mul_f32_e32 v43, v179, v43
	v_cndmask_b32_e32 v45, v45, v46, vcc
	v_mov_b32_e32 v46, s20
	v_mov_b32_e32 v47, s1
	v_readlane_b32 s1, v34, 23
	v_readlane_b32 s20, v34, 55
	v_mul_f32_e32 v44, v180, v44
	v_cndmask_b32_e32 v46, v46, v47, vcc
	v_mov_b32_e32 v47, s20
	v_mov_b32_e32 v48, s1
	v_readlane_b32 s1, v34, 24
	v_readlane_b32 s20, v34, 56
	v_mul_f32_e32 v45, v181, v45
	v_cndmask_b32_e32 v47, v47, v48, vcc
	v_mov_b32_e32 v48, s20
	v_mov_b32_e32 v49, s1
	v_readlane_b32 s1, v34, 25
	v_readlane_b32 s20, v34, 57
	v_mul_f32_e32 v46, v182, v46
	v_cndmask_b32_e32 v48, v48, v49, vcc
	v_mov_b32_e32 v49, s20
	v_mov_b32_e32 v50, s1
	v_readlane_b32 s1, v34, 26
	v_readlane_b32 s20, v34, 58
	v_mul_f32_e32 v47, v183, v47
	v_cndmask_b32_e32 v49, v49, v50, vcc
	v_mov_b32_e32 v50, s20
	v_mov_b32_e32 v51, s1
	v_readlane_b32 s1, v34, 27
	v_readlane_b32 s20, v34, 59
	v_mul_f32_e32 v48, v184, v48
	v_cndmask_b32_e32 v50, v50, v51, vcc
	v_mov_b32_e32 v51, s20
	v_mov_b32_e32 v52, s1
	v_readlane_b32 s1, v34, 28
	v_readlane_b32 s20, v34, 60
	v_mul_f32_e32 v49, v185, v49
	v_cndmask_b32_e32 v51, v51, v52, vcc
	v_mov_b32_e32 v52, s20
	v_mov_b32_e32 v53, s1
	v_cndmask_b32_e32 v52, v52, v53, vcc
	v_readlane_b32 s1, v34, 29
	v_readlane_b32 s20, v34, 61
	v_mul_f32_e32 v52, v188, v52
	v_mov_b32_e32 v53, s1
	v_mov_b32_e32 v36, s20
	v_cndmask_b32_e32 v36, v36, v53, vcc
	v_readlane_b32 s1, v34, 30
	v_readlane_b32 s20, v34, 62
	v_mul_f32_e32 v53, v189, v36
	v_mov_b32_e32 v37, s1
	v_mov_b32_e32 v36, s20
	v_cndmask_b32_e32 v36, v36, v37, vcc
	v_readlane_b32 s1, v34, 31
	v_readlane_b32 s20, v34, 63
	v_mul_f32_e32 v50, v186, v50
	v_mul_f32_e32 v54, v190, v36
	v_mov_b32_e32 v34, s20
	v_mov_b32_e32 v36, s1
	v_cndmask_b32_e32 v34, v34, v36, vcc
	v_cvt_pk_bf16_f32 v41, v40, v41
	v_cvt_pk_bf16_f32 v40, v42, v43
	v_mul_f32_e32 v51, v187, v51
	v_lshlrev_b32_e32 v36, 16, v41
	v_and_b32_e32 v37, 0xffff0000, v41
	v_max_f32_e64 v37, |v37|, |v37|
	v_max_f32_e64 v36, |v36|, |v36|
	v_max_f32_e32 v36, v36, v37
	v_lshlrev_b32_e32 v37, 16, v40
	v_and_b32_e32 v38, 0xffff0000, v40
	v_max_f32_e64 v38, |v38|, |v38|
	v_max_f32_e64 v37, |v37|, |v37|
	v_max_f32_e32 v37, v37, v38
	v_mul_f32_e32 v34, v191, v34
	v_max3_f32 v55, v35, v36, v37
	v_cvt_pk_bf16_f32 v39, v44, v45
	s_lshl_b32 s20, s0, 9
	v_lshlrev_b32_e32 v35, 16, v39
	v_and_b32_e32 v36, 0xffff0000, v39
	v_max_f32_e64 v44, |v36|, |v36|
	v_max_f32_e64 v45, |v35|, |v35|
	v_cvt_pk_bf16_f32 v38, v46, v47
	v_cvt_pk_bf16_f32 v37, v48, v49
	v_cvt_pk_bf16_f32 v36, v50, v51
	v_cvt_pk_bf16_f32 v35, v52, v53
	v_cvt_pk_bf16_f32 v34, v54, v34
	v_lshl_add_u64 v[42:43], v[6:7], 0, s[20:21]
	s_mul_i32 s20, s0, 0x204
	v_max_f32_e32 v44, v45, v44
	v_lshlrev_b32_e32 v45, 16, v38
	v_and_b32_e32 v46, 0xffff0000, v38
	v_lshl_add_u64 v[42:43], v[6:7], 0, s[20:21]
	v_max_f32_e64 v42, |v46|, |v46|
	v_max_f32_e64 v43, |v45|, |v45|
	s_mul_i32 s20, s0, 0x208
	v_max_f32_e32 v45, v43, v42
	v_lshl_add_u64 v[42:43], v[6:7], 0, s[20:21]
	s_mul_i32 s20, s0, 0x20c
	v_max3_f32 v44, v55, v44, v45
	v_lshlrev_b32_e32 v45, 16, v37
	v_and_b32_e32 v46, 0xffff0000, v37
	v_lshl_add_u64 v[42:43], v[6:7], 0, s[20:21]
	v_max_f32_e64 v42, |v46|, |v46|
	v_max_f32_e64 v43, |v45|, |v45|
	v_max_f32_e32 v42, v43, v42
	v_lshlrev_b32_e32 v43, 16, v36
	v_and_b32_e32 v45, 0xffff0000, v36
	v_max_f32_e64 v45, |v45|, |v45|
	v_max_f32_e64 v43, |v43|, |v43|
	v_max_f32_e32 v43, v43, v45
	v_max3_f32 v44, v44, v42, v43
	v_lshlrev_b32_e32 v42, 16, v35
	v_and_b32_e32 v43, 0xffff0000, v35
	v_max_f32_e64 v43, |v43|, |v43|
	v_max_f32_e64 v42, |v42|, |v42|
	s_mul_i32 s20, s0, 0x210
	v_max_f32_e32 v45, v42, v43
	v_lshlrev_b32_e32 v46, 16, v34
	v_and_b32_e32 v47, 0xffff0000, v34
	v_lshl_add_u64 v[42:43], v[6:7], 0, s[20:21]
	v_max_f32_e64 v42, |v47|, |v47|
	v_max_f32_e64 v43, |v46|, |v46|
	s_mul_i32 s20, s0, 0x214
	v_max_f32_e32 v46, v43, v42
	v_lshl_add_u64 v[42:43], v[6:7], 0, s[20:21]
	s_mul_i32 s20, s0, 0x218
	v_lshl_add_u64 v[42:43], v[6:7], 0, s[20:21]
	s_mul_i32 s20, s0, 0x21c
	v_max3_f32 v61, v44, v45, v46
	v_lshl_add_u64 v[44:45], v[6:7], 0, s[20:21]
	s_mul_i32 s20, s0, 0x220
	v_lshl_add_u64 v[42:43], v[6:7], 0, s[20:21]
	s_mul_i32 s20, s0, 0x224
	v_lshl_add_u64 v[44:45], v[6:7], 0, s[20:21]
	s_mul_i32 s20, s0, 0x228
	v_lshl_add_u64 v[46:47], v[6:7], 0, s[20:21]
	s_mul_i32 s20, s0, 0x22c
	v_lshl_add_u64 v[42:43], v[6:7], 0, s[20:21]
	s_mul_i32 s20, s0, 0x230
	v_lshl_add_u64 v[44:45], v[6:7], 0, s[20:21]
	s_mul_i32 s20, s0, 0x234
	v_lshl_add_u64 v[48:49], v[6:7], 0, s[20:21]
	s_mul_i32 s20, s0, 0x238
	v_lshl_add_u64 v[50:51], v[6:7], 0, s[20:21]
	s_mul_i32 s20, s0, 0x23c
	v_lshl_add_u64 v[52:53], v[6:7], 0, s[20:21]
	s_nop 0
	s_nop 0
	s_nop 0
	s_nop 0
	v_readlane_b32 s1, v56, 0
	v_readlane_b32 s20, v56, 32
	s_nop 0
	v_mov_b32_e32 v43, s1
	v_mov_b32_e32 v42, s20
	v_readlane_b32 s1, v56, 1
	v_readlane_b32 s20, v56, 33
	v_cndmask_b32_e32 v42, v42, v43, vcc
	v_mov_b32_e32 v50, s1
	v_mov_b32_e32 v43, s20
	v_readlane_b32 s1, v56, 2
	v_readlane_b32 s20, v56, 34
	v_cndmask_b32_e32 v43, v43, v50, vcc
	v_mov_b32_e32 v51, s1
	v_mov_b32_e32 v50, s20
	v_readlane_b32 s1, v56, 3
	v_readlane_b32 s20, v56, 35
	s_mov_b32 s101, 0
	s_mul_i32 s100, s0, 0x240
	v_lshl_add_u64 v[154:155], v[6:7], 0, s[100:101]
	global_load_dword v176, v[154:155], off
	s_mul_i32 s100, s0, 0x244
	v_lshl_add_u64 v[154:155], v[6:7], 0, s[100:101]
	global_load_dword v177, v[154:155], off
	s_mul_i32 s100, s0, 0x248
	v_lshl_add_u64 v[154:155], v[6:7], 0, s[100:101]
	global_load_dword v178, v[154:155], off
	s_mul_i32 s100, s0, 0x24c
	v_lshl_add_u64 v[154:155], v[6:7], 0, s[100:101]
	global_load_dword v179, v[154:155], off
	s_mul_i32 s100, s0, 0x250
	v_lshl_add_u64 v[154:155], v[6:7], 0, s[100:101]
	global_load_dword v180, v[154:155], off
	s_mul_i32 s100, s0, 0x254
	v_lshl_add_u64 v[154:155], v[6:7], 0, s[100:101]
	global_load_dword v181, v[154:155], off
	s_mul_i32 s100, s0, 0x258
	v_lshl_add_u64 v[154:155], v[6:7], 0, s[100:101]
	global_load_dword v182, v[154:155], off
	s_mul_i32 s100, s0, 0x25c
	v_lshl_add_u64 v[154:155], v[6:7], 0, s[100:101]
	global_load_dword v183, v[154:155], off
	s_mul_i32 s100, s0, 0x260
	v_lshl_add_u64 v[154:155], v[6:7], 0, s[100:101]
	global_load_dword v184, v[154:155], off
	s_mul_i32 s100, s0, 0x264
	v_lshl_add_u64 v[154:155], v[6:7], 0, s[100:101]
	global_load_dword v185, v[154:155], off
	s_mul_i32 s100, s0, 0x268
	v_lshl_add_u64 v[154:155], v[6:7], 0, s[100:101]
	global_load_dword v186, v[154:155], off
	s_mul_i32 s100, s0, 0x26c
	v_lshl_add_u64 v[154:155], v[6:7], 0, s[100:101]
	global_load_dword v187, v[154:155], off
	s_mul_i32 s100, s0, 0x270
	v_lshl_add_u64 v[154:155], v[6:7], 0, s[100:101]
	global_load_dword v188, v[154:155], off
	s_mul_i32 s100, s0, 0x274
	v_lshl_add_u64 v[154:155], v[6:7], 0, s[100:101]
	global_load_dword v189, v[154:155], off
	s_mul_i32 s100, s0, 0x278
	v_lshl_add_u64 v[154:155], v[6:7], 0, s[100:101]
	global_load_dword v190, v[154:155], off
	s_mul_i32 s100, s0, 0x27c
	v_lshl_add_u64 v[154:155], v[6:7], 0, s[100:101]
	global_load_dword v191, v[154:155], off
	s_waitcnt vmcnt(16) lgkmcnt(0)
	v_mul_f32_e32 v42, v160, v42
	v_mul_f32_e32 v43, v161, v43
	v_cndmask_b32_e32 v50, v50, v51, vcc
	v_mov_b32_e32 v51, s20
	v_mov_b32_e32 v52, s1
	v_cndmask_b32_e32 v51, v51, v52, vcc
	v_cvt_pk_bf16_f32 v43, v42, v43
	v_readlane_b32 s1, v56, 4
	v_and_b32_e32 v42, 0xffff0000, v43
	v_lshlrev_b32_e32 v52, 16, v43
	v_mul_f32_e32 v50, v162, v50
	v_max_f32_e64 v42, |v42|, |v42|
	v_max_f32_e64 v52, |v52|, |v52|
	v_mul_f32_e32 v51, v163, v51
	v_max_f32_e32 v52, v52, v42
	v_cvt_pk_bf16_f32 v42, v50, v51
	v_readlane_b32 s20, v56, 36
	v_and_b32_e32 v50, 0xffff0000, v42
	v_lshlrev_b32_e32 v51, 16, v42
	v_max_f32_e64 v50, |v50|, |v50|
	v_max_f32_e64 v51, |v51|, |v51|
	v_max_f32_e32 v50, v51, v50
	v_max3_f32 v52, v61, v52, v50
	v_mov_b32_e32 v50, s20
	v_mov_b32_e32 v51, s1
	v_readlane_b32 s1, v56, 5
	v_readlane_b32 s20, v56, 37
	v_cndmask_b32_e32 v50, v50, v51, vcc
	v_mov_b32_e32 v53, s1
	v_mov_b32_e32 v51, s20
	v_readlane_b32 s1, v56, 6
	v_readlane_b32 s20, v56, 38
	v_cndmask_b32_e32 v51, v51, v53, vcc
	v_mov_b32_e32 v54, s1
	v_mov_b32_e32 v53, s20
	v_readlane_b32 s1, v56, 7
	v_readlane_b32 s20, v56, 39
	v_cndmask_b32_e32 v53, v53, v54, vcc
	v_mov_b32_e32 v55, s1
	v_mov_b32_e32 v54, s20
	v_readlane_b32 s1, v56, 8
	v_readlane_b32 s20, v56, 40
	v_cndmask_b32_e32 v54, v54, v55, vcc
	v_mov_b32_e32 v57, s1
	v_mov_b32_e32 v55, s20
	v_readlane_b32 s1, v56, 9
	v_readlane_b32 s20, v56, 41
	v_cndmask_b32_e32 v55, v55, v57, vcc
	v_mov_b32_e32 v58, s1
	v_mov_b32_e32 v57, s20
	v_readlane_b32 s1, v56, 10
	v_readlane_b32 s20, v56, 42
	v_mul_f32_e32 v50, v164, v50
	v_cndmask_b32_e32 v57, v57, v58, vcc
	v_mov_b32_e32 v58, s20
	v_mov_b32_e32 v59, s1
	v_cndmask_b32_e32 v58, v58, v59, vcc
	v_readlane_b32 s1, v56, 11
	v_readlane_b32 s20, v56, 43
	v_mul_f32_e32 v46, v170, v58
	v_mov_b32_e32 v59, s1
	v_mov_b32_e32 v58, s20
	v_cndmask_b32_e32 v58, v58, v59, vcc
	v_readlane_b32 s1, v56, 12
	v_readlane_b32 s20, v56, 44
	v_mul_f32_e32 v58, v171, v58
	v_mov_b32_e32 v59, s1
	v_mov_b32_e32 v47, s20
	v_cndmask_b32_e32 v47, v47, v59, vcc
	v_readlane_b32 s1, v56, 13
	v_readlane_b32 s20, v56, 45
	v_mul_f32_e32 v44, v172, v47
	v_mov_b32_e32 v59, s1
	v_mov_b32_e32 v47, s20
	v_cndmask_b32_e32 v47, v47, v59, vcc
	v_readlane_b32 s1, v56, 14
	v_readlane_b32 s20, v56, 46
	v_mul_f32_e32 v45, v173, v47
	v_mov_b32_e32 v59, s1
	v_mov_b32_e32 v47, s20
	v_cndmask_b32_e32 v47, v47, v59, vcc
	v_readlane_b32 s1, v56, 15
	v_readlane_b32 s20, v56, 47
	v_mul_f32_e32 v59, v174, v47
	v_mov_b32_e32 v48, s1
	v_mov_b32_e32 v47, s20
	v_cndmask_b32_e32 v47, v47, v48, vcc
	v_mul_f32_e32 v51, v165, v51
	v_mul_f32_e32 v60, v175, v47
	v_cvt_pk_bf16_f32 v49, v50, v51
	s_mul_i32 s20, s0, 0x240
	v_lshlrev_b32_e32 v47, 16, v49
	v_and_b32_e32 v48, 0xffff0000, v49
	v_mul_f32_e32 v53, v166, v53
	v_mul_f32_e32 v54, v167, v54
	v_mul_f32_e32 v55, v168, v55
	v_mul_f32_e32 v57, v169, v57
	v_max_f32_e64 v61, |v48|, |v48|
	v_max_f32_e64 v62, |v47|, |v47|
	v_cvt_pk_bf16_f32 v48, v53, v54
	v_cvt_pk_bf16_f32 v47, v55, v57
	v_cvt_pk_bf16_f32 v46, v46, v58
	v_cvt_pk_bf16_f32 v45, v44, v45
	v_cvt_pk_bf16_f32 v44, v59, v60
	v_lshl_add_u64 v[50:51], v[6:7], 0, s[20:21]
	s_mul_i32 s20, s0, 0x244
	v_lshlrev_b32_e32 v54, 16, v48
	v_and_b32_e32 v55, 0xffff0000, v48
	v_lshl_add_u64 v[50:51], v[6:7], 0, s[20:21]
	v_max_f32_e64 v50, |v55|, |v55|
	v_max_f32_e64 v51, |v54|, |v54|
	s_mul_i32 s20, s0, 0x248
	v_max_f32_e32 v53, v62, v61
	v_max_f32_e32 v54, v51, v50
	v_lshl_add_u64 v[50:51], v[6:7], 0, s[20:21]
	s_mul_i32 s20, s0, 0x24c
	v_max3_f32 v52, v52, v53, v54
	v_lshlrev_b32_e32 v53, 16, v47
	v_and_b32_e32 v54, 0xffff0000, v47
	v_lshl_add_u64 v[50:51], v[6:7], 0, s[20:21]
	v_max_f32_e64 v50, |v54|, |v54|
	v_max_f32_e64 v51, |v53|, |v53|
	v_max_f32_e32 v50, v51, v50
	v_lshlrev_b32_e32 v51, 16, v46
	v_and_b32_e32 v53, 0xffff0000, v46
	v_max_f32_e64 v53, |v53|, |v53|
	v_max_f32_e64 v51, |v51|, |v51|
	v_max_f32_e32 v51, v51, v53
	v_max3_f32 v52, v52, v50, v51
	v_lshlrev_b32_e32 v50, 16, v45
	v_and_b32_e32 v51, 0xffff0000, v45
	v_max_f32_e64 v51, |v51|, |v51|
	v_max_f32_e64 v50, |v50|, |v50|
	s_mul_i32 s20, s0, 0x250
	v_max_f32_e32 v53, v50, v51
	v_lshl_add_u64 v[50:51], v[6:7], 0, s[20:21]
	v_and_b32_e32 v50, 0xffff0000, v44
	v_lshlrev_b32_e32 v51, 16, v44
	v_max_f32_e64 v50, |v50|, |v50|
	v_max_f32_e64 v51, |v51|, |v51|
	s_mul_i32 s20, s0, 0x254
	v_max_f32_e32 v54, v51, v50
	v_lshl_add_u64 v[50:51], v[6:7], 0, s[20:21]
	s_mul_i32 s20, s0, 0x258
	v_lshl_add_u64 v[50:51], v[6:7], 0, s[20:21]
	s_mul_i32 s20, s0, 0x25c
	v_max3_f32 v75, v52, v53, v54
	v_lshl_add_u64 v[52:53], v[6:7], 0, s[20:21]
	s_mul_i32 s20, s0, 0x260
	v_lshl_add_u64 v[50:51], v[6:7], 0, s[20:21]
	s_mul_i32 s20, s0, 0x264
	v_lshl_add_u64 v[52:53], v[6:7], 0, s[20:21]
	s_mul_i32 s20, s0, 0x268
	v_lshl_add_u64 v[54:55], v[6:7], 0, s[20:21]
	s_mul_i32 s20, s0, 0x26c
	v_lshl_add_u64 v[58:59], v[6:7], 0, s[20:21]
	s_mul_i32 s20, s0, 0x270
	v_lshl_add_u64 v[60:61], v[6:7], 0, s[20:21]
	s_mul_i32 s20, s0, 0x274
	v_lshl_add_u64 v[62:63], v[6:7], 0, s[20:21]
	s_mul_i32 s20, s0, 0x278
	v_lshl_add_u64 v[64:65], v[6:7], 0, s[20:21]
	s_mul_i32 s20, s0, 0x27c
	v_lshl_add_u64 v[66:67], v[6:7], 0, s[20:21]
	s_nop 0
	s_nop 0
	s_nop 0
	s_nop 0
	v_readlane_b32 s1, v56, 16
	v_readlane_b32 s20, v56, 48
	s_nop 0
	v_mov_b32_e32 v51, s1
	v_mov_b32_e32 v50, s20
	v_readlane_b32 s1, v56, 17
	v_readlane_b32 s20, v56, 49
	v_cndmask_b32_e32 v50, v50, v51, vcc
	v_mov_b32_e32 v52, s1
	v_mov_b32_e32 v51, s20
	v_readlane_b32 s1, v56, 18
	v_readlane_b32 s20, v56, 50
	v_cndmask_b32_e32 v51, v51, v52, vcc
	v_mov_b32_e32 v53, s1
	v_mov_b32_e32 v52, s20
	v_readlane_b32 s1, v56, 19
	v_readlane_b32 s20, v56, 51
	s_mov_b32 s101, 0
	s_mul_i32 s100, s0, 0x300
	v_lshl_add_u64 v[154:155], v[6:7], 0, s[100:101]
	global_load_dword v160, v[154:155], off
	s_mul_i32 s100, s0, 0x304
	v_lshl_add_u64 v[154:155], v[6:7], 0, s[100:101]
	global_load_dword v161, v[154:155], off
	s_mul_i32 s100, s0, 0x308
	v_lshl_add_u64 v[154:155], v[6:7], 0, s[100:101]
	global_load_dword v162, v[154:155], off
	s_mul_i32 s100, s0, 0x30c
	v_lshl_add_u64 v[154:155], v[6:7], 0, s[100:101]
	global_load_dword v163, v[154:155], off
	s_mul_i32 s100, s0, 0x310
	v_lshl_add_u64 v[154:155], v[6:7], 0, s[100:101]
	global_load_dword v164, v[154:155], off
	s_mul_i32 s100, s0, 0x314
	v_lshl_add_u64 v[154:155], v[6:7], 0, s[100:101]
	global_load_dword v165, v[154:155], off
	s_mul_i32 s100, s0, 0x318
	v_lshl_add_u64 v[154:155], v[6:7], 0, s[100:101]
	global_load_dword v166, v[154:155], off
	s_mul_i32 s100, s0, 0x31c
	v_lshl_add_u64 v[154:155], v[6:7], 0, s[100:101]
	global_load_dword v167, v[154:155], off
	s_mul_i32 s100, s0, 0x320
	v_lshl_add_u64 v[154:155], v[6:7], 0, s[100:101]
	global_load_dword v168, v[154:155], off
	s_mul_i32 s100, s0, 0x324
	v_lshl_add_u64 v[154:155], v[6:7], 0, s[100:101]
	global_load_dword v169, v[154:155], off
	s_mul_i32 s100, s0, 0x328
	v_lshl_add_u64 v[154:155], v[6:7], 0, s[100:101]
	global_load_dword v170, v[154:155], off
	s_mul_i32 s100, s0, 0x32c
	v_lshl_add_u64 v[154:155], v[6:7], 0, s[100:101]
	global_load_dword v171, v[154:155], off
	s_mul_i32 s100, s0, 0x330
	v_lshl_add_u64 v[154:155], v[6:7], 0, s[100:101]
	global_load_dword v172, v[154:155], off
	s_mul_i32 s100, s0, 0x334
	v_lshl_add_u64 v[154:155], v[6:7], 0, s[100:101]
	global_load_dword v173, v[154:155], off
	s_mul_i32 s100, s0, 0x338
	v_lshl_add_u64 v[154:155], v[6:7], 0, s[100:101]
	global_load_dword v174, v[154:155], off
	s_mul_i32 s100, s0, 0x33c
	v_lshl_add_u64 v[154:155], v[6:7], 0, s[100:101]
	global_load_dword v175, v[154:155], off
	s_waitcnt vmcnt(16) lgkmcnt(0)
	v_mul_f32_e32 v50, v176, v50
	v_mul_f32_e32 v51, v177, v51
	v_cndmask_b32_e32 v52, v52, v53, vcc
	v_mov_b32_e32 v53, s20
	v_mov_b32_e32 v57, s1
	v_cndmask_b32_e32 v53, v53, v57, vcc
	v_cvt_pk_bf16_f32 v51, v50, v51
	v_readlane_b32 s1, v56, 20
	v_and_b32_e32 v50, 0xffff0000, v51
	v_lshlrev_b32_e32 v57, 16, v51
	v_mul_f32_e32 v52, v178, v52
	v_max_f32_e64 v50, |v50|, |v50|
	v_max_f32_e64 v57, |v57|, |v57|
	v_max_f32_e32 v57, v57, v50
	v_mul_f32_e32 v53, v179, v53
	v_cvt_pk_bf16_f32 v50, v52, v53
	v_readlane_b32 s20, v56, 52
	v_and_b32_e32 v52, 0xffff0000, v50
	v_lshlrev_b32_e32 v53, 16, v50
	v_max_f32_e64 v52, |v52|, |v52|
	v_max_f32_e64 v53, |v53|, |v53|
	v_max_f32_e32 v52, v53, v52
	v_max3_f32 v62, v75, v57, v52
	v_mov_b32_e32 v52, s20
	v_mov_b32_e32 v53, s1
	v_readlane_b32 s1, v56, 21
	v_readlane_b32 s20, v56, 53
	v_cndmask_b32_e32 v52, v52, v53, vcc
	v_mov_b32_e32 v57, s1
	v_mov_b32_e32 v53, s20
	v_readlane_b32 s1, v56, 22
	v_readlane_b32 s20, v56, 54
	v_cndmask_b32_e32 v53, v53, v57, vcc
	v_mov_b32_e32 v63, s1
	v_mov_b32_e32 v57, s20
	v_readlane_b32 s1, v56, 23
	v_readlane_b32 s20, v56, 55
	v_mul_f32_e32 v52, v180, v52
	v_cndmask_b32_e32 v57, v57, v63, vcc
	v_mul_f32_e32 v53, v181, v53
	v_mov_b32_e32 v63, s20
	v_mov_b32_e32 v64, s1
	v_cndmask_b32_e32 v63, v63, v64, vcc
	v_cvt_pk_bf16_f32 v53, v52, v53
	v_mul_f32_e32 v57, v182, v57
	v_and_b32_e32 v52, 0xffff0000, v53
	v_mul_f32_e32 v63, v183, v63
	v_max_f32_e64 v64, |v52|, |v52|
	v_lshlrev_b32_e32 v52, 16, v53
	v_readlane_b32 s1, v56, 24
	v_readlane_b32 s20, v56, 56
	v_max_f32_e64 v65, |v52|, |v52|
	v_cvt_pk_bf16_f32 v52, v57, v63
	v_mov_b32_e32 v63, s1
	v_mov_b32_e32 v57, s20
	v_readlane_b32 s1, v56, 25
	v_readlane_b32 s20, v56, 57
	v_cndmask_b32_e32 v57, v57, v63, vcc
	v_mov_b32_e32 v66, s1
	v_mov_b32_e32 v63, s20
	v_readlane_b32 s1, v56, 26
	v_readlane_b32 s20, v56, 58
	v_cndmask_b32_e32 v63, v63, v66, vcc
	v_mov_b32_e32 v67, s1
	v_mov_b32_e32 v66, s20
	v_cndmask_b32_e32 v66, v66, v67, vcc
	v_readlane_b32 s1, v56, 27
	v_readlane_b32 s20, v56, 59
	v_mul_f32_e32 v54, v186, v66
	v_mov_b32_e32 v67, s1
	v_mov_b32_e32 v66, s20
	v_mul_f32_e32 v57, v184, v57
	v_mul_f32_e32 v63, v185, v63
	v_cndmask_b32_e32 v66, v66, v67, vcc
	v_readlane_b32 s1, v56, 28
	v_readlane_b32 s20, v56, 60
	v_mul_f32_e32 v66, v187, v66
	v_cvt_pk_bf16_f32 v55, v57, v63
	v_mov_b32_e32 v63, s1
	v_mov_b32_e32 v57, s20
	v_cndmask_b32_e32 v57, v57, v63, vcc
	v_readlane_b32 s1, v56, 29
	v_readlane_b32 s20, v56, 61
	v_mul_f32_e32 v57, v188, v57
	v_mov_b32_e32 v63, s1
	v_mov_b32_e32 v58, s20
	v_cndmask_b32_e32 v58, v58, v63, vcc
	v_readlane_b32 s1, v56, 30
	v_readlane_b32 s20, v56, 62
	v_mul_f32_e32 v58, v189, v58
	v_mov_b32_e32 v63, s1
	v_mov_b32_e32 v59, s20
	v_cndmask_b32_e32 v59, v59, v63, vcc
	v_readlane_b32 s1, v56, 31
	v_readlane_b32 s20, v56, 63
	v_mul_f32_e32 v59, v190, v59
	v_mov_b32_e32 v60, s1
	v_mov_b32_e32 v56, s20
	v_cndmask_b32_e32 v56, v56, v60, vcc
	v_mul_f32_e32 v56, v191, v56
	s_mul_i32 s20, s0, 0x300
	v_cvt_pk_bf16_f32 v54, v54, v66
	v_cvt_pk_bf16_f32 v57, v57, v58
	v_cvt_pk_bf16_f32 v56, v59, v56
	v_lshl_add_u64 v[58:59], v[6:7], 0, s[20:21]
	v_and_b32_e32 v58, 0xffff0000, v52
	s_mul_i32 s20, s0, 0x304
	v_max_f32_e64 v61, |v58|, |v58|
	v_lshl_add_u64 v[58:59], v[6:7], 0, s[20:21]
	v_lshlrev_b32_e32 v58, 16, v52
	v_max_f32_e64 v58, |v58|, |v58|
	s_mul_i32 s20, s0, 0x308
	v_max_f32_e32 v61, v58, v61
	v_lshl_add_u64 v[58:59], v[6:7], 0, s[20:21]
	v_max_f32_e32 v60, v65, v64
	v_and_b32_e32 v58, 0xffff0000, v55
	s_mul_i32 s20, s0, 0x30c
	v_max3_f32 v60, v62, v60, v61
	v_max_f32_e64 v61, |v58|, |v58|
	v_lshl_add_u64 v[58:59], v[6:7], 0, s[20:21]
	v_lshlrev_b32_e32 v58, 16, v55
	v_max_f32_e64 v58, |v58|, |v58|
	v_max_f32_e32 v58, v58, v61
	v_and_b32_e32 v59, 0xffff0000, v54
	v_lshlrev_b32_e32 v61, 16, v54
	v_max_f32_e64 v59, |v59|, |v59|
	v_max_f32_e64 v61, |v61|, |v61|
	v_max_f32_e32 v59, v61, v59
	v_max3_f32 v60, v60, v58, v59
	v_and_b32_e32 v58, 0xffff0000, v57
	v_lshlrev_b32_e32 v59, 16, v57
	v_max_f32_e64 v58, |v58|, |v58|
	v_max_f32_e64 v59, |v59|, |v59|
	v_max_f32_e32 v61, v59, v58
	v_and_b32_e32 v58, 0xffff0000, v56
	s_mul_i32 s20, s0, 0x310
	v_max_f32_e64 v62, |v58|, |v58|
	v_lshl_add_u64 v[58:59], v[6:7], 0, s[20:21]
	v_lshlrev_b32_e32 v58, 16, v56
	v_max_f32_e64 v58, |v58|, |v58|
	s_mul_i32 s20, s0, 0x314
	v_max_f32_e32 v62, v58, v62
	v_lshl_add_u64 v[58:59], v[6:7], 0, s[20:21]
	s_mul_i32 s20, s0, 0x318
	v_lshl_add_u64 v[58:59], v[6:7], 0, s[20:21]
	s_mul_i32 s20, s0, 0x31c
	v_max3_f32 v82, v60, v61, v62
	v_lshl_add_u64 v[60:61], v[6:7], 0, s[20:21]
	s_mul_i32 s20, s0, 0x320
	v_lshl_add_u64 v[58:59], v[6:7], 0, s[20:21]
	s_mul_i32 s20, s0, 0x324
	v_lshl_add_u64 v[60:61], v[6:7], 0, s[20:21]
	s_mul_i32 s20, s0, 0x328
	v_lshl_add_u64 v[62:63], v[6:7], 0, s[20:21]
	s_mul_i32 s20, s0, 0x32c
	v_lshl_add_u64 v[64:65], v[6:7], 0, s[20:21]
	s_mul_i32 s20, s0, 0x330
	v_lshl_add_u64 v[66:67], v[6:7], 0, s[20:21]
	s_mul_i32 s20, s0, 0x334
	v_lshl_add_u64 v[68:69], v[6:7], 0, s[20:21]
	s_mul_i32 s20, s0, 0x338
	v_lshl_add_u64 v[70:71], v[6:7], 0, s[20:21]
	s_mul_i32 s20, s0, 0x33c
	v_lshl_add_u64 v[76:77], v[6:7], 0, s[20:21]
	s_nop 0
	s_nop 0
	s_nop 0
	s_nop 0
	v_readlane_b32 s1, v72, 0
	v_readlane_b32 s20, v72, 32
	s_nop 0
	v_mov_b32_e32 v59, s1
	v_mov_b32_e32 v58, s20
	v_readlane_b32 s1, v72, 1
	v_readlane_b32 s20, v72, 33
	v_cndmask_b32_e32 v58, v58, v59, vcc
	v_mov_b32_e32 v60, s1
	v_mov_b32_e32 v59, s20
	v_readlane_b32 s1, v72, 2
	v_readlane_b32 s20, v72, 34
	v_cndmask_b32_e32 v59, v59, v60, vcc
	v_mov_b32_e32 v61, s1
	v_mov_b32_e32 v60, s20
	v_readlane_b32 s1, v72, 3
	v_readlane_b32 s20, v72, 35
	s_mov_b32 s101, 0
	s_mul_i32 s100, s0, 0x340
	v_lshl_add_u64 v[154:155], v[6:7], 0, s[100:101]
	global_load_dword v176, v[154:155], off
	s_mul_i32 s100, s0, 0x344
	v_lshl_add_u64 v[154:155], v[6:7], 0, s[100:101]
	global_load_dword v177, v[154:155], off
	s_mul_i32 s100, s0, 0x348
	v_lshl_add_u64 v[154:155], v[6:7], 0, s[100:101]
	global_load_dword v178, v[154:155], off
	s_mul_i32 s100, s0, 0x34c
	v_lshl_add_u64 v[154:155], v[6:7], 0, s[100:101]
	global_load_dword v179, v[154:155], off
	s_mul_i32 s100, s0, 0x350
	v_lshl_add_u64 v[154:155], v[6:7], 0, s[100:101]
	global_load_dword v180, v[154:155], off
	s_mul_i32 s100, s0, 0x354
	v_lshl_add_u64 v[154:155], v[6:7], 0, s[100:101]
	global_load_dword v181, v[154:155], off
	s_mul_i32 s100, s0, 0x358
	v_lshl_add_u64 v[154:155], v[6:7], 0, s[100:101]
	global_load_dword v182, v[154:155], off
	s_mul_i32 s100, s0, 0x35c
	v_lshl_add_u64 v[154:155], v[6:7], 0, s[100:101]
	global_load_dword v183, v[154:155], off
	s_mul_i32 s100, s0, 0x360
	v_lshl_add_u64 v[154:155], v[6:7], 0, s[100:101]
	global_load_dword v184, v[154:155], off
	s_mul_i32 s100, s0, 0x364
	v_lshl_add_u64 v[154:155], v[6:7], 0, s[100:101]
	global_load_dword v185, v[154:155], off
	s_mul_i32 s100, s0, 0x368
	v_lshl_add_u64 v[154:155], v[6:7], 0, s[100:101]
	global_load_dword v186, v[154:155], off
	s_mul_i32 s100, s0, 0x36c
	v_lshl_add_u64 v[154:155], v[6:7], 0, s[100:101]
	global_load_dword v187, v[154:155], off
	s_mul_i32 s100, s0, 0x370
	v_lshl_add_u64 v[154:155], v[6:7], 0, s[100:101]
	global_load_dword v188, v[154:155], off
	s_mul_i32 s100, s0, 0x374
	v_lshl_add_u64 v[154:155], v[6:7], 0, s[100:101]
	global_load_dword v189, v[154:155], off
	s_mul_i32 s100, s0, 0x378
	v_lshl_add_u64 v[154:155], v[6:7], 0, s[100:101]
	global_load_dword v190, v[154:155], off
	s_mul_i32 s100, s0, 0x37c
	v_lshl_add_u64 v[154:155], v[6:7], 0, s[100:101]
	global_load_dword v191, v[154:155], off
	s_waitcnt vmcnt(16) lgkmcnt(0)
	v_mul_f32_e32 v58, v160, v58
	v_mul_f32_e32 v59, v161, v59
	v_cndmask_b32_e32 v60, v60, v61, vcc
	v_mov_b32_e32 v61, s20
	v_mov_b32_e32 v68, s1
	v_cndmask_b32_e32 v61, v61, v68, vcc
	v_cvt_pk_bf16_f32 v59, v58, v59
	v_readlane_b32 s1, v72, 4
	v_and_b32_e32 v58, 0xffff0000, v59
	v_lshlrev_b32_e32 v68, 16, v59
	v_mul_f32_e32 v60, v162, v60
	v_max_f32_e64 v58, |v58|, |v58|
	v_max_f32_e64 v68, |v68|, |v68|
	v_max_f32_e32 v68, v68, v58
	v_mul_f32_e32 v61, v163, v61
	v_cvt_pk_bf16_f32 v58, v60, v61
	v_readlane_b32 s20, v72, 36
	v_and_b32_e32 v60, 0xffff0000, v58
	v_lshlrev_b32_e32 v61, 16, v58
	v_max_f32_e64 v60, |v60|, |v60|
	v_max_f32_e64 v61, |v61|, |v61|
	v_max_f32_e32 v60, v61, v60
	v_max3_f32 v68, v82, v68, v60
	v_mov_b32_e32 v60, s20
	v_mov_b32_e32 v61, s1
	v_readlane_b32 s1, v72, 5
	v_readlane_b32 s20, v72, 37
	v_cndmask_b32_e32 v60, v60, v61, vcc
	v_mov_b32_e32 v69, s1
	v_mov_b32_e32 v61, s20
	v_readlane_b32 s1, v72, 6
	v_readlane_b32 s20, v72, 38
	v_cndmask_b32_e32 v61, v61, v69, vcc
	v_mov_b32_e32 v70, s1
	v_mov_b32_e32 v69, s20
	v_readlane_b32 s1, v72, 7
	v_readlane_b32 s20, v72, 39
	v_mul_f32_e32 v60, v164, v60
	v_cndmask_b32_e32 v69, v69, v70, vcc
	v_mul_f32_e32 v61, v165, v61
	v_mov_b32_e32 v70, s20
	v_mov_b32_e32 v71, s1
	v_cndmask_b32_e32 v70, v70, v71, vcc
	v_cvt_pk_bf16_f32 v61, v60, v61
	v_mul_f32_e32 v69, v166, v69
	v_and_b32_e32 v60, 0xffff0000, v61
	v_mul_f32_e32 v70, v167, v70
	v_max_f32_e64 v71, |v60|, |v60|
	v_lshlrev_b32_e32 v60, 16, v61
	v_readlane_b32 s1, v72, 8
	v_readlane_b32 s20, v72, 40
	v_max_f32_e64 v73, |v60|, |v60|
	v_cvt_pk_bf16_f32 v60, v69, v70
	v_mov_b32_e32 v70, s1
	v_mov_b32_e32 v69, s20
	v_readlane_b32 s1, v72, 9
	v_readlane_b32 s20, v72, 41
	v_cndmask_b32_e32 v69, v69, v70, vcc
	v_mov_b32_e32 v75, s1
	v_mov_b32_e32 v70, s20
	v_readlane_b32 s1, v72, 10
	v_readlane_b32 s20, v72, 42
	v_cndmask_b32_e32 v70, v70, v75, vcc
	v_mov_b32_e32 v76, s1
	v_mov_b32_e32 v75, s20
	v_cndmask_b32_e32 v75, v75, v76, vcc
	v_readlane_b32 s1, v72, 11
	v_readlane_b32 s20, v72, 43
	v_mul_f32_e32 v62, v170, v75
	v_mov_b32_e32 v76, s1
	v_mov_b32_e32 v75, s20
	v_mul_f32_e32 v69, v168, v69
	v_mul_f32_e32 v70, v169, v70
	v_cndmask_b32_e32 v75, v75, v76, vcc
	v_readlane_b32 s1, v72, 12
	v_readlane_b32 s20, v72, 44
	v_mul_f32_e32 v75, v171, v75
	v_cvt_pk_bf16_f32 v63, v69, v70
	v_mov_b32_e32 v70, s1
	v_mov_b32_e32 v69, s20
	v_cndmask_b32_e32 v69, v69, v70, vcc
	v_readlane_b32 s1, v72, 13
	v_readlane_b32 s20, v72, 45
	v_mul_f32_e32 v64, v172, v69
	v_mov_b32_e32 v70, s1
	v_mov_b32_e32 v69, s20
	v_cndmask_b32_e32 v69, v69, v70, vcc
	v_readlane_b32 s1, v72, 14
	v_readlane_b32 s20, v72, 46
	v_mul_f32_e32 v65, v173, v69
	v_mov_b32_e32 v70, s1
	v_mov_b32_e32 v69, s20
	v_cndmask_b32_e32 v69, v69, v70, vcc
	v_readlane_b32 s1, v72, 15
	v_readlane_b32 s20, v72, 47
	v_mul_f32_e32 v66, v174, v69
	v_mov_b32_e32 v70, s1
	v_mov_b32_e32 v69, s20
	v_cndmask_b32_e32 v69, v69, v70, vcc
	v_mul_f32_e32 v67, v175, v69
	s_mul_i32 s20, s0, 0x340
	v_cvt_pk_bf16_f32 v62, v62, v75
	v_cvt_pk_bf16_f32 v65, v64, v65
	v_cvt_pk_bf16_f32 v64, v66, v67
	v_lshl_add_u64 v[66:67], v[6:7], 0, s[20:21]
	v_and_b32_e32 v66, 0xffff0000, v60
	s_mul_i32 s20, s0, 0x344
	v_max_f32_e64 v70, |v66|, |v66|
	v_lshl_add_u64 v[66:67], v[6:7], 0, s[20:21]
	v_max_f32_e32 v69, v73, v71
	v_lshlrev_b32_e32 v66, 16, v60
	v_max_f32_e64 v66, |v66|, |v66|
	s_mul_i32 s20, s0, 0x348
	v_max_f32_e32 v70, v66, v70
	v_lshl_add_u64 v[66:67], v[6:7], 0, s[20:21]
	v_and_b32_e32 v66, 0xffff0000, v63
	s_mul_i32 s20, s0, 0x34c
	v_max3_f32 v68, v68, v69, v70
	v_max_f32_e64 v69, |v66|, |v66|
	v_lshl_add_u64 v[66:67], v[6:7], 0, s[20:21]
	v_lshlrev_b32_e32 v66, 16, v63
	v_max_f32_e64 v66, |v66|, |v66|
	v_max_f32_e32 v66, v66, v69
	v_and_b32_e32 v67, 0xffff0000, v62
	v_lshlrev_b32_e32 v69, 16, v62
	v_max_f32_e64 v67, |v67|, |v67|
	v_max_f32_e64 v69, |v69|, |v69|
	v_max_f32_e32 v67, v69, v67
	v_max3_f32 v68, v68, v66, v67
	v_and_b32_e32 v66, 0xffff0000, v65
	v_lshlrev_b32_e32 v67, 16, v65
	v_max_f32_e64 v66, |v66|, |v66|
	v_max_f32_e64 v67, |v67|, |v67|
	v_max_f32_e32 v69, v67, v66
	v_and_b32_e32 v66, 0xffff0000, v64
	s_mul_i32 s20, s0, 0x350
	v_max_f32_e64 v70, |v66|, |v66|
	v_lshl_add_u64 v[66:67], v[6:7], 0, s[20:21]
	v_lshlrev_b32_e32 v66, 16, v64
	v_max_f32_e64 v66, |v66|, |v66|
	s_mul_i32 s20, s0, 0x354
	v_max_f32_e32 v70, v66, v70
	v_lshl_add_u64 v[66:67], v[6:7], 0, s[20:21]
	s_mul_i32 s20, s0, 0x358
	v_lshl_add_u64 v[66:67], v[6:7], 0, s[20:21]
	s_mul_i32 s20, s0, 0x35c
	v_max3_f32 v91, v68, v69, v70
	v_lshl_add_u64 v[68:69], v[6:7], 0, s[20:21]
	s_mul_i32 s20, s0, 0x360
	v_lshl_add_u64 v[66:67], v[6:7], 0, s[20:21]
	s_mul_i32 s20, s0, 0x364
	v_lshl_add_u64 v[68:69], v[6:7], 0, s[20:21]
	s_mul_i32 s20, s0, 0x368
	v_lshl_add_u64 v[70:71], v[6:7], 0, s[20:21]
	s_mul_i32 s20, s0, 0x36c
	v_lshl_add_u64 v[76:77], v[6:7], 0, s[20:21]
	s_mul_i32 s20, s0, 0x370
	v_lshl_add_u64 v[78:79], v[6:7], 0, s[20:21]
	s_mul_i32 s20, s0, 0x374
	v_lshl_add_u64 v[80:81], v[6:7], 0, s[20:21]
	s_mul_i32 s20, s0, 0x378
	v_lshl_add_u64 v[82:83], v[6:7], 0, s[20:21]
	s_mul_i32 s20, s0, 0x37c
	v_lshl_add_u64 v[84:85], v[6:7], 0, s[20:21]
	s_nop 0
	s_nop 0
	s_nop 0
	s_nop 0
	v_readlane_b32 s1, v72, 16
	v_readlane_b32 s20, v72, 48
	s_nop 0
	v_mov_b32_e32 v67, s1
	v_mov_b32_e32 v66, s20
	v_readlane_b32 s1, v72, 17
	v_readlane_b32 s20, v72, 49
	v_cndmask_b32_e32 v66, v66, v67, vcc
	v_mov_b32_e32 v68, s1
	v_mov_b32_e32 v67, s20
	v_readlane_b32 s1, v72, 18
	v_readlane_b32 s20, v72, 50
	v_cndmask_b32_e32 v67, v67, v68, vcc
	v_mov_b32_e32 v69, s1
	v_mov_b32_e32 v68, s20
	v_readlane_b32 s1, v72, 19
	v_readlane_b32 s20, v72, 51
	s_mov_b32 s101, 0
	s_mul_i32 s100, s0, 0x400
	v_lshl_add_u64 v[154:155], v[6:7], 0, s[100:101]
	global_load_dword v160, v[154:155], off
	s_mul_i32 s100, s0, 0x404
	v_lshl_add_u64 v[154:155], v[6:7], 0, s[100:101]
	global_load_dword v161, v[154:155], off
	s_mul_i32 s100, s0, 0x408
	v_lshl_add_u64 v[154:155], v[6:7], 0, s[100:101]
	global_load_dword v162, v[154:155], off
	s_mul_i32 s100, s0, 0x40c
	v_lshl_add_u64 v[154:155], v[6:7], 0, s[100:101]
	global_load_dword v163, v[154:155], off
	s_mul_i32 s100, s0, 0x410
	v_lshl_add_u64 v[154:155], v[6:7], 0, s[100:101]
	global_load_dword v164, v[154:155], off
	s_mul_i32 s100, s0, 0x414
	v_lshl_add_u64 v[154:155], v[6:7], 0, s[100:101]
	global_load_dword v165, v[154:155], off
	s_mul_i32 s100, s0, 0x418
	v_lshl_add_u64 v[154:155], v[6:7], 0, s[100:101]
	global_load_dword v166, v[154:155], off
	s_mul_i32 s100, s0, 0x41c
	v_lshl_add_u64 v[154:155], v[6:7], 0, s[100:101]
	global_load_dword v167, v[154:155], off
	s_mul_i32 s100, s0, 0x420
	v_lshl_add_u64 v[154:155], v[6:7], 0, s[100:101]
	global_load_dword v168, v[154:155], off
	s_mul_i32 s100, s0, 0x424
	v_lshl_add_u64 v[154:155], v[6:7], 0, s[100:101]
	global_load_dword v169, v[154:155], off
	s_mul_i32 s100, s0, 0x428
	v_lshl_add_u64 v[154:155], v[6:7], 0, s[100:101]
	global_load_dword v170, v[154:155], off
	s_mul_i32 s100, s0, 0x42c
	v_lshl_add_u64 v[154:155], v[6:7], 0, s[100:101]
	global_load_dword v171, v[154:155], off
	s_mul_i32 s100, s0, 0x430
	v_lshl_add_u64 v[154:155], v[6:7], 0, s[100:101]
	global_load_dword v172, v[154:155], off
	s_mul_i32 s100, s0, 0x434
	v_lshl_add_u64 v[154:155], v[6:7], 0, s[100:101]
	global_load_dword v173, v[154:155], off
	s_mul_i32 s100, s0, 0x438
	v_lshl_add_u64 v[154:155], v[6:7], 0, s[100:101]
	global_load_dword v174, v[154:155], off
	s_mul_i32 s100, s0, 0x43c
	v_lshl_add_u64 v[154:155], v[6:7], 0, s[100:101]
	global_load_dword v175, v[154:155], off
	s_waitcnt vmcnt(16) lgkmcnt(0)
	v_mul_f32_e32 v66, v176, v66
	v_cndmask_b32_e32 v68, v68, v69, vcc
	v_mul_f32_e32 v67, v177, v67
	v_mov_b32_e32 v69, s20
	v_mov_b32_e32 v73, s1
	v_cndmask_b32_e32 v69, v69, v73, vcc
	v_cvt_pk_bf16_f32 v67, v66, v67
	v_readlane_b32 s1, v72, 20
	v_and_b32_e32 v66, 0xffff0000, v67
	v_lshlrev_b32_e32 v73, 16, v67
	v_mul_f32_e32 v68, v178, v68
	v_max_f32_e64 v66, |v66|, |v66|
	v_max_f32_e64 v73, |v73|, |v73|
	v_max_f32_e32 v73, v73, v66
	v_mul_f32_e32 v69, v179, v69
	v_cvt_pk_bf16_f32 v66, v68, v69
	v_readlane_b32 s20, v72, 52
	v_and_b32_e32 v68, 0xffff0000, v66
	v_lshlrev_b32_e32 v69, 16, v66
	v_max_f32_e64 v68, |v68|, |v68|
	v_max_f32_e64 v69, |v69|, |v69|
	v_max_f32_e32 v68, v69, v68
	v_max3_f32 v75, v91, v73, v68
	v_mov_b32_e32 v68, s20
	v_mov_b32_e32 v69, s1
	v_readlane_b32 s1, v72, 21
	v_readlane_b32 s20, v72, 53
	v_cndmask_b32_e32 v68, v68, v69, vcc
	v_mov_b32_e32 v73, s1
	v_mov_b32_e32 v69, s20
	v_readlane_b32 s1, v72, 22
	v_readlane_b32 s20, v72, 54
	v_cndmask_b32_e32 v69, v69, v73, vcc
	v_mov_b32_e32 v80, s1
	v_mov_b32_e32 v73, s20
	v_readlane_b32 s1, v72, 23
	v_readlane_b32 s20, v72, 55
	v_mul_f32_e32 v68, v180, v68
	v_cndmask_b32_e32 v73, v73, v80, vcc
	v_mul_f32_e32 v69, v181, v69
	v_mov_b32_e32 v80, s20
	v_mov_b32_e32 v81, s1
	v_cndmask_b32_e32 v80, v80, v81, vcc
	v_cvt_pk_bf16_f32 v69, v68, v69
	v_mul_f32_e32 v73, v182, v73
	v_and_b32_e32 v68, 0xffff0000, v69
	v_mul_f32_e32 v80, v183, v80
	v_max_f32_e64 v81, |v68|, |v68|
	v_lshlrev_b32_e32 v68, 16, v69
	v_readlane_b32 s1, v72, 24
	v_readlane_b32 s20, v72, 56
	v_max_f32_e64 v82, |v68|, |v68|
	v_cvt_pk_bf16_f32 v68, v73, v80
	v_mov_b32_e32 v80, s1
	v_mov_b32_e32 v73, s20
	v_readlane_b32 s1, v72, 25
	v_readlane_b32 s20, v72, 57
	v_cndmask_b32_e32 v73, v73, v80, vcc
	v_mov_b32_e32 v83, s1
	v_mov_b32_e32 v80, s20
	v_readlane_b32 s1, v72, 26
	v_readlane_b32 s20, v72, 58
	v_cndmask_b32_e32 v80, v80, v83, vcc
	v_mov_b32_e32 v84, s1
	v_mov_b32_e32 v83, s20
	v_cndmask_b32_e32 v83, v83, v84, vcc
	v_readlane_b32 s1, v72, 27
	v_readlane_b32 s20, v72, 59
	v_mul_f32_e32 v70, v186, v83
	v_mov_b32_e32 v84, s1
	v_mov_b32_e32 v83, s20
	v_mul_f32_e32 v73, v184, v73
	v_mul_f32_e32 v80, v185, v80
	v_cndmask_b32_e32 v83, v83, v84, vcc
	v_readlane_b32 s1, v72, 28
	v_readlane_b32 s20, v72, 60
	v_mul_f32_e32 v83, v187, v83
	v_cvt_pk_bf16_f32 v71, v73, v80
	v_mov_b32_e32 v80, s1
	v_mov_b32_e32 v73, s20
	v_cndmask_b32_e32 v73, v73, v80, vcc
	v_readlane_b32 s1, v72, 29
	v_readlane_b32 s20, v72, 61
	v_mul_f32_e32 v73, v188, v73
	v_mov_b32_e32 v80, s1
	v_mov_b32_e32 v76, s20
	v_cndmask_b32_e32 v76, v76, v80, vcc
	v_readlane_b32 s1, v72, 30
	v_readlane_b32 s20, v72, 62
	v_mul_f32_e32 v76, v189, v76
	v_mov_b32_e32 v80, s1
	v_mov_b32_e32 v77, s20
	v_cndmask_b32_e32 v77, v77, v80, vcc
	v_readlane_b32 s1, v72, 31
	v_readlane_b32 s20, v72, 63
	v_mul_f32_e32 v77, v190, v77
	v_mov_b32_e32 v78, s1
	v_mov_b32_e32 v72, s20
	v_cndmask_b32_e32 v72, v72, v78, vcc
	v_mul_f32_e32 v72, v191, v72
	s_lshl_b32 s20, s0, 10
	v_cvt_pk_bf16_f32 v70, v70, v83
	v_cvt_pk_bf16_f32 v73, v73, v76
	v_cvt_pk_bf16_f32 v72, v77, v72
	v_lshl_add_u64 v[76:77], v[6:7], 0, s[20:21]
	v_and_b32_e32 v76, 0xffff0000, v68
	s_mul_i32 s20, s0, 0x404
	v_max_f32_e64 v79, |v76|, |v76|
	v_lshl_add_u64 v[76:77], v[6:7], 0, s[20:21]
	v_lshlrev_b32_e32 v76, 16, v68
	v_max_f32_e64 v76, |v76|, |v76|
	s_mul_i32 s20, s0, 0x408
	v_max_f32_e32 v79, v76, v79
	v_lshl_add_u64 v[76:77], v[6:7], 0, s[20:21]
	v_max_f32_e32 v78, v82, v81
	v_and_b32_e32 v76, 0xffff0000, v71
	s_mul_i32 s20, s0, 0x40c
	v_max3_f32 v75, v75, v78, v79
	v_max_f32_e64 v78, |v76|, |v76|
	v_lshl_add_u64 v[76:77], v[6:7], 0, s[20:21]
	v_lshlrev_b32_e32 v76, 16, v71
	v_max_f32_e64 v76, |v76|, |v76|
	v_max_f32_e32 v76, v76, v78
	v_and_b32_e32 v77, 0xffff0000, v70
	v_lshlrev_b32_e32 v78, 16, v70
	v_max_f32_e64 v77, |v77|, |v77|
	v_max_f32_e64 v78, |v78|, |v78|
	v_max_f32_e32 v77, v78, v77
	v_max3_f32 v75, v75, v76, v77
	v_and_b32_e32 v76, 0xffff0000, v73
	v_lshlrev_b32_e32 v77, 16, v73
	v_max_f32_e64 v76, |v76|, |v76|
	v_max_f32_e64 v77, |v77|, |v77|
	v_max_f32_e32 v78, v77, v76
	v_and_b32_e32 v76, 0xffff0000, v72
	s_mul_i32 s20, s0, 0x410
	v_max_f32_e64 v79, |v76|, |v76|
	v_lshl_add_u64 v[76:77], v[6:7], 0, s[20:21]
	v_lshlrev_b32_e32 v76, 16, v72
	v_max_f32_e64 v76, |v76|, |v76|
	s_mul_i32 s20, s0, 0x414
	v_max_f32_e32 v79, v76, v79
	v_lshl_add_u64 v[76:77], v[6:7], 0, s[20:21]
	s_mul_i32 s20, s0, 0x418
	v_lshl_add_u64 v[76:77], v[6:7], 0, s[20:21]
	s_mul_i32 s20, s0, 0x41c
	v_max3_f32 v99, v75, v78, v79
	v_lshl_add_u64 v[78:79], v[6:7], 0, s[20:21]
	s_mul_i32 s20, s0, 0x420
	v_lshl_add_u64 v[76:77], v[6:7], 0, s[20:21]
	s_mul_i32 s20, s0, 0x424
	v_lshl_add_u64 v[78:79], v[6:7], 0, s[20:21]
	s_mul_i32 s20, s0, 0x428
	v_lshl_add_u64 v[80:81], v[6:7], 0, s[20:21]
	s_mul_i32 s20, s0, 0x42c
	v_lshl_add_u64 v[82:83], v[6:7], 0, s[20:21]
	s_mul_i32 s20, s0, 0x430
	v_lshl_add_u64 v[84:85], v[6:7], 0, s[20:21]
	s_mul_i32 s20, s0, 0x434
	v_lshl_add_u64 v[86:87], v[6:7], 0, s[20:21]
	s_mul_i32 s20, s0, 0x438
	v_lshl_add_u64 v[90:91], v[6:7], 0, s[20:21]
	s_mul_i32 s20, s0, 0x43c
	v_lshl_add_u64 v[92:93], v[6:7], 0, s[20:21]
	s_nop 0
	s_nop 0
	s_nop 0
	s_nop 0
	s_nop 0
	v_readlane_b32 s1, v89, 0
	v_readlane_b32 s20, v89, 32
	s_nop 0
	v_mov_b32_e32 v76, s1
	v_mov_b32_e32 v75, s20
	v_readlane_b32 s1, v89, 1
	v_readlane_b32 s20, v89, 33
	v_cndmask_b32_e32 v75, v75, v76, vcc
	v_mov_b32_e32 v77, s1
	v_mov_b32_e32 v76, s20
	v_readlane_b32 s1, v89, 2
	v_readlane_b32 s20, v89, 34
	v_cndmask_b32_e32 v76, v76, v77, vcc
	v_mov_b32_e32 v78, s1
	v_mov_b32_e32 v77, s20
	v_readlane_b32 s1, v89, 3
	v_readlane_b32 s20, v89, 35
	s_mov_b32 s101, 0
	s_mul_i32 s100, s0, 0x440
	v_lshl_add_u64 v[154:155], v[6:7], 0, s[100:101]
	global_load_dword v176, v[154:155], off
	s_mul_i32 s100, s0, 0x444
	v_lshl_add_u64 v[154:155], v[6:7], 0, s[100:101]
	global_load_dword v177, v[154:155], off
	s_mul_i32 s100, s0, 0x448
	v_lshl_add_u64 v[154:155], v[6:7], 0, s[100:101]
	global_load_dword v178, v[154:155], off
	s_mul_i32 s100, s0, 0x44c
	v_lshl_add_u64 v[154:155], v[6:7], 0, s[100:101]
	global_load_dword v179, v[154:155], off
	s_mul_i32 s100, s0, 0x450
	v_lshl_add_u64 v[154:155], v[6:7], 0, s[100:101]
	global_load_dword v180, v[154:155], off
	s_mul_i32 s100, s0, 0x454
	v_lshl_add_u64 v[154:155], v[6:7], 0, s[100:101]
	global_load_dword v181, v[154:155], off
	s_mul_i32 s100, s0, 0x458
	v_lshl_add_u64 v[154:155], v[6:7], 0, s[100:101]
	global_load_dword v182, v[154:155], off
	s_mul_i32 s100, s0, 0x45c
	v_lshl_add_u64 v[154:155], v[6:7], 0, s[100:101]
	global_load_dword v183, v[154:155], off
	s_mul_i32 s100, s0, 0x460
	v_lshl_add_u64 v[154:155], v[6:7], 0, s[100:101]
	global_load_dword v184, v[154:155], off
	s_mul_i32 s100, s0, 0x464
	v_lshl_add_u64 v[154:155], v[6:7], 0, s[100:101]
	global_load_dword v185, v[154:155], off
	s_mul_i32 s100, s0, 0x468
	v_lshl_add_u64 v[154:155], v[6:7], 0, s[100:101]
	global_load_dword v186, v[154:155], off
	s_mul_i32 s100, s0, 0x46c
	v_lshl_add_u64 v[154:155], v[6:7], 0, s[100:101]
	global_load_dword v187, v[154:155], off
	s_mul_i32 s100, s0, 0x470
	v_lshl_add_u64 v[154:155], v[6:7], 0, s[100:101]
	global_load_dword v188, v[154:155], off
	s_mul_i32 s100, s0, 0x474
	v_lshl_add_u64 v[154:155], v[6:7], 0, s[100:101]
	global_load_dword v189, v[154:155], off
	s_mul_i32 s100, s0, 0x478
	v_lshl_add_u64 v[154:155], v[6:7], 0, s[100:101]
	global_load_dword v190, v[154:155], off
	s_mul_i32 s100, s0, 0x47c
	v_lshl_add_u64 v[154:155], v[6:7], 0, s[100:101]
	global_load_dword v191, v[154:155], off
	s_waitcnt vmcnt(16) lgkmcnt(0)
	v_mul_f32_e32 v75, v160, v75
	v_mul_f32_e32 v76, v161, v76
	v_cndmask_b32_e32 v77, v77, v78, vcc
	v_mov_b32_e32 v78, s20
	v_mov_b32_e32 v86, s1
	v_cndmask_b32_e32 v78, v78, v86, vcc
	v_cvt_pk_bf16_f32 v76, v75, v76
	v_readlane_b32 s1, v89, 4
	v_and_b32_e32 v75, 0xffff0000, v76
	v_lshlrev_b32_e32 v86, 16, v76
	v_mul_f32_e32 v77, v162, v77
	v_max_f32_e64 v75, |v75|, |v75|
	v_max_f32_e64 v86, |v86|, |v86|
	v_max_f32_e32 v86, v86, v75
	v_mul_f32_e32 v78, v163, v78
	v_cvt_pk_bf16_f32 v75, v77, v78
	v_readlane_b32 s20, v89, 36
	v_and_b32_e32 v77, 0xffff0000, v75
	v_lshlrev_b32_e32 v78, 16, v75
	v_max_f32_e64 v77, |v77|, |v77|
	v_max_f32_e64 v78, |v78|, |v78|
	v_max_f32_e32 v77, v78, v77
	v_max3_f32 v86, v99, v86, v77
	v_mov_b32_e32 v77, s20
	v_mov_b32_e32 v78, s1
	v_readlane_b32 s1, v89, 5
	v_readlane_b32 s20, v89, 37
	v_cndmask_b32_e32 v77, v77, v78, vcc
	v_mov_b32_e32 v87, s1
	v_mov_b32_e32 v78, s20
	v_readlane_b32 s1, v89, 6
	v_readlane_b32 s20, v89, 38
	v_cndmask_b32_e32 v78, v78, v87, vcc
	v_mov_b32_e32 v88, s1
	v_mov_b32_e32 v87, s20
	v_readlane_b32 s1, v89, 7
	v_readlane_b32 s20, v89, 39
	v_mul_f32_e32 v77, v164, v77
	v_cndmask_b32_e32 v87, v87, v88, vcc
	v_mul_f32_e32 v78, v165, v78
	v_mov_b32_e32 v88, s20
	v_mov_b32_e32 v90, s1
	v_cndmask_b32_e32 v88, v88, v90, vcc
	v_cvt_pk_bf16_f32 v78, v77, v78
	v_mul_f32_e32 v87, v166, v87
	v_and_b32_e32 v77, 0xffff0000, v78
	v_mul_f32_e32 v88, v167, v88
	v_max_f32_e64 v90, |v77|, |v77|
	v_lshlrev_b32_e32 v77, 16, v78
	v_readlane_b32 s1, v89, 8
	v_readlane_b32 s20, v89, 40
	v_max_f32_e64 v91, |v77|, |v77|
	v_cvt_pk_bf16_f32 v77, v87, v88
	v_mov_b32_e32 v88, s1
	v_mov_b32_e32 v87, s20
	v_readlane_b32 s1, v89, 9
	v_readlane_b32 s20, v89, 41
	v_cndmask_b32_e32 v87, v87, v88, vcc
	v_mov_b32_e32 v92, s1
	v_mov_b32_e32 v88, s20
	v_cndmask_b32_e32 v88, v88, v92, vcc
	v_readlane_b32 s1, v89, 10
	v_readlane_b32 s20, v89, 42
	v_mul_f32_e32 v79, v169, v88
	v_mov_b32_e32 v92, s1
	v_mov_b32_e32 v88, s20
	v_cndmask_b32_e32 v88, v88, v92, vcc
	v_readlane_b32 s1, v89, 11
	v_readlane_b32 s20, v89, 43
	v_mul_f32_e32 v88, v170, v88
	v_mov_b32_e32 v92, s1
	v_mov_b32_e32 v80, s20
	v_cndmask_b32_e32 v80, v80, v92, vcc
	v_mul_f32_e32 v87, v168, v87
	v_mul_f32_e32 v81, v171, v80
	v_readlane_b32 s1, v89, 12
	v_readlane_b32 s20, v89, 44
	v_cvt_pk_bf16_f32 v80, v87, v79
	v_cvt_pk_bf16_f32 v79, v88, v81
	s_nop 0
	v_mov_b32_e32 v87, s1
	v_mov_b32_e32 v81, s20
	v_cndmask_b32_e32 v81, v81, v87, vcc
	v_readlane_b32 s1, v89, 13
	v_readlane_b32 s20, v89, 45
	v_mul_f32_e32 v81, v172, v81
	v_mov_b32_e32 v87, s1
	v_mov_b32_e32 v82, s20
	v_cndmask_b32_e32 v82, v82, v87, vcc
	v_readlane_b32 s1, v89, 14
	v_readlane_b32 s20, v89, 46
	v_mul_f32_e32 v82, v173, v82
	v_mov_b32_e32 v87, s1
	v_mov_b32_e32 v83, s20
	v_cndmask_b32_e32 v83, v83, v87, vcc
	v_readlane_b32 s1, v89, 15
	v_readlane_b32 s20, v89, 47
	v_mul_f32_e32 v83, v174, v83
	v_mov_b32_e32 v87, s1
	v_mov_b32_e32 v84, s20
	v_cndmask_b32_e32 v84, v84, v87, vcc
	v_mul_f32_e32 v84, v175, v84
	s_mul_i32 s20, s0, 0x440
	v_cvt_pk_bf16_f32 v82, v81, v82
	v_cvt_pk_bf16_f32 v81, v83, v84
	v_lshl_add_u64 v[84:85], v[6:7], 0, s[20:21]
	v_and_b32_e32 v84, 0xffff0000, v77
	s_mul_i32 s20, s0, 0x444
	v_max_f32_e64 v88, |v84|, |v84|
	v_lshl_add_u64 v[84:85], v[6:7], 0, s[20:21]
	v_lshlrev_b32_e32 v84, 16, v77
	v_max_f32_e64 v84, |v84|, |v84|
	s_mul_i32 s20, s0, 0x448
	v_max_f32_e32 v88, v84, v88
	v_lshl_add_u64 v[84:85], v[6:7], 0, s[20:21]
	v_max_f32_e32 v87, v91, v90
	v_and_b32_e32 v84, 0xffff0000, v80
	s_mul_i32 s20, s0, 0x44c
	v_max3_f32 v86, v86, v87, v88
	v_max_f32_e64 v87, |v84|, |v84|
	v_lshl_add_u64 v[84:85], v[6:7], 0, s[20:21]
	v_lshlrev_b32_e32 v84, 16, v80
	v_max_f32_e64 v84, |v84|, |v84|
	v_max_f32_e32 v84, v84, v87
	v_and_b32_e32 v85, 0xffff0000, v79
	v_lshlrev_b32_e32 v87, 16, v79
	v_max_f32_e64 v85, |v85|, |v85|
	v_max_f32_e64 v87, |v87|, |v87|
	v_max_f32_e32 v85, v87, v85
	v_max3_f32 v86, v86, v84, v85
	v_and_b32_e32 v84, 0xffff0000, v82
	v_lshlrev_b32_e32 v85, 16, v82
	v_max_f32_e64 v84, |v84|, |v84|
	v_max_f32_e64 v85, |v85|, |v85|
	v_max_f32_e32 v87, v85, v84
	v_and_b32_e32 v84, 0xffff0000, v81
	s_mul_i32 s20, s0, 0x450
	v_max_f32_e64 v90, |v84|, |v84|
	v_lshl_add_u64 v[84:85], v[6:7], 0, s[20:21]
	v_lshlrev_b32_e32 v84, 16, v81
	v_max_f32_e64 v84, |v84|, |v84|
	s_mul_i32 s20, s0, 0x454
	v_max_f32_e32 v90, v84, v90
	v_lshl_add_u64 v[84:85], v[6:7], 0, s[20:21]
	s_mul_i32 s20, s0, 0x458
	v_lshl_add_u64 v[84:85], v[6:7], 0, s[20:21]
	s_mul_i32 s20, s0, 0x45c
	v_max3_f32 v106, v86, v87, v90
	v_lshl_add_u64 v[86:87], v[6:7], 0, s[20:21]
	s_mul_i32 s20, s0, 0x460
	v_lshl_add_u64 v[84:85], v[6:7], 0, s[20:21]
	s_mul_i32 s20, s0, 0x464
	v_lshl_add_u64 v[86:87], v[6:7], 0, s[20:21]
	s_mul_i32 s20, s0, 0x468
	v_lshl_add_u64 v[90:91], v[6:7], 0, s[20:21]
	s_mul_i32 s20, s0, 0x46c
	v_lshl_add_u64 v[92:93], v[6:7], 0, s[20:21]
	s_mul_i32 s20, s0, 0x470
	v_lshl_add_u64 v[94:95], v[6:7], 0, s[20:21]
	s_mul_i32 s20, s0, 0x474
	v_lshl_add_u64 v[96:97], v[6:7], 0, s[20:21]
	s_mul_i32 s20, s0, 0x478
	v_lshl_add_u64 v[98:99], v[6:7], 0, s[20:21]
	s_mul_i32 s20, s0, 0x47c
	v_lshl_add_u64 v[100:101], v[6:7], 0, s[20:21]
	s_nop 0
	s_nop 0
	s_nop 0
	s_nop 0
	s_nop 0
	v_readlane_b32 s1, v89, 16
	v_readlane_b32 s20, v89, 48
	s_nop 0
	v_mov_b32_e32 v85, s1
	v_mov_b32_e32 v84, s20
	v_cndmask_b32_e32 v84, v84, v85, vcc
	v_readlane_b32 s1, v89, 17
	v_readlane_b32 s20, v89, 49
	s_mov_b32 s101, 0
	s_mul_i32 s100, s0, 0x500
	v_lshl_add_u64 v[154:155], v[6:7], 0, s[100:101]
	global_load_dword v160, v[154:155], off
	s_mul_i32 s100, s0, 0x504
	v_lshl_add_u64 v[154:155], v[6:7], 0, s[100:101]
	global_load_dword v161, v[154:155], off
	s_mul_i32 s100, s0, 0x508
	v_lshl_add_u64 v[154:155], v[6:7], 0, s[100:101]
	global_load_dword v162, v[154:155], off
	s_mul_i32 s100, s0, 0x50c
	v_lshl_add_u64 v[154:155], v[6:7], 0, s[100:101]
	global_load_dword v163, v[154:155], off
	s_mul_i32 s100, s0, 0x510
	v_lshl_add_u64 v[154:155], v[6:7], 0, s[100:101]
	global_load_dword v164, v[154:155], off
	s_mul_i32 s100, s0, 0x514
	v_lshl_add_u64 v[154:155], v[6:7], 0, s[100:101]
	global_load_dword v165, v[154:155], off
	s_mul_i32 s100, s0, 0x518
	v_lshl_add_u64 v[154:155], v[6:7], 0, s[100:101]
	global_load_dword v166, v[154:155], off
	s_mul_i32 s100, s0, 0x51c
	v_lshl_add_u64 v[154:155], v[6:7], 0, s[100:101]
	global_load_dword v167, v[154:155], off
	s_mul_i32 s100, s0, 0x520
	v_lshl_add_u64 v[154:155], v[6:7], 0, s[100:101]
	global_load_dword v168, v[154:155], off
	s_mul_i32 s100, s0, 0x524
	v_lshl_add_u64 v[154:155], v[6:7], 0, s[100:101]
	global_load_dword v169, v[154:155], off
	s_mul_i32 s100, s0, 0x528
	v_lshl_add_u64 v[154:155], v[6:7], 0, s[100:101]
	global_load_dword v170, v[154:155], off
	s_mul_i32 s100, s0, 0x52c
	v_lshl_add_u64 v[154:155], v[6:7], 0, s[100:101]
	global_load_dword v171, v[154:155], off
	s_mul_i32 s100, s0, 0x530
	v_lshl_add_u64 v[154:155], v[6:7], 0, s[100:101]
	global_load_dword v172, v[154:155], off
	s_mul_i32 s100, s0, 0x534
	v_lshl_add_u64 v[154:155], v[6:7], 0, s[100:101]
	global_load_dword v173, v[154:155], off
	s_mul_i32 s100, s0, 0x538
	v_lshl_add_u64 v[154:155], v[6:7], 0, s[100:101]
	global_load_dword v174, v[154:155], off
	s_mul_i32 s100, s0, 0x53c
	v_lshl_add_u64 v[154:155], v[6:7], 0, s[100:101]
	global_load_dword v175, v[154:155], off
	s_waitcnt vmcnt(16) lgkmcnt(0)
	v_mul_f32_e32 v83, v176, v84
	v_mov_b32_e32 v84, s20
	v_mov_b32_e32 v85, s1
	v_readlane_b32 s1, v89, 18
	v_readlane_b32 s20, v89, 50
	v_cndmask_b32_e32 v84, v84, v85, vcc
	v_mov_b32_e32 v86, s1
	v_mov_b32_e32 v85, s20
	v_readlane_b32 s1, v89, 19
	v_readlane_b32 s20, v89, 51
	v_cndmask_b32_e32 v85, v85, v86, vcc
	v_mov_b32_e32 v96, s1
	v_mov_b32_e32 v86, s20
	v_mul_f32_e32 v84, v177, v84
	v_cndmask_b32_e32 v86, v86, v96, vcc
	v_cvt_pk_bf16_f32 v84, v83, v84
	v_mul_f32_e32 v85, v178, v85
	v_and_b32_e32 v83, 0xffff0000, v84
	v_mul_f32_e32 v86, v179, v86
	v_lshlrev_b32_e32 v88, 16, v84
	v_max_f32_e64 v83, |v83|, |v83|
	v_max_f32_e64 v88, |v88|, |v88|
	v_max_f32_e32 v88, v88, v83
	v_cvt_pk_bf16_f32 v83, v85, v86
	v_readlane_b32 s1, v89, 20
	v_and_b32_e32 v85, 0xffff0000, v83
	v_lshlrev_b32_e32 v86, 16, v83
	v_max_f32_e64 v85, |v85|, |v85|
	v_max_f32_e64 v86, |v86|, |v86|
	v_max_f32_e32 v85, v86, v85
	v_readlane_b32 s20, v89, 52
	v_max3_f32 v96, v106, v88, v85
	v_mov_b32_e32 v86, s1
	v_mov_b32_e32 v85, s20
	v_readlane_b32 s1, v89, 21
	v_readlane_b32 s20, v89, 53
	v_cndmask_b32_e32 v85, v85, v86, vcc
	v_mov_b32_e32 v88, s1
	v_mov_b32_e32 v86, s20
	v_readlane_b32 s1, v89, 22
	v_readlane_b32 s20, v89, 54
	v_cndmask_b32_e32 v86, v86, v88, vcc
	v_mov_b32_e32 v97, s1
	v_mov_b32_e32 v88, s20
	v_readlane_b32 s1, v89, 23
	v_readlane_b32 s20, v89, 55
	v_mul_f32_e32 v85, v180, v85
	v_mul_f32_e32 v86, v181, v86
	v_cndmask_b32_e32 v88, v88, v97, vcc
	v_mov_b32_e32 v97, s20
	v_mov_b32_e32 v98, s1
	v_cndmask_b32_e32 v97, v97, v98, vcc
	v_cvt_pk_bf16_f32 v86, v85, v86
	v_mul_f32_e32 v88, v182, v88
	v_and_b32_e32 v85, 0xffff0000, v86
	v_mul_f32_e32 v97, v183, v97
	v_max_f32_e64 v98, |v85|, |v85|
	v_lshlrev_b32_e32 v85, 16, v86
	v_readlane_b32 s1, v89, 24
	v_readlane_b32 s20, v89, 56
	v_max_f32_e64 v99, |v85|, |v85|
	v_cvt_pk_bf16_f32 v85, v88, v97
	v_mov_b32_e32 v97, s1
	v_mov_b32_e32 v88, s20
	v_readlane_b32 s1, v89, 25
	v_readlane_b32 s20, v89, 57
	v_cndmask_b32_e32 v88, v88, v97, vcc
	v_mov_b32_e32 v100, s1
	v_mov_b32_e32 v97, s20
	v_cndmask_b32_e32 v97, v97, v100, vcc
	v_readlane_b32 s1, v89, 26
	v_readlane_b32 s20, v89, 58
	v_mul_f32_e32 v87, v185, v97
	v_mov_b32_e32 v100, s1
	v_mov_b32_e32 v97, s20
	v_cndmask_b32_e32 v97, v97, v100, vcc
	v_readlane_b32 s1, v89, 27
	v_readlane_b32 s20, v89, 59
	v_mul_f32_e32 v90, v186, v97
	v_mov_b32_e32 v100, s1
	v_mov_b32_e32 v97, s20
	v_cndmask_b32_e32 v97, v97, v100, vcc
	v_mul_f32_e32 v88, v184, v88
	v_mul_f32_e32 v91, v187, v97
	v_readlane_b32 s1, v89, 28
	v_readlane_b32 s20, v89, 60
	v_cvt_pk_bf16_f32 v88, v88, v87
	v_cvt_pk_bf16_f32 v87, v90, v91
	s_nop 0
	v_mov_b32_e32 v91, s1
	v_mov_b32_e32 v90, s20
	v_cndmask_b32_e32 v90, v90, v91, vcc
	v_readlane_b32 s1, v89, 29
	v_readlane_b32 s20, v89, 61
	v_mul_f32_e32 v90, v188, v90
	v_mov_b32_e32 v92, s1
	v_mov_b32_e32 v91, s20
	v_cndmask_b32_e32 v91, v91, v92, vcc
	v_readlane_b32 s1, v89, 30
	v_readlane_b32 s20, v89, 62
	v_mul_f32_e32 v91, v189, v91
	v_mov_b32_e32 v93, s1
	v_mov_b32_e32 v92, s20
	v_readlane_b32 s1, v89, 31
	v_readlane_b32 s20, v89, 63
	v_cndmask_b32_e32 v92, v92, v93, vcc
	v_mov_b32_e32 v93, s1
	v_mov_b32_e32 v89, s20
	v_cndmask_b32_e32 v89, v89, v93, vcc
	v_mul_f32_e32 v92, v190, v92
	v_mul_f32_e32 v89, v191, v89
	s_mul_i32 s20, s0, 0x500
	v_cvt_pk_bf16_f32 v90, v90, v91
	v_cvt_pk_bf16_f32 v89, v92, v89
	v_lshl_add_u64 v[92:93], v[6:7], 0, s[20:21]
	v_and_b32_e32 v92, 0xffff0000, v85
	s_mul_i32 s20, s0, 0x504
	v_max_f32_e64 v95, |v92|, |v92|
	v_lshl_add_u64 v[92:93], v[6:7], 0, s[20:21]
	v_lshlrev_b32_e32 v92, 16, v85
	v_max_f32_e64 v92, |v92|, |v92|
	s_mul_i32 s20, s0, 0x508
	v_max_f32_e32 v95, v92, v95
	v_lshl_add_u64 v[92:93], v[6:7], 0, s[20:21]
	v_max_f32_e32 v94, v99, v98
	v_and_b32_e32 v92, 0xffff0000, v88
	s_mul_i32 s20, s0, 0x50c
	v_max3_f32 v94, v96, v94, v95
	v_max_f32_e64 v95, |v92|, |v92|
	v_lshl_add_u64 v[92:93], v[6:7], 0, s[20:21]
	v_lshlrev_b32_e32 v92, 16, v88
	v_max_f32_e64 v92, |v92|, |v92|
	v_max_f32_e32 v92, v92, v95
	v_and_b32_e32 v93, 0xffff0000, v87
	v_lshlrev_b32_e32 v95, 16, v87
	v_max_f32_e64 v93, |v93|, |v93|
	v_max_f32_e64 v95, |v95|, |v95|
	v_max_f32_e32 v93, v95, v93
	v_max3_f32 v94, v94, v92, v93
	v_and_b32_e32 v92, 0xffff0000, v90
	v_lshlrev_b32_e32 v93, 16, v90
	v_max_f32_e64 v92, |v92|, |v92|
	v_max_f32_e64 v93, |v93|, |v93|
	v_max_f32_e32 v95, v93, v92
	v_and_b32_e32 v92, 0xffff0000, v89
	s_mul_i32 s20, s0, 0x510
	v_max_f32_e64 v96, |v92|, |v92|
	v_lshl_add_u64 v[92:93], v[6:7], 0, s[20:21]
	v_lshlrev_b32_e32 v92, 16, v89
	v_max_f32_e64 v92, |v92|, |v92|
	s_mul_i32 s20, s0, 0x514
	v_max_f32_e32 v96, v92, v96
	v_lshl_add_u64 v[92:93], v[6:7], 0, s[20:21]
	s_mul_i32 s20, s0, 0x518
	v_lshl_add_u64 v[92:93], v[6:7], 0, s[20:21]
	s_mul_i32 s20, s0, 0x51c
	v_max3_f32 v113, v94, v95, v96
	v_lshl_add_u64 v[94:95], v[6:7], 0, s[20:21]
	s_mul_i32 s20, s0, 0x520
	v_lshl_add_u64 v[92:93], v[6:7], 0, s[20:21]
	s_mul_i32 s20, s0, 0x524
	v_lshl_add_u64 v[94:95], v[6:7], 0, s[20:21]
	s_mul_i32 s20, s0, 0x528
	v_lshl_add_u64 v[96:97], v[6:7], 0, s[20:21]
	s_mul_i32 s20, s0, 0x52c
	v_lshl_add_u64 v[98:99], v[6:7], 0, s[20:21]
	s_mul_i32 s20, s0, 0x530
	v_lshl_add_u64 v[100:101], v[6:7], 0, s[20:21]
	s_mul_i32 s20, s0, 0x534
	v_lshl_add_u64 v[102:103], v[6:7], 0, s[20:21]
	s_mul_i32 s20, s0, 0x538
	v_lshl_add_u64 v[104:105], v[6:7], 0, s[20:21]
	s_mul_i32 s20, s0, 0x53c
	v_lshl_add_u64 v[106:107], v[6:7], 0, s[20:21]
	s_nop 0
	s_nop 0
	s_nop 0
	s_nop 0
	s_nop 0
	v_readlane_b32 s1, v74, 0
	v_readlane_b32 s20, v74, 32
	s_nop 0
	v_mov_b32_e32 v93, s1
	v_mov_b32_e32 v92, s20
	v_cndmask_b32_e32 v92, v92, v93, vcc
	v_readlane_b32 s1, v74, 1
	v_readlane_b32 s20, v74, 33
	s_mov_b32 s101, 0
	s_mul_i32 s100, s0, 0x540
	v_lshl_add_u64 v[154:155], v[6:7], 0, s[100:101]
	global_load_dword v176, v[154:155], off
	s_mul_i32 s100, s0, 0x544
	v_lshl_add_u64 v[154:155], v[6:7], 0, s[100:101]
	global_load_dword v177, v[154:155], off
	s_mul_i32 s100, s0, 0x548
	v_lshl_add_u64 v[154:155], v[6:7], 0, s[100:101]
	global_load_dword v178, v[154:155], off
	s_mul_i32 s100, s0, 0x54c
	v_lshl_add_u64 v[154:155], v[6:7], 0, s[100:101]
	global_load_dword v179, v[154:155], off
	s_mul_i32 s100, s0, 0x550
	v_lshl_add_u64 v[154:155], v[6:7], 0, s[100:101]
	global_load_dword v180, v[154:155], off
	s_mul_i32 s100, s0, 0x554
	v_lshl_add_u64 v[154:155], v[6:7], 0, s[100:101]
	global_load_dword v181, v[154:155], off
	s_mul_i32 s100, s0, 0x558
	v_lshl_add_u64 v[154:155], v[6:7], 0, s[100:101]
	global_load_dword v182, v[154:155], off
	s_mul_i32 s100, s0, 0x55c
	v_lshl_add_u64 v[154:155], v[6:7], 0, s[100:101]
	global_load_dword v183, v[154:155], off
	s_mul_i32 s100, s0, 0x560
	v_lshl_add_u64 v[154:155], v[6:7], 0, s[100:101]
	global_load_dword v184, v[154:155], off
	s_mul_i32 s100, s0, 0x564
	v_lshl_add_u64 v[154:155], v[6:7], 0, s[100:101]
	global_load_dword v185, v[154:155], off
	s_mul_i32 s100, s0, 0x568
	v_lshl_add_u64 v[154:155], v[6:7], 0, s[100:101]
	global_load_dword v186, v[154:155], off
	s_mul_i32 s100, s0, 0x56c
	v_lshl_add_u64 v[154:155], v[6:7], 0, s[100:101]
	global_load_dword v187, v[154:155], off
	s_mul_i32 s100, s0, 0x570
	v_lshl_add_u64 v[154:155], v[6:7], 0, s[100:101]
	global_load_dword v188, v[154:155], off
	s_mul_i32 s100, s0, 0x574
	v_lshl_add_u64 v[154:155], v[6:7], 0, s[100:101]
	global_load_dword v189, v[154:155], off
	s_mul_i32 s100, s0, 0x578
	v_lshl_add_u64 v[154:155], v[6:7], 0, s[100:101]
	global_load_dword v190, v[154:155], off
	s_mul_i32 s100, s0, 0x57c
	v_lshl_add_u64 v[154:155], v[6:7], 0, s[100:101]
	global_load_dword v191, v[154:155], off
	s_waitcnt vmcnt(16) lgkmcnt(0)
	v_mul_f32_e32 v91, v160, v92
	v_mov_b32_e32 v92, s20
	v_mov_b32_e32 v93, s1
	v_readlane_b32 s1, v74, 2
	v_readlane_b32 s20, v74, 34
	v_cndmask_b32_e32 v92, v92, v93, vcc
	v_mov_b32_e32 v94, s1
	v_mov_b32_e32 v93, s20
	v_readlane_b32 s1, v74, 3
	v_readlane_b32 s20, v74, 35
	v_mul_f32_e32 v92, v161, v92
	v_cndmask_b32_e32 v93, v93, v94, vcc
	v_mov_b32_e32 v94, s20
	v_mov_b32_e32 v102, s1
	v_cndmask_b32_e32 v94, v94, v102, vcc
	v_cvt_pk_bf16_f32 v92, v91, v92
	v_mul_f32_e32 v93, v162, v93
	v_and_b32_e32 v91, 0xffff0000, v92
	v_lshlrev_b32_e32 v102, 16, v92
	v_mul_f32_e32 v94, v163, v94
	v_max_f32_e64 v91, |v91|, |v91|
	v_max_f32_e64 v102, |v102|, |v102|
	v_max_f32_e32 v102, v102, v91
	v_cvt_pk_bf16_f32 v91, v93, v94
	v_readlane_b32 s1, v74, 4
	v_and_b32_e32 v93, 0xffff0000, v91
	v_lshlrev_b32_e32 v94, 16, v91
	v_max_f32_e64 v93, |v93|, |v93|
	v_max_f32_e64 v94, |v94|, |v94|
	v_max_f32_e32 v93, v94, v93
	v_readlane_b32 s20, v74, 36
	v_max3_f32 v102, v113, v102, v93
	v_mov_b32_e32 v94, s1
	v_mov_b32_e32 v93, s20
	v_readlane_b32 s1, v74, 5
	v_readlane_b32 s20, v74, 37
	v_cndmask_b32_e32 v93, v93, v94, vcc
	v_mov_b32_e32 v103, s1
	v_mov_b32_e32 v94, s20
	v_readlane_b32 s1, v74, 6
	v_readlane_b32 s20, v74, 38
	v_cndmask_b32_e32 v94, v94, v103, vcc
	v_mov_b32_e32 v104, s1
	v_mov_b32_e32 v103, s20
	v_readlane_b32 s1, v74, 7
	v_readlane_b32 s20, v74, 39
	v_mul_f32_e32 v93, v164, v93
	v_mul_f32_e32 v94, v165, v94
	v_cndmask_b32_e32 v103, v103, v104, vcc
	v_mov_b32_e32 v104, s20
	v_mov_b32_e32 v105, s1
	v_cndmask_b32_e32 v104, v104, v105, vcc
	v_cvt_pk_bf16_f32 v94, v93, v94
	v_mul_f32_e32 v103, v166, v103
	v_and_b32_e32 v93, 0xffff0000, v94
	v_mul_f32_e32 v104, v167, v104
	v_max_f32_e64 v105, |v93|, |v93|
	v_lshlrev_b32_e32 v93, 16, v94
	v_readlane_b32 s1, v74, 8
	v_readlane_b32 s20, v74, 40
	v_max_f32_e64 v106, |v93|, |v93|
	v_cvt_pk_bf16_f32 v93, v103, v104
	v_mov_b32_e32 v104, s1
	v_mov_b32_e32 v103, s20
	v_readlane_b32 s1, v74, 9
	v_readlane_b32 s20, v74, 41
	v_cndmask_b32_e32 v103, v103, v104, vcc
	v_mov_b32_e32 v107, s1
	v_mov_b32_e32 v104, s20
	v_cndmask_b32_e32 v104, v104, v107, vcc
	v_readlane_b32 s1, v74, 10
	v_readlane_b32 s20, v74, 42
	v_mul_f32_e32 v95, v169, v104
	v_mov_b32_e32 v107, s1
	v_mov_b32_e32 v104, s20
	v_cndmask_b32_e32 v104, v104, v107, vcc
	v_readlane_b32 s1, v74, 11
	v_readlane_b32 s20, v74, 43
	v_mul_f32_e32 v104, v170, v104
	v_mov_b32_e32 v107, s1
	v_mov_b32_e32 v96, s20
	v_cndmask_b32_e32 v96, v96, v107, vcc
	v_mul_f32_e32 v103, v168, v103
	v_mul_f32_e32 v97, v171, v96
	v_readlane_b32 s1, v74, 12
	v_readlane_b32 s20, v74, 44
	v_cvt_pk_bf16_f32 v96, v103, v95
	v_cvt_pk_bf16_f32 v95, v104, v97
	s_nop 0
	v_mov_b32_e32 v103, s1
	v_mov_b32_e32 v97, s20
	v_cndmask_b32_e32 v97, v97, v103, vcc
	v_readlane_b32 s1, v74, 13
	v_readlane_b32 s20, v74, 45
	v_mul_f32_e32 v97, v172, v97
	v_mov_b32_e32 v103, s1
	v_mov_b32_e32 v98, s20
	v_cndmask_b32_e32 v98, v98, v103, vcc
	v_readlane_b32 s1, v74, 14
	v_readlane_b32 s20, v74, 46
	v_mul_f32_e32 v98, v173, v98
	v_mov_b32_e32 v103, s1
	v_mov_b32_e32 v99, s20
	v_cndmask_b32_e32 v99, v99, v103, vcc
	v_readlane_b32 s1, v74, 15
	v_readlane_b32 s20, v74, 47
	v_mul_f32_e32 v99, v174, v99
	v_mov_b32_e32 v103, s1
	v_mov_b32_e32 v100, s20
	v_cndmask_b32_e32 v100, v100, v103, vcc
	v_mul_f32_e32 v100, v175, v100
	s_mul_i32 s20, s0, 0x540
	v_cvt_pk_bf16_f32 v98, v97, v98
	v_cvt_pk_bf16_f32 v97, v99, v100
	v_lshl_add_u64 v[100:101], v[6:7], 0, s[20:21]
	v_and_b32_e32 v100, 0xffff0000, v93
	s_mul_i32 s20, s0, 0x544
	v_max_f32_e64 v104, |v100|, |v100|
	v_lshl_add_u64 v[100:101], v[6:7], 0, s[20:21]
	v_lshlrev_b32_e32 v100, 16, v93
	v_max_f32_e64 v100, |v100|, |v100|
	s_mul_i32 s20, s0, 0x548
	v_max_f32_e32 v104, v100, v104
	v_lshl_add_u64 v[100:101], v[6:7], 0, s[20:21]
	v_max_f32_e32 v103, v106, v105
	v_and_b32_e32 v100, 0xffff0000, v96
	s_mul_i32 s20, s0, 0x54c
	v_max3_f32 v102, v102, v103, v104
	v_max_f32_e64 v103, |v100|, |v100|
	v_lshl_add_u64 v[100:101], v[6:7], 0, s[20:21]
	v_lshlrev_b32_e32 v100, 16, v96
	v_max_f32_e64 v100, |v100|, |v100|
	v_max_f32_e32 v100, v100, v103
	v_and_b32_e32 v101, 0xffff0000, v95
	v_lshlrev_b32_e32 v103, 16, v95
	v_max_f32_e64 v101, |v101|, |v101|
	v_max_f32_e64 v103, |v103|, |v103|
	v_max_f32_e32 v101, v103, v101
	v_max3_f32 v102, v102, v100, v101
	v_and_b32_e32 v100, 0xffff0000, v98
	v_lshlrev_b32_e32 v101, 16, v98
	v_max_f32_e64 v100, |v100|, |v100|
	v_max_f32_e64 v101, |v101|, |v101|
	v_max_f32_e32 v103, v101, v100
	v_and_b32_e32 v100, 0xffff0000, v97
	s_mul_i32 s20, s0, 0x550
	v_max_f32_e64 v104, |v100|, |v100|
	v_lshl_add_u64 v[100:101], v[6:7], 0, s[20:21]
	v_lshlrev_b32_e32 v100, 16, v97
	v_max_f32_e64 v100, |v100|, |v100|
	s_mul_i32 s20, s0, 0x554
	v_max_f32_e32 v104, v100, v104
	v_lshl_add_u64 v[100:101], v[6:7], 0, s[20:21]
	s_mul_i32 s20, s0, 0x558
	v_lshl_add_u64 v[100:101], v[6:7], 0, s[20:21]
	s_mul_i32 s20, s0, 0x55c
	v_max3_f32 v121, v102, v103, v104
	v_lshl_add_u64 v[102:103], v[6:7], 0, s[20:21]
	s_mul_i32 s20, s0, 0x560
	v_lshl_add_u64 v[100:101], v[6:7], 0, s[20:21]
	s_mul_i32 s20, s0, 0x564
	v_lshl_add_u64 v[102:103], v[6:7], 0, s[20:21]
	s_mul_i32 s20, s0, 0x568
	v_lshl_add_u64 v[104:105], v[6:7], 0, s[20:21]
	s_mul_i32 s20, s0, 0x56c
	v_lshl_add_u64 v[106:107], v[6:7], 0, s[20:21]
	s_mul_i32 s20, s0, 0x570
	v_lshl_add_u64 v[108:109], v[6:7], 0, s[20:21]
	s_mul_i32 s20, s0, 0x574
	v_lshl_add_u64 v[110:111], v[6:7], 0, s[20:21]
	s_mul_i32 s20, s0, 0x578
	v_lshl_add_u64 v[112:113], v[6:7], 0, s[20:21]
	s_mul_i32 s20, s0, 0x57c
	v_lshl_add_u64 v[114:115], v[6:7], 0, s[20:21]
	s_nop 0
	s_nop 0
	s_nop 0
	s_nop 0
	s_nop 0
	v_readlane_b32 s1, v74, 16
	v_readlane_b32 s20, v74, 48
	s_nop 0
	v_mov_b32_e32 v101, s1
	v_mov_b32_e32 v100, s20
	v_cndmask_b32_e32 v100, v100, v101, vcc
	v_readlane_b32 s1, v74, 17
	v_readlane_b32 s20, v74, 49
	s_mov_b32 s101, 0
	s_mul_i32 s100, s0, 0x600
	v_lshl_add_u64 v[154:155], v[6:7], 0, s[100:101]
	global_load_dword v160, v[154:155], off
	s_mul_i32 s100, s0, 0x604
	v_lshl_add_u64 v[154:155], v[6:7], 0, s[100:101]
	global_load_dword v161, v[154:155], off
	s_mul_i32 s100, s0, 0x608
	v_lshl_add_u64 v[154:155], v[6:7], 0, s[100:101]
	global_load_dword v162, v[154:155], off
	s_mul_i32 s100, s0, 0x60c
	v_lshl_add_u64 v[154:155], v[6:7], 0, s[100:101]
	global_load_dword v163, v[154:155], off
	s_mul_i32 s100, s0, 0x610
	v_lshl_add_u64 v[154:155], v[6:7], 0, s[100:101]
	global_load_dword v164, v[154:155], off
	s_mul_i32 s100, s0, 0x614
	v_lshl_add_u64 v[154:155], v[6:7], 0, s[100:101]
	global_load_dword v165, v[154:155], off
	s_mul_i32 s100, s0, 0x618
	v_lshl_add_u64 v[154:155], v[6:7], 0, s[100:101]
	global_load_dword v166, v[154:155], off
	s_mul_i32 s100, s0, 0x61c
	v_lshl_add_u64 v[154:155], v[6:7], 0, s[100:101]
	global_load_dword v167, v[154:155], off
	s_mul_i32 s100, s0, 0x620
	v_lshl_add_u64 v[154:155], v[6:7], 0, s[100:101]
	global_load_dword v168, v[154:155], off
	s_mul_i32 s100, s0, 0x624
	v_lshl_add_u64 v[154:155], v[6:7], 0, s[100:101]
	global_load_dword v169, v[154:155], off
	s_mul_i32 s100, s0, 0x628
	v_lshl_add_u64 v[154:155], v[6:7], 0, s[100:101]
	global_load_dword v170, v[154:155], off
	s_mul_i32 s100, s0, 0x62c
	v_lshl_add_u64 v[154:155], v[6:7], 0, s[100:101]
	global_load_dword v171, v[154:155], off
	s_mul_i32 s100, s0, 0x630
	v_lshl_add_u64 v[154:155], v[6:7], 0, s[100:101]
	global_load_dword v172, v[154:155], off
	s_mul_i32 s100, s0, 0x634
	v_lshl_add_u64 v[154:155], v[6:7], 0, s[100:101]
	global_load_dword v173, v[154:155], off
	s_mul_i32 s100, s0, 0x638
	v_lshl_add_u64 v[154:155], v[6:7], 0, s[100:101]
	global_load_dword v174, v[154:155], off
	s_mul_i32 s100, s0, 0x63c
	v_lshl_add_u64 v[154:155], v[6:7], 0, s[100:101]
	global_load_dword v175, v[154:155], off
	s_waitcnt vmcnt(16) lgkmcnt(0)
	v_mul_f32_e32 v99, v176, v100
	v_mov_b32_e32 v100, s20
	v_mov_b32_e32 v101, s1
	v_readlane_b32 s1, v74, 18
	v_readlane_b32 s20, v74, 50
	v_cndmask_b32_e32 v100, v100, v101, vcc
	v_mov_b32_e32 v102, s1
	v_mov_b32_e32 v101, s20
	v_readlane_b32 s1, v74, 19
	v_readlane_b32 s20, v74, 51
	v_mul_f32_e32 v100, v177, v100
	v_cndmask_b32_e32 v101, v101, v102, vcc
	v_mov_b32_e32 v102, s20
	v_mov_b32_e32 v110, s1
	v_cndmask_b32_e32 v102, v102, v110, vcc
	v_cvt_pk_bf16_f32 v100, v99, v100
	v_mul_f32_e32 v101, v178, v101
	v_and_b32_e32 v99, 0xffff0000, v100
	v_lshlrev_b32_e32 v110, 16, v100
	v_mul_f32_e32 v102, v179, v102
	v_max_f32_e64 v99, |v99|, |v99|
	v_max_f32_e64 v110, |v110|, |v110|
	v_max_f32_e32 v110, v110, v99
	v_cvt_pk_bf16_f32 v99, v101, v102
	v_readlane_b32 s1, v74, 20
	v_and_b32_e32 v101, 0xffff0000, v99
	v_lshlrev_b32_e32 v102, 16, v99
	v_max_f32_e64 v101, |v101|, |v101|
	v_max_f32_e64 v102, |v102|, |v102|
	v_max_f32_e32 v101, v102, v101
	v_readlane_b32 s20, v74, 52
	v_max3_f32 v110, v121, v110, v101
	v_mov_b32_e32 v102, s1
	v_mov_b32_e32 v101, s20
	v_readlane_b32 s1, v74, 21
	v_readlane_b32 s20, v74, 53
	v_cndmask_b32_e32 v101, v101, v102, vcc
	v_mov_b32_e32 v111, s1
	v_mov_b32_e32 v102, s20
	v_readlane_b32 s1, v74, 22
	v_readlane_b32 s20, v74, 54
	v_cndmask_b32_e32 v102, v102, v111, vcc
	v_mov_b32_e32 v112, s1
	v_mov_b32_e32 v111, s20
	v_readlane_b32 s1, v74, 23
	v_readlane_b32 s20, v74, 55
	v_mul_f32_e32 v101, v180, v101
	v_mul_f32_e32 v102, v181, v102
	v_cndmask_b32_e32 v111, v111, v112, vcc
	v_mov_b32_e32 v112, s20
	v_mov_b32_e32 v113, s1
	v_cndmask_b32_e32 v112, v112, v113, vcc
	v_cvt_pk_bf16_f32 v102, v101, v102
	v_mul_f32_e32 v111, v182, v111
	v_and_b32_e32 v101, 0xffff0000, v102
	v_mul_f32_e32 v112, v183, v112
	v_max_f32_e64 v113, |v101|, |v101|
	v_lshlrev_b32_e32 v101, 16, v102
	v_readlane_b32 s1, v74, 24
	v_readlane_b32 s20, v74, 56
	v_max_f32_e64 v114, |v101|, |v101|
	v_cvt_pk_bf16_f32 v101, v111, v112
	v_mov_b32_e32 v112, s1
	v_mov_b32_e32 v111, s20
	v_readlane_b32 s1, v74, 25
	v_readlane_b32 s20, v74, 57
	v_cndmask_b32_e32 v111, v111, v112, vcc
	v_mov_b32_e32 v115, s1
	v_mov_b32_e32 v112, s20
	v_cndmask_b32_e32 v112, v112, v115, vcc
	v_readlane_b32 s1, v74, 26
	v_readlane_b32 s20, v74, 58
	v_mul_f32_e32 v103, v185, v112
	v_mov_b32_e32 v115, s1
	v_mov_b32_e32 v112, s20
	v_cndmask_b32_e32 v112, v112, v115, vcc
	v_readlane_b32 s1, v74, 27
	v_readlane_b32 s20, v74, 59
	v_mul_f32_e32 v112, v186, v112
	v_mov_b32_e32 v115, s1
	v_mov_b32_e32 v104, s20
	v_cndmask_b32_e32 v104, v104, v115, vcc
	v_mul_f32_e32 v111, v184, v111
	v_mul_f32_e32 v105, v187, v104
	v_readlane_b32 s1, v74, 28
	v_readlane_b32 s20, v74, 60
	v_cvt_pk_bf16_f32 v104, v111, v103
	v_cvt_pk_bf16_f32 v103, v112, v105
	s_nop 0
	v_mov_b32_e32 v111, s1
	v_mov_b32_e32 v105, s20
	v_cndmask_b32_e32 v105, v105, v111, vcc
	v_readlane_b32 s1, v74, 29
	v_readlane_b32 s20, v74, 61
	v_mul_f32_e32 v105, v188, v105
	v_mov_b32_e32 v111, s1
	v_mov_b32_e32 v106, s20
	v_cndmask_b32_e32 v106, v106, v111, vcc
	v_readlane_b32 s1, v74, 30
	v_readlane_b32 s20, v74, 62
	v_mul_f32_e32 v106, v189, v106
	v_mov_b32_e32 v111, s1
	v_mov_b32_e32 v107, s20
	v_cndmask_b32_e32 v107, v107, v111, vcc
	v_readlane_b32 s1, v74, 31
	v_readlane_b32 s20, v74, 63
	v_mul_f32_e32 v107, v190, v107
	v_mov_b32_e32 v108, s1
	v_mov_b32_e32 v74, s20
	v_cndmask_b32_e32 v74, v74, v108, vcc
	v_mul_f32_e32 v74, v191, v74
	s_mul_i32 s20, s0, 0x600
	v_cvt_pk_bf16_f32 v105, v105, v106
	v_cvt_pk_bf16_f32 v74, v107, v74
	v_lshl_add_u64 v[106:107], v[6:7], 0, s[20:21]
	v_and_b32_e32 v106, 0xffff0000, v101
	s_mul_i32 s20, s0, 0x604
	v_max_f32_e64 v109, |v106|, |v106|
	v_lshl_add_u64 v[106:107], v[6:7], 0, s[20:21]
	v_lshlrev_b32_e32 v106, 16, v101
	v_max_f32_e64 v106, |v106|, |v106|
	s_mul_i32 s20, s0, 0x608
	v_max_f32_e32 v109, v106, v109
	v_lshl_add_u64 v[106:107], v[6:7], 0, s[20:21]
	v_max_f32_e32 v108, v114, v113
	v_and_b32_e32 v106, 0xffff0000, v104
	s_mul_i32 s20, s0, 0x60c
	v_max3_f32 v108, v110, v108, v109
	v_max_f32_e64 v109, |v106|, |v106|
	v_lshl_add_u64 v[106:107], v[6:7], 0, s[20:21]
	v_lshlrev_b32_e32 v106, 16, v104
	v_max_f32_e64 v106, |v106|, |v106|
	v_max_f32_e32 v106, v106, v109
	v_and_b32_e32 v107, 0xffff0000, v103
	v_lshlrev_b32_e32 v109, 16, v103
	v_max_f32_e64 v107, |v107|, |v107|
	v_max_f32_e64 v109, |v109|, |v109|
	v_max_f32_e32 v107, v109, v107
	v_max3_f32 v108, v108, v106, v107
	v_and_b32_e32 v106, 0xffff0000, v105
	v_lshlrev_b32_e32 v107, 16, v105
	v_max_f32_e64 v106, |v106|, |v106|
	v_max_f32_e64 v107, |v107|, |v107|
	v_max_f32_e32 v109, v107, v106
	v_and_b32_e32 v106, 0xffff0000, v74
	s_mul_i32 s20, s0, 0x610
	v_max_f32_e64 v110, |v106|, |v106|
	v_lshl_add_u64 v[106:107], v[6:7], 0, s[20:21]
	v_lshlrev_b32_e32 v106, 16, v74
	v_max_f32_e64 v106, |v106|, |v106|
	s_mul_i32 s20, s0, 0x614
	v_max_f32_e32 v110, v106, v110
	v_lshl_add_u64 v[106:107], v[6:7], 0, s[20:21]
	s_mul_i32 s20, s0, 0x618
	v_lshl_add_u64 v[106:107], v[6:7], 0, s[20:21]
	s_mul_i32 s20, s0, 0x61c
	v_max3_f32 v128, v108, v109, v110
	v_lshl_add_u64 v[108:109], v[6:7], 0, s[20:21]
	s_mul_i32 s20, s0, 0x620
	v_lshl_add_u64 v[106:107], v[6:7], 0, s[20:21]
	s_mul_i32 s20, s0, 0x624
	v_lshl_add_u64 v[108:109], v[6:7], 0, s[20:21]
	s_mul_i32 s20, s0, 0x628
	v_lshl_add_u64 v[110:111], v[6:7], 0, s[20:21]
	s_mul_i32 s20, s0, 0x62c
	v_lshl_add_u64 v[112:113], v[6:7], 0, s[20:21]
	s_mul_i32 s20, s0, 0x630
	v_lshl_add_u64 v[114:115], v[6:7], 0, s[20:21]
	s_mul_i32 s20, s0, 0x634
	v_lshl_add_u64 v[116:117], v[6:7], 0, s[20:21]
	s_mul_i32 s20, s0, 0x638
	v_lshl_add_u64 v[118:119], v[6:7], 0, s[20:21]
	s_mul_i32 s20, s0, 0x63c
	v_lshl_add_u64 v[120:121], v[6:7], 0, s[20:21]
	s_nop 0
	s_nop 0
	s_nop 0
	s_nop 0
	v_readlane_b32 s1, v5, 0
	v_readlane_b32 s20, v5, 32
	s_nop 0
	v_mov_b32_e32 v107, s1
	v_mov_b32_e32 v106, s20
	v_readlane_b32 s1, v5, 1
	v_readlane_b32 s20, v5, 33
	v_cndmask_b32_e32 v106, v106, v107, vcc
	v_mov_b32_e32 v108, s1
	v_mov_b32_e32 v107, s20
	v_readlane_b32 s1, v5, 2
	v_readlane_b32 s20, v5, 34
	v_cndmask_b32_e32 v107, v107, v108, vcc
	v_mov_b32_e32 v109, s1
	v_mov_b32_e32 v108, s20
	v_readlane_b32 s1, v5, 3
	v_readlane_b32 s20, v5, 35
	s_mov_b32 s101, 0
	s_mul_i32 s100, s0, 0x640
	v_lshl_add_u64 v[154:155], v[6:7], 0, s[100:101]
	global_load_dword v176, v[154:155], off
	s_mul_i32 s100, s0, 0x644
	v_lshl_add_u64 v[154:155], v[6:7], 0, s[100:101]
	global_load_dword v177, v[154:155], off
	s_mul_i32 s100, s0, 0x648
	v_lshl_add_u64 v[154:155], v[6:7], 0, s[100:101]
	global_load_dword v178, v[154:155], off
	s_mul_i32 s100, s0, 0x64c
	v_lshl_add_u64 v[154:155], v[6:7], 0, s[100:101]
	global_load_dword v179, v[154:155], off
	s_mul_i32 s100, s0, 0x650
	v_lshl_add_u64 v[154:155], v[6:7], 0, s[100:101]
	global_load_dword v180, v[154:155], off
	s_mul_i32 s100, s0, 0x654
	v_lshl_add_u64 v[154:155], v[6:7], 0, s[100:101]
	global_load_dword v181, v[154:155], off
	s_mul_i32 s100, s0, 0x658
	v_lshl_add_u64 v[154:155], v[6:7], 0, s[100:101]
	global_load_dword v182, v[154:155], off
	s_mul_i32 s100, s0, 0x65c
	v_lshl_add_u64 v[154:155], v[6:7], 0, s[100:101]
	global_load_dword v183, v[154:155], off
	s_mul_i32 s100, s0, 0x660
	v_lshl_add_u64 v[154:155], v[6:7], 0, s[100:101]
	global_load_dword v184, v[154:155], off
	s_mul_i32 s100, s0, 0x664
	v_lshl_add_u64 v[154:155], v[6:7], 0, s[100:101]
	global_load_dword v185, v[154:155], off
	s_mul_i32 s100, s0, 0x668
	v_lshl_add_u64 v[154:155], v[6:7], 0, s[100:101]
	global_load_dword v186, v[154:155], off
	s_mul_i32 s100, s0, 0x66c
	v_lshl_add_u64 v[154:155], v[6:7], 0, s[100:101]
	global_load_dword v187, v[154:155], off
	s_mul_i32 s100, s0, 0x670
	v_lshl_add_u64 v[154:155], v[6:7], 0, s[100:101]
	global_load_dword v188, v[154:155], off
	s_mul_i32 s100, s0, 0x674
	v_lshl_add_u64 v[154:155], v[6:7], 0, s[100:101]
	global_load_dword v189, v[154:155], off
	s_mul_i32 s100, s0, 0x678
	v_lshl_add_u64 v[154:155], v[6:7], 0, s[100:101]
	global_load_dword v190, v[154:155], off
	s_mul_i32 s100, s0, 0x67c
	v_lshl_add_u64 v[154:155], v[6:7], 0, s[100:101]
	global_load_dword v191, v[154:155], off
	s_waitcnt vmcnt(16) lgkmcnt(0)
	v_mul_f32_e32 v106, v160, v106
	v_mul_f32_e32 v107, v161, v107
	v_cndmask_b32_e32 v108, v108, v109, vcc
	v_mov_b32_e32 v109, s20
	v_mov_b32_e32 v116, s1
	v_cndmask_b32_e32 v109, v109, v116, vcc
	v_cvt_pk_bf16_f32 v107, v106, v107
	v_readlane_b32 s1, v5, 4
	v_and_b32_e32 v106, 0xffff0000, v107
	v_lshlrev_b32_e32 v116, 16, v107
	v_mul_f32_e32 v108, v162, v108
	v_max_f32_e64 v106, |v106|, |v106|
	v_max_f32_e64 v116, |v116|, |v116|
	v_max_f32_e32 v116, v116, v106
	v_mul_f32_e32 v109, v163, v109
	v_cvt_pk_bf16_f32 v106, v108, v109
	v_readlane_b32 s20, v5, 36
	v_and_b32_e32 v108, 0xffff0000, v106
	v_lshlrev_b32_e32 v109, 16, v106
	v_max_f32_e64 v108, |v108|, |v108|
	v_max_f32_e64 v109, |v109|, |v109|
	v_max_f32_e32 v108, v109, v108
	v_max3_f32 v116, v128, v116, v108
	v_mov_b32_e32 v108, s20
	v_mov_b32_e32 v109, s1
	v_readlane_b32 s1, v5, 5
	v_readlane_b32 s20, v5, 37
	v_cndmask_b32_e32 v108, v108, v109, vcc
	v_mov_b32_e32 v117, s1
	v_mov_b32_e32 v109, s20
	v_readlane_b32 s1, v5, 6
	v_readlane_b32 s20, v5, 38
	v_cndmask_b32_e32 v109, v109, v117, vcc
	v_mov_b32_e32 v118, s1
	v_mov_b32_e32 v117, s20
	v_readlane_b32 s1, v5, 7
	v_readlane_b32 s20, v5, 39
	v_mul_f32_e32 v108, v164, v108
	v_cndmask_b32_e32 v117, v117, v118, vcc
	v_mul_f32_e32 v109, v165, v109
	v_mov_b32_e32 v118, s20
	v_mov_b32_e32 v119, s1
	v_cndmask_b32_e32 v118, v118, v119, vcc
	v_cvt_pk_bf16_f32 v109, v108, v109
	v_mul_f32_e32 v117, v166, v117
	v_and_b32_e32 v108, 0xffff0000, v109
	v_mul_f32_e32 v118, v167, v118
	v_max_f32_e64 v119, |v108|, |v108|
	v_lshlrev_b32_e32 v108, 16, v109
	v_readlane_b32 s1, v5, 8
	v_readlane_b32 s20, v5, 40
	v_max_f32_e64 v120, |v108|, |v108|
	v_cvt_pk_bf16_f32 v108, v117, v118
	v_mov_b32_e32 v118, s1
	v_mov_b32_e32 v117, s20
	v_readlane_b32 s1, v5, 9
	v_readlane_b32 s20, v5, 41
	v_cndmask_b32_e32 v117, v117, v118, vcc
	v_mov_b32_e32 v121, s1
	v_mov_b32_e32 v118, s20
	v_readlane_b32 s1, v5, 10
	v_readlane_b32 s20, v5, 42
	v_cndmask_b32_e32 v118, v118, v121, vcc
	v_mov_b32_e32 v122, s1
	v_mov_b32_e32 v121, s20
	v_cndmask_b32_e32 v121, v121, v122, vcc
	v_readlane_b32 s1, v5, 11
	v_readlane_b32 s20, v5, 43
	v_mul_f32_e32 v110, v170, v121
	v_mov_b32_e32 v122, s1
	v_mov_b32_e32 v121, s20
	v_mul_f32_e32 v117, v168, v117
	v_mul_f32_e32 v118, v169, v118
	v_cndmask_b32_e32 v121, v121, v122, vcc
	v_readlane_b32 s1, v5, 12
	v_readlane_b32 s20, v5, 44
	v_mul_f32_e32 v121, v171, v121
	v_cvt_pk_bf16_f32 v111, v117, v118
	v_mov_b32_e32 v118, s1
	v_mov_b32_e32 v117, s20
	v_cndmask_b32_e32 v117, v117, v118, vcc
	v_readlane_b32 s1, v5, 13
	v_readlane_b32 s20, v5, 45
	v_mul_f32_e32 v112, v172, v117
	v_mov_b32_e32 v118, s1
	v_mov_b32_e32 v117, s20
	v_cndmask_b32_e32 v117, v117, v118, vcc
	v_readlane_b32 s1, v5, 14
	v_readlane_b32 s20, v5, 46
	v_mul_f32_e32 v113, v173, v117
	v_mov_b32_e32 v118, s1
	v_mov_b32_e32 v117, s20
	v_cndmask_b32_e32 v117, v117, v118, vcc
	v_readlane_b32 s1, v5, 15
	v_readlane_b32 s20, v5, 47
	v_mul_f32_e32 v114, v174, v117
	v_mov_b32_e32 v118, s1
	v_mov_b32_e32 v117, s20
	v_cndmask_b32_e32 v117, v117, v118, vcc
	v_mul_f32_e32 v115, v175, v117
	s_mul_i32 s20, s0, 0x640
	v_cvt_pk_bf16_f32 v110, v110, v121
	v_cvt_pk_bf16_f32 v113, v112, v113
	v_cvt_pk_bf16_f32 v112, v114, v115
	v_lshl_add_u64 v[114:115], v[6:7], 0, s[20:21]
	v_and_b32_e32 v114, 0xffff0000, v108
	s_mul_i32 s20, s0, 0x644
	v_max_f32_e64 v118, |v114|, |v114|
	v_lshl_add_u64 v[114:115], v[6:7], 0, s[20:21]
	v_lshlrev_b32_e32 v114, 16, v108
	v_max_f32_e64 v114, |v114|, |v114|
	s_mul_i32 s20, s0, 0x648
	v_max_f32_e32 v118, v114, v118
	v_lshl_add_u64 v[114:115], v[6:7], 0, s[20:21]
	v_max_f32_e32 v117, v120, v119
	v_and_b32_e32 v114, 0xffff0000, v111
	s_mul_i32 s20, s0, 0x64c
	v_max3_f32 v116, v116, v117, v118
	v_max_f32_e64 v117, |v114|, |v114|
	v_lshl_add_u64 v[114:115], v[6:7], 0, s[20:21]
	v_lshlrev_b32_e32 v114, 16, v111
	v_max_f32_e64 v114, |v114|, |v114|
	v_max_f32_e32 v114, v114, v117
	v_and_b32_e32 v115, 0xffff0000, v110
	v_lshlrev_b32_e32 v117, 16, v110
	v_max_f32_e64 v115, |v115|, |v115|
	v_max_f32_e64 v117, |v117|, |v117|
	v_max_f32_e32 v115, v117, v115
	v_max3_f32 v116, v116, v114, v115
	v_and_b32_e32 v114, 0xffff0000, v113
	v_lshlrev_b32_e32 v115, 16, v113
	v_max_f32_e64 v114, |v114|, |v114|
	v_max_f32_e64 v115, |v115|, |v115|
	v_max_f32_e32 v117, v115, v114
	v_and_b32_e32 v114, 0xffff0000, v112
	s_mul_i32 s20, s0, 0x650
	v_max_f32_e64 v118, |v114|, |v114|
	v_lshl_add_u64 v[114:115], v[6:7], 0, s[20:21]
	v_lshlrev_b32_e32 v114, 16, v112
	v_max_f32_e64 v114, |v114|, |v114|
	s_mul_i32 s20, s0, 0x654
	v_max_f32_e32 v118, v114, v118
	v_lshl_add_u64 v[114:115], v[6:7], 0, s[20:21]
	s_mul_i32 s20, s0, 0x658
	v_lshl_add_u64 v[114:115], v[6:7], 0, s[20:21]
	s_mul_i32 s20, s0, 0x65c
	v_max3_f32 v136, v116, v117, v118
	v_lshl_add_u64 v[116:117], v[6:7], 0, s[20:21]
	s_mul_i32 s20, s0, 0x660
	v_lshl_add_u64 v[114:115], v[6:7], 0, s[20:21]
	s_mul_i32 s20, s0, 0x664
	v_lshl_add_u64 v[116:117], v[6:7], 0, s[20:21]
	s_mul_i32 s20, s0, 0x668
	v_lshl_add_u64 v[118:119], v[6:7], 0, s[20:21]
	s_mul_i32 s20, s0, 0x66c
	v_lshl_add_u64 v[120:121], v[6:7], 0, s[20:21]
	s_mul_i32 s20, s0, 0x670
	v_lshl_add_u64 v[122:123], v[6:7], 0, s[20:21]
	s_mul_i32 s20, s0, 0x674
	v_lshl_add_u64 v[124:125], v[6:7], 0, s[20:21]
	s_mul_i32 s20, s0, 0x678
	v_lshl_add_u64 v[126:127], v[6:7], 0, s[20:21]
	s_mul_i32 s20, s0, 0x67c
	v_lshl_add_u64 v[128:129], v[6:7], 0, s[20:21]
	s_nop 0
	s_nop 0
	s_nop 0
	s_nop 0
	v_readlane_b32 s1, v5, 16
	v_readlane_b32 s20, v5, 48
	s_nop 0
	v_mov_b32_e32 v115, s1
	v_mov_b32_e32 v114, s20
	v_readlane_b32 s1, v5, 17
	v_readlane_b32 s20, v5, 49
	v_cndmask_b32_e32 v114, v114, v115, vcc
	v_mov_b32_e32 v116, s1
	v_mov_b32_e32 v115, s20
	v_readlane_b32 s1, v5, 18
	v_readlane_b32 s20, v5, 50
	v_cndmask_b32_e32 v115, v115, v116, vcc
	v_mov_b32_e32 v117, s1
	v_mov_b32_e32 v116, s20
	v_readlane_b32 s1, v5, 19
	v_readlane_b32 s20, v5, 51
	s_mov_b32 s101, 0
	s_mul_i32 s100, s0, 0x700
	v_lshl_add_u64 v[154:155], v[6:7], 0, s[100:101]
	global_load_dword v160, v[154:155], off
	s_mul_i32 s100, s0, 0x704
	v_lshl_add_u64 v[154:155], v[6:7], 0, s[100:101]
	global_load_dword v161, v[154:155], off
	s_mul_i32 s100, s0, 0x708
	v_lshl_add_u64 v[154:155], v[6:7], 0, s[100:101]
	global_load_dword v162, v[154:155], off
	s_mul_i32 s100, s0, 0x70c
	v_lshl_add_u64 v[154:155], v[6:7], 0, s[100:101]
	global_load_dword v163, v[154:155], off
	s_mul_i32 s100, s0, 0x710
	v_lshl_add_u64 v[154:155], v[6:7], 0, s[100:101]
	global_load_dword v164, v[154:155], off
	s_mul_i32 s100, s0, 0x714
	v_lshl_add_u64 v[154:155], v[6:7], 0, s[100:101]
	global_load_dword v165, v[154:155], off
	s_mul_i32 s100, s0, 0x718
	v_lshl_add_u64 v[154:155], v[6:7], 0, s[100:101]
	global_load_dword v166, v[154:155], off
	s_mul_i32 s100, s0, 0x71c
	v_lshl_add_u64 v[154:155], v[6:7], 0, s[100:101]
	global_load_dword v167, v[154:155], off
	s_mul_i32 s100, s0, 0x720
	v_lshl_add_u64 v[154:155], v[6:7], 0, s[100:101]
	global_load_dword v168, v[154:155], off
	s_mul_i32 s100, s0, 0x724
	v_lshl_add_u64 v[154:155], v[6:7], 0, s[100:101]
	global_load_dword v169, v[154:155], off
	s_mul_i32 s100, s0, 0x728
	v_lshl_add_u64 v[154:155], v[6:7], 0, s[100:101]
	global_load_dword v170, v[154:155], off
	s_mul_i32 s100, s0, 0x72c
	v_lshl_add_u64 v[154:155], v[6:7], 0, s[100:101]
	global_load_dword v171, v[154:155], off
	s_mul_i32 s100, s0, 0x730
	v_lshl_add_u64 v[154:155], v[6:7], 0, s[100:101]
	global_load_dword v172, v[154:155], off
	s_mul_i32 s100, s0, 0x734
	v_lshl_add_u64 v[154:155], v[6:7], 0, s[100:101]
	global_load_dword v173, v[154:155], off
	s_mul_i32 s100, s0, 0x738
	v_lshl_add_u64 v[154:155], v[6:7], 0, s[100:101]
	global_load_dword v174, v[154:155], off
	s_mul_i32 s100, s0, 0x73c
	v_lshl_add_u64 v[154:155], v[6:7], 0, s[100:101]
	global_load_dword v175, v[154:155], off
	s_waitcnt vmcnt(16) lgkmcnt(0)
	v_mul_f32_e32 v114, v176, v114
	v_mul_f32_e32 v115, v177, v115
	v_cndmask_b32_e32 v116, v116, v117, vcc
	v_mov_b32_e32 v117, s20
	v_mov_b32_e32 v124, s1
	v_cndmask_b32_e32 v117, v117, v124, vcc
	v_cvt_pk_bf16_f32 v115, v114, v115
	v_readlane_b32 s1, v5, 20
	v_and_b32_e32 v114, 0xffff0000, v115
	v_lshlrev_b32_e32 v124, 16, v115
	v_mul_f32_e32 v116, v178, v116
	v_max_f32_e64 v114, |v114|, |v114|
	v_max_f32_e64 v124, |v124|, |v124|
	v_max_f32_e32 v124, v124, v114
	v_mul_f32_e32 v117, v179, v117
	v_cvt_pk_bf16_f32 v114, v116, v117
	v_readlane_b32 s20, v5, 52
	v_and_b32_e32 v116, 0xffff0000, v114
	v_lshlrev_b32_e32 v117, 16, v114
	v_max_f32_e64 v116, |v116|, |v116|
	v_max_f32_e64 v117, |v117|, |v117|
	v_max_f32_e32 v116, v117, v116
	v_max3_f32 v124, v136, v124, v116
	v_mov_b32_e32 v116, s20
	v_mov_b32_e32 v117, s1
	v_readlane_b32 s1, v5, 21
	v_readlane_b32 s20, v5, 53
	v_cndmask_b32_e32 v116, v116, v117, vcc
	v_mov_b32_e32 v125, s1
	v_mov_b32_e32 v117, s20
	v_readlane_b32 s1, v5, 22
	v_readlane_b32 s20, v5, 54
	v_cndmask_b32_e32 v117, v117, v125, vcc
	v_mov_b32_e32 v126, s1
	v_mov_b32_e32 v125, s20
	v_readlane_b32 s1, v5, 23
	v_readlane_b32 s20, v5, 55
	v_mul_f32_e32 v116, v180, v116
	v_cndmask_b32_e32 v125, v125, v126, vcc
	v_mul_f32_e32 v117, v181, v117
	v_mov_b32_e32 v126, s20
	v_mov_b32_e32 v127, s1
	v_cndmask_b32_e32 v126, v126, v127, vcc
	v_cvt_pk_bf16_f32 v117, v116, v117
	v_mul_f32_e32 v125, v182, v125
	v_and_b32_e32 v116, 0xffff0000, v117
	v_mul_f32_e32 v126, v183, v126
	v_max_f32_e64 v127, |v116|, |v116|
	v_lshlrev_b32_e32 v116, 16, v117
	v_readlane_b32 s1, v5, 24
	v_readlane_b32 s20, v5, 56
	v_max_f32_e64 v128, |v116|, |v116|
	v_cvt_pk_bf16_f32 v116, v125, v126
	v_mov_b32_e32 v126, s1
	v_mov_b32_e32 v125, s20
	v_readlane_b32 s1, v5, 25
	v_readlane_b32 s20, v5, 57
	v_cndmask_b32_e32 v125, v125, v126, vcc
	v_mov_b32_e32 v129, s1
	v_mov_b32_e32 v126, s20
	v_readlane_b32 s1, v5, 26
	v_readlane_b32 s20, v5, 58
	v_cndmask_b32_e32 v126, v126, v129, vcc
	v_mov_b32_e32 v130, s1
	v_mov_b32_e32 v129, s20
	v_cndmask_b32_e32 v129, v129, v130, vcc
	v_readlane_b32 s1, v5, 27
	v_readlane_b32 s20, v5, 59
	v_mul_f32_e32 v118, v186, v129
	v_mov_b32_e32 v130, s1
	v_mov_b32_e32 v129, s20
	v_mul_f32_e32 v125, v184, v125
	v_mul_f32_e32 v126, v185, v126
	v_cndmask_b32_e32 v129, v129, v130, vcc
	v_readlane_b32 s1, v5, 28
	v_readlane_b32 s20, v5, 60
	v_mul_f32_e32 v129, v187, v129
	v_cvt_pk_bf16_f32 v119, v125, v126
	v_mov_b32_e32 v126, s1
	v_mov_b32_e32 v125, s20
	v_cndmask_b32_e32 v125, v125, v126, vcc
	v_readlane_b32 s1, v5, 29
	v_readlane_b32 s20, v5, 61
	v_mul_f32_e32 v120, v188, v125
	v_mov_b32_e32 v126, s1
	v_mov_b32_e32 v125, s20
	v_cndmask_b32_e32 v125, v125, v126, vcc
	v_readlane_b32 s1, v5, 30
	v_readlane_b32 s20, v5, 62
	v_mul_f32_e32 v121, v189, v125
	v_mov_b32_e32 v126, s1
	v_mov_b32_e32 v125, s20
	v_cndmask_b32_e32 v125, v125, v126, vcc
	v_readlane_b32 s1, v5, 31
	v_readlane_b32 s20, v5, 63
	v_mul_f32_e32 v122, v190, v125
	v_mov_b32_e32 v125, s1
	v_mov_b32_e32 v5, s20
	v_cndmask_b32_e32 v5, v5, v125, vcc
	s_mul_i32 s20, s0, 0x700
	v_cvt_pk_bf16_f32 v118, v118, v129
	v_mul_f32_e32 v5, v191, v5
	v_cvt_pk_bf16_f32 v121, v120, v121
	v_cvt_pk_bf16_f32 v120, v122, v5
	v_lshl_add_u64 v[122:123], v[6:7], 0, s[20:21]
	v_and_b32_e32 v122, 0xffff0000, v116
	s_mul_i32 s20, s0, 0x704
	v_max_f32_e64 v126, |v122|, |v122|
	v_lshl_add_u64 v[122:123], v[6:7], 0, s[20:21]
	v_lshlrev_b32_e32 v122, 16, v116
	v_max_f32_e64 v122, |v122|, |v122|
	s_mul_i32 s20, s0, 0x708
	v_max_f32_e32 v126, v122, v126
	v_lshl_add_u64 v[122:123], v[6:7], 0, s[20:21]
	v_max_f32_e32 v125, v128, v127
	v_and_b32_e32 v122, 0xffff0000, v119
	s_mul_i32 s20, s0, 0x70c
	v_max3_f32 v124, v124, v125, v126
	v_max_f32_e64 v125, |v122|, |v122|
	v_lshl_add_u64 v[122:123], v[6:7], 0, s[20:21]
	v_lshlrev_b32_e32 v122, 16, v119
	v_max_f32_e64 v122, |v122|, |v122|
	v_max_f32_e32 v122, v122, v125
	v_and_b32_e32 v123, 0xffff0000, v118
	v_lshlrev_b32_e32 v125, 16, v118
	v_max_f32_e64 v123, |v123|, |v123|
	v_max_f32_e64 v125, |v125|, |v125|
	v_max_f32_e32 v123, v125, v123
	v_max3_f32 v124, v124, v122, v123
	v_and_b32_e32 v122, 0xffff0000, v121
	v_lshlrev_b32_e32 v123, 16, v121
	v_max_f32_e64 v122, |v122|, |v122|
	v_max_f32_e64 v123, |v123|, |v123|
	v_max_f32_e32 v125, v123, v122
	v_and_b32_e32 v122, 0xffff0000, v120
	s_mul_i32 s20, s0, 0x710
	v_max_f32_e64 v126, |v122|, |v122|
	v_lshl_add_u64 v[122:123], v[6:7], 0, s[20:21]
	v_lshlrev_b32_e32 v122, 16, v120
	v_max_f32_e64 v122, |v122|, |v122|
	s_mul_i32 s20, s0, 0x714
	v_max_f32_e32 v126, v122, v126
	v_lshl_add_u64 v[122:123], v[6:7], 0, s[20:21]
	s_mul_i32 s20, s0, 0x718
	v_lshl_add_u64 v[122:123], v[6:7], 0, s[20:21]
	s_mul_i32 s20, s0, 0x71c
	v_max3_f32 v143, v124, v125, v126
	v_lshl_add_u64 v[124:125], v[6:7], 0, s[20:21]
	s_mul_i32 s20, s0, 0x720
	v_lshl_add_u64 v[122:123], v[6:7], 0, s[20:21]
	s_mul_i32 s20, s0, 0x724
	v_lshl_add_u64 v[124:125], v[6:7], 0, s[20:21]
	s_mul_i32 s20, s0, 0x728
	v_lshl_add_u64 v[126:127], v[6:7], 0, s[20:21]
	s_mul_i32 s20, s0, 0x72c
	v_lshl_add_u64 v[128:129], v[6:7], 0, s[20:21]
	s_mul_i32 s20, s0, 0x730
	v_lshl_add_u64 v[130:131], v[6:7], 0, s[20:21]
	s_mul_i32 s20, s0, 0x734
	v_lshl_add_u64 v[132:133], v[6:7], 0, s[20:21]
	s_mul_i32 s20, s0, 0x738
	v_lshl_add_u64 v[134:135], v[6:7], 0, s[20:21]
	s_mul_i32 s20, s0, 0x73c
	v_lshl_add_u64 v[136:137], v[6:7], 0, s[20:21]
	s_nop 0
	s_nop 0
	s_nop 0
	s_nop 0
	v_readlane_b32 s1, v0, 0
	v_readlane_b32 s20, v0, 32
	s_nop 0
	v_mov_b32_e32 v123, s1
	v_mov_b32_e32 v122, s20
	v_cndmask_b32_e32 v122, v122, v123, vcc
	v_readlane_b32 s1, v0, 1
	v_readlane_b32 s20, v0, 33
	s_mov_b32 s101, 0
	s_mul_i32 s100, s0, 0x740
	v_lshl_add_u64 v[154:155], v[6:7], 0, s[100:101]
	global_load_dword v176, v[154:155], off
	s_mul_i32 s100, s0, 0x744
	v_lshl_add_u64 v[154:155], v[6:7], 0, s[100:101]
	global_load_dword v177, v[154:155], off
	s_mul_i32 s100, s0, 0x748
	v_lshl_add_u64 v[154:155], v[6:7], 0, s[100:101]
	global_load_dword v178, v[154:155], off
	s_mul_i32 s100, s0, 0x74c
	v_lshl_add_u64 v[154:155], v[6:7], 0, s[100:101]
	global_load_dword v179, v[154:155], off
	s_mul_i32 s100, s0, 0x750
	v_lshl_add_u64 v[154:155], v[6:7], 0, s[100:101]
	global_load_dword v180, v[154:155], off
	s_mul_i32 s100, s0, 0x754
	v_lshl_add_u64 v[154:155], v[6:7], 0, s[100:101]
	global_load_dword v181, v[154:155], off
	s_mul_i32 s100, s0, 0x758
	v_lshl_add_u64 v[154:155], v[6:7], 0, s[100:101]
	global_load_dword v182, v[154:155], off
	s_mul_i32 s100, s0, 0x75c
	v_lshl_add_u64 v[154:155], v[6:7], 0, s[100:101]
	global_load_dword v183, v[154:155], off
	s_mul_i32 s100, s0, 0x760
	v_lshl_add_u64 v[154:155], v[6:7], 0, s[100:101]
	global_load_dword v184, v[154:155], off
	s_mul_i32 s100, s0, 0x764
	v_lshl_add_u64 v[154:155], v[6:7], 0, s[100:101]
	global_load_dword v185, v[154:155], off
	s_mul_i32 s100, s0, 0x768
	v_lshl_add_u64 v[154:155], v[6:7], 0, s[100:101]
	global_load_dword v186, v[154:155], off
	s_mul_i32 s100, s0, 0x76c
	v_lshl_add_u64 v[154:155], v[6:7], 0, s[100:101]
	global_load_dword v187, v[154:155], off
	s_mul_i32 s100, s0, 0x770
	v_lshl_add_u64 v[154:155], v[6:7], 0, s[100:101]
	global_load_dword v188, v[154:155], off
	s_mul_i32 s100, s0, 0x774
	v_lshl_add_u64 v[154:155], v[6:7], 0, s[100:101]
	global_load_dword v189, v[154:155], off
	s_mul_i32 s100, s0, 0x778
	v_lshl_add_u64 v[154:155], v[6:7], 0, s[100:101]
	global_load_dword v190, v[154:155], off
	s_mul_i32 s100, s0, 0x77c
	v_lshl_add_u64 v[154:155], v[6:7], 0, s[100:101]
	global_load_dword v191, v[154:155], off
	s_waitcnt vmcnt(16) lgkmcnt(0)
	v_mul_f32_e32 v5, v160, v122
	v_mov_b32_e32 v122, s20
	v_mov_b32_e32 v123, s1
	v_readlane_b32 s1, v0, 2
	v_readlane_b32 s20, v0, 34
	v_cndmask_b32_e32 v122, v122, v123, vcc
	v_mov_b32_e32 v124, s1
	v_mov_b32_e32 v123, s20
	v_cndmask_b32_e32 v123, v123, v124, vcc
	v_readlane_b32 s1, v0, 3
	v_readlane_b32 s20, v0, 35
	v_mul_f32_e32 v122, v161, v122
	v_mul_f32_e32 v124, v162, v123
	v_mov_b32_e32 v123, s20
	v_mov_b32_e32 v125, s1
	v_cndmask_b32_e32 v123, v123, v125, vcc
	v_readlane_b32 s1, v0, 4
	v_readlane_b32 s20, v0, 36
	v_mul_f32_e32 v125, v163, v123
	v_cvt_pk_bf16_f32 v123, v5, v122
	s_nop 0
	v_and_b32_e32 v5, 0xffff0000, v123
	v_lshlrev_b32_e32 v122, 16, v123
	v_max_f32_e64 v5, |v5|, |v5|
	v_max_f32_e64 v122, |v122|, |v122|
	v_max_f32_e32 v5, v122, v5
	v_cvt_pk_bf16_f32 v122, v124, v125
	s_nop 0
	v_and_b32_e32 v124, 0xffff0000, v122
	v_lshlrev_b32_e32 v125, 16, v122
	v_max_f32_e64 v124, |v124|, |v124|
	v_max_f32_e64 v125, |v125|, |v125|
	v_max_f32_e32 v124, v125, v124
	v_max3_f32 v5, v143, v5, v124
	v_mov_b32_e32 v124, s20
	v_mov_b32_e32 v125, s1
	v_readlane_b32 s1, v0, 5
	v_readlane_b32 s20, v0, 37
	v_cndmask_b32_e32 v124, v124, v125, vcc
	v_mov_b32_e32 v132, s1
	v_mov_b32_e32 v125, s20
	v_readlane_b32 s1, v0, 6
	v_readlane_b32 s20, v0, 38
	v_cndmask_b32_e32 v125, v125, v132, vcc
	v_mov_b32_e32 v133, s1
	v_mov_b32_e32 v132, s20
	v_readlane_b32 s1, v0, 7
	v_readlane_b32 s20, v0, 39
	v_mul_f32_e32 v124, v164, v124
	v_mul_f32_e32 v125, v165, v125
	v_cndmask_b32_e32 v132, v132, v133, vcc
	v_mov_b32_e32 v133, s20
	v_mov_b32_e32 v134, s1
	v_cndmask_b32_e32 v133, v133, v134, vcc
	v_cvt_pk_bf16_f32 v125, v124, v125
	v_mul_f32_e32 v132, v166, v132
	v_and_b32_e32 v124, 0xffff0000, v125
	v_mul_f32_e32 v133, v167, v133
	v_max_f32_e64 v134, |v124|, |v124|
	v_lshlrev_b32_e32 v124, 16, v125
	v_readlane_b32 s1, v0, 8
	v_readlane_b32 s20, v0, 40
	v_max_f32_e64 v135, |v124|, |v124|
	v_cvt_pk_bf16_f32 v124, v132, v133
	v_mov_b32_e32 v133, s1
	v_mov_b32_e32 v132, s20
	v_readlane_b32 s1, v0, 9
	v_readlane_b32 s20, v0, 41
	v_cndmask_b32_e32 v132, v132, v133, vcc
	v_mov_b32_e32 v136, s1
	v_mov_b32_e32 v133, s20
	v_readlane_b32 s1, v0, 10
	v_readlane_b32 s20, v0, 42
	v_cndmask_b32_e32 v133, v133, v136, vcc
	v_mov_b32_e32 v137, s1
	v_mov_b32_e32 v136, s20
	v_cndmask_b32_e32 v136, v136, v137, vcc
	v_readlane_b32 s1, v0, 11
	v_readlane_b32 s20, v0, 43
	v_mul_f32_e32 v126, v170, v136
	v_mov_b32_e32 v137, s1
	v_mov_b32_e32 v136, s20
	v_mul_f32_e32 v132, v168, v132
	v_mul_f32_e32 v133, v169, v133
	v_cndmask_b32_e32 v136, v136, v137, vcc
	v_readlane_b32 s1, v0, 12
	v_readlane_b32 s20, v0, 44
	v_mul_f32_e32 v136, v171, v136
	v_cvt_pk_bf16_f32 v127, v132, v133
	v_mov_b32_e32 v133, s1
	v_mov_b32_e32 v132, s20
	v_cndmask_b32_e32 v132, v132, v133, vcc
	v_readlane_b32 s1, v0, 13
	v_readlane_b32 s20, v0, 45
	v_mul_f32_e32 v128, v172, v132
	v_mov_b32_e32 v133, s1
	v_mov_b32_e32 v132, s20
	v_cndmask_b32_e32 v132, v132, v133, vcc
	v_readlane_b32 s1, v0, 14
	v_readlane_b32 s20, v0, 46
	v_mul_f32_e32 v129, v173, v132
	v_mov_b32_e32 v133, s1
	v_mov_b32_e32 v132, s20
	v_cndmask_b32_e32 v132, v132, v133, vcc
	v_readlane_b32 s1, v0, 15
	v_readlane_b32 s20, v0, 47
	v_mul_f32_e32 v130, v174, v132
	v_mov_b32_e32 v133, s1
	v_mov_b32_e32 v132, s20
	v_cndmask_b32_e32 v132, v132, v133, vcc
	v_mul_f32_e32 v131, v175, v132
	s_mul_i32 s20, s0, 0x740
	v_cvt_pk_bf16_f32 v126, v126, v136
	v_cvt_pk_bf16_f32 v129, v128, v129
	v_cvt_pk_bf16_f32 v128, v130, v131
	v_lshl_add_u64 v[130:131], v[6:7], 0, s[20:21]
	v_and_b32_e32 v130, 0xffff0000, v124
	s_mul_i32 s20, s0, 0x744
	v_max_f32_e64 v133, |v130|, |v130|
	v_lshl_add_u64 v[130:131], v[6:7], 0, s[20:21]
	v_lshlrev_b32_e32 v130, 16, v124
	v_max_f32_e64 v130, |v130|, |v130|
	s_mul_i32 s20, s0, 0x748
	v_max_f32_e32 v133, v130, v133
	v_lshl_add_u64 v[130:131], v[6:7], 0, s[20:21]
	v_max_f32_e32 v132, v135, v134
	v_and_b32_e32 v130, 0xffff0000, v127
	s_mul_i32 s20, s0, 0x74c
	v_max3_f32 v5, v5, v132, v133
	v_max_f32_e64 v132, |v130|, |v130|
	v_lshl_add_u64 v[130:131], v[6:7], 0, s[20:21]
	v_lshlrev_b32_e32 v130, 16, v127
	v_max_f32_e64 v130, |v130|, |v130|
	v_max_f32_e32 v130, v130, v132
	v_and_b32_e32 v131, 0xffff0000, v126
	v_lshlrev_b32_e32 v132, 16, v126
	v_max_f32_e64 v131, |v131|, |v131|
	v_max_f32_e64 v132, |v132|, |v132|
	v_max_f32_e32 v131, v132, v131
	v_max3_f32 v5, v5, v130, v131
	v_and_b32_e32 v130, 0xffff0000, v129
	v_lshlrev_b32_e32 v131, 16, v129
	v_max_f32_e64 v130, |v130|, |v130|
	v_max_f32_e64 v131, |v131|, |v131|
	v_max_f32_e32 v132, v131, v130
	v_and_b32_e32 v130, 0xffff0000, v128
	s_mul_i32 s20, s0, 0x750
	v_max_f32_e64 v133, |v130|, |v130|
	v_lshl_add_u64 v[130:131], v[6:7], 0, s[20:21]
	v_lshlrev_b32_e32 v130, 16, v128
	v_max_f32_e64 v130, |v130|, |v130|
	s_mul_i32 s20, s0, 0x754
	v_max_f32_e32 v133, v130, v133
	v_lshl_add_u64 v[130:131], v[6:7], 0, s[20:21]
	s_mul_i32 s20, s0, 0x758
	v_lshl_add_u64 v[130:131], v[6:7], 0, s[20:21]
	s_mul_i32 s20, s0, 0x75c
	v_max3_f32 v5, v5, v132, v133
	v_lshl_add_u64 v[132:133], v[6:7], 0, s[20:21]
	s_mul_i32 s20, s0, 0x760
	v_lshl_add_u64 v[130:131], v[6:7], 0, s[20:21]
	s_mul_i32 s20, s0, 0x764
	v_lshl_add_u64 v[132:133], v[6:7], 0, s[20:21]
	s_mul_i32 s20, s0, 0x768
	v_lshl_add_u64 v[134:135], v[6:7], 0, s[20:21]
	s_mul_i32 s20, s0, 0x76c
	v_lshl_add_u64 v[136:137], v[6:7], 0, s[20:21]
	s_mul_i32 s20, s0, 0x770
	v_lshl_add_u64 v[138:139], v[6:7], 0, s[20:21]
	s_mul_i32 s20, s0, 0x774
	v_lshl_add_u64 v[140:141], v[6:7], 0, s[20:21]
	s_mul_i32 s20, s0, 0x778
	v_lshl_add_u64 v[142:143], v[6:7], 0, s[20:21]
	s_mul_i32 s20, s0, 0x77c
	v_lshl_add_u64 v[6:7], v[6:7], 0, s[20:21]
	s_nop 0
	s_nop 0
	s_nop 0
	s_nop 0
	v_readlane_b32 s0, v0, 16
	v_readlane_b32 s1, v0, 48
	s_nop 0
	v_mov_b32_e32 v7, s0
	v_mov_b32_e32 v6, s1
	v_readlane_b32 s0, v0, 17
	v_readlane_b32 s1, v0, 49
	v_cndmask_b32_e32 v6, v6, v7, vcc
	v_mov_b32_e32 v130, s0
	v_mov_b32_e32 v7, s1
	v_readlane_b32 s0, v0, 18
	v_readlane_b32 s1, v0, 50
	v_cndmask_b32_e32 v7, v7, v130, vcc
	v_mov_b32_e32 v131, s0
	v_mov_b32_e32 v130, s1
	v_readlane_b32 s0, v0, 19
	v_readlane_b32 s1, v0, 51
	s_waitcnt vmcnt(0) lgkmcnt(0)
	v_mul_f32_e32 v6, v176, v6
	v_mul_f32_e32 v7, v177, v7
	v_cndmask_b32_e32 v130, v130, v131, vcc
	v_mov_b32_e32 v131, s1
	v_mov_b32_e32 v139, s0
	v_cndmask_b32_e32 v131, v131, v139, vcc
	v_cvt_pk_bf16_f32 v7, v6, v7
	v_readlane_b32 s0, v0, 20
	v_and_b32_e32 v6, 0xffff0000, v7
	v_lshlrev_b32_e32 v139, 16, v7
	v_mul_f32_e32 v130, v178, v130
	v_max_f32_e64 v6, |v6|, |v6|
	v_max_f32_e64 v139, |v139|, |v139|
	v_max_f32_e32 v139, v139, v6
	v_mul_f32_e32 v131, v179, v131
	v_cvt_pk_bf16_f32 v6, v130, v131
	v_readlane_b32 s1, v0, 52
	v_and_b32_e32 v130, 0xffff0000, v6
	v_lshlrev_b32_e32 v131, 16, v6
	v_max_f32_e64 v130, |v130|, |v130|
	v_max_f32_e64 v131, |v131|, |v131|
	v_max_f32_e32 v130, v131, v130
	v_max3_f32 v5, v5, v139, v130
	v_mov_b32_e32 v130, s1
	v_mov_b32_e32 v131, s0
	v_readlane_b32 s0, v0, 21
	v_readlane_b32 s1, v0, 53
	v_cndmask_b32_e32 v130, v130, v131, vcc
	v_mov_b32_e32 v139, s0
	v_mov_b32_e32 v131, s1
	v_readlane_b32 s0, v0, 22
	v_readlane_b32 s1, v0, 54
	v_cndmask_b32_e32 v131, v131, v139, vcc
	v_mov_b32_e32 v140, s0
	v_mov_b32_e32 v139, s1
	v_readlane_b32 s0, v0, 23
	v_readlane_b32 s1, v0, 55
	v_mul_f32_e32 v130, v180, v130
	v_cndmask_b32_e32 v139, v139, v140, vcc
	v_mul_f32_e32 v131, v181, v131
	v_mov_b32_e32 v140, s1
	v_mov_b32_e32 v141, s0
	v_cndmask_b32_e32 v140, v140, v141, vcc
	v_cvt_pk_bf16_f32 v131, v130, v131
	v_mul_f32_e32 v139, v182, v139
	v_and_b32_e32 v130, 0xffff0000, v131
	v_lshlrev_b32_e32 v141, 16, v131
	v_mul_f32_e32 v140, v183, v140
	v_max_f32_e64 v130, |v130|, |v130|
	v_max_f32_e64 v141, |v141|, |v141|
	v_max_f32_e32 v141, v141, v130
	v_cvt_pk_bf16_f32 v130, v139, v140
	v_readlane_b32 s0, v0, 24
	v_and_b32_e32 v139, 0xffff0000, v130
	v_lshlrev_b32_e32 v140, 16, v130
	v_max_f32_e64 v139, |v139|, |v139|
	v_max_f32_e64 v140, |v140|, |v140|
	v_max_f32_e32 v139, v140, v139
	v_readlane_b32 s1, v0, 56
	v_max3_f32 v5, v5, v141, v139
	v_mov_b32_e32 v140, s0
	v_mov_b32_e32 v139, s1
	v_readlane_b32 s0, v0, 25
	v_readlane_b32 s1, v0, 57
	v_cndmask_b32_e32 v139, v139, v140, vcc
	v_mov_b32_e32 v141, s0
	v_mov_b32_e32 v140, s1
	v_cndmask_b32_e32 v140, v140, v141, vcc
	v_readlane_b32 s0, v0, 26
	v_readlane_b32 s1, v0, 58
	v_mul_f32_e32 v132, v185, v140
	v_mov_b32_e32 v141, s0
	v_mov_b32_e32 v140, s1
	v_cndmask_b32_e32 v140, v140, v141, vcc
	v_readlane_b32 s0, v0, 27
	v_readlane_b32 s1, v0, 59
	v_mul_f32_e32 v140, v186, v140
	v_mov_b32_e32 v141, s0
	v_mov_b32_e32 v133, s1
	v_mul_f32_e32 v139, v184, v139
	v_cndmask_b32_e32 v133, v133, v141, vcc
	v_mul_f32_e32 v134, v187, v133
	v_cvt_pk_bf16_f32 v133, v139, v132
	v_readlane_b32 s0, v0, 28
	v_and_b32_e32 v132, 0xffff0000, v133
	v_lshlrev_b32_e32 v139, 16, v133
	v_max_f32_e64 v132, |v132|, |v132|
	v_max_f32_e64 v139, |v139|, |v139|
	v_max_f32_e32 v139, v139, v132
	v_cvt_pk_bf16_f32 v132, v140, v134
	v_readlane_b32 s1, v0, 60
	v_and_b32_e32 v134, 0xffff0000, v132
	v_lshlrev_b32_e32 v140, 16, v132
	v_max_f32_e64 v134, |v134|, |v134|
	v_max_f32_e64 v140, |v140|, |v140|
	v_max_f32_e32 v134, v140, v134
	v_max3_f32 v5, v5, v139, v134
	v_mov_b32_e32 v134, s1
	v_mov_b32_e32 v139, s0
	v_cndmask_b32_e32 v134, v134, v139, vcc
	v_readlane_b32 s0, v0, 29
	v_readlane_b32 s1, v0, 61
	v_mul_f32_e32 v134, v188, v134
	v_mov_b32_e32 v139, s0
	v_mov_b32_e32 v135, s1
	v_cndmask_b32_e32 v135, v135, v139, vcc
	v_readlane_b32 s0, v0, 30
	v_readlane_b32 s1, v0, 62
	v_mul_f32_e32 v135, v189, v135
	v_mov_b32_e32 v139, s0
	v_mov_b32_e32 v136, s1
	v_cndmask_b32_e32 v136, v136, v139, vcc
	v_readlane_b32 s0, v0, 31
	v_readlane_b32 s1, v0, 63
	v_mul_f32_e32 v136, v190, v136
	v_mov_b32_e32 v137, s0
	v_mov_b32_e32 v0, s1
	v_cndmask_b32_e32 v0, v0, v137, vcc
	v_cvt_pk_bf16_f32 v135, v134, v135
	v_mul_f32_e32 v0, v191, v0
	v_and_b32_e32 v134, 0xffff0000, v135
	v_lshlrev_b32_e32 v137, 16, v135
	v_max_f32_e64 v134, |v134|, |v134|
	v_max_f32_e64 v137, |v137|, |v137|
	v_max_f32_e32 v137, v137, v134
	v_cvt_pk_bf16_f32 v134, v136, v0
	v_cmp_gt_i32_e32 vcc, 32, v2
	v_and_b32_e32 v0, 0xffff0000, v134
	v_lshlrev_b32_e32 v136, 16, v134
	v_max_f32_e64 v0, |v0|, |v0|
	v_max_f32_e64 v136, |v136|, |v136|
	v_max_f32_e32 v0, v136, v0
	v_max3_f32 v0, v5, v137, v0
	v_mov_b32_e32 v5, v0
	s_nop 1
	v_permlane32_swap_b32_e32 v0, v5
	s_and_saveexec_b64 s[0:1], vcc
	v_max_f32_e32 v0, v0, v0
	v_max_f32_e32 v5, v5, v5
	v_max_f32_e32 v0, v0, v5
	v_lshl_add_u32 v5, v2, 2, s27
	ds_write_b32 v5, v0
	s_or_b64 exec, exec, s[0:1]
	v_lshl_add_u32 v0, v9, 2, 0
	v_add_u32_e32 v0, 0x20000, v0
	s_waitcnt lgkmcnt(0)
	s_waitcnt lgkmcnt(0)
	s_barrier
	ds_read2_b32 v[136:137], v0 offset1:32
	ds_read2_b32 v[138:139], v0 offset0:64 offset1:96
	ds_read2_b32 v[140:141], v0 offset0:128 offset1:160
	ds_read2_b32 v[142:143], v0 offset0:192 offset1:224
	s_and_b64 s[0:1], s[30:31], vcc
	s_waitcnt lgkmcnt(3)
	v_max3_f32 v0, v136, 0, v137
	s_waitcnt lgkmcnt(2)
	v_max3_f32 v0, v0, v138, v139
	s_waitcnt lgkmcnt(1)
	v_max3_f32 v0, v0, v140, v141
	s_waitcnt lgkmcnt(0)
	v_max3_f32 v0, v0, v142, v143
	s_and_saveexec_b64 s[54:55], s[0:1]
	s_cbranch_execz .LBB0_34
	s_and_b64 s[0:1], s[52:53], exec
	s_cselect_b32 s1, s61, 0x6ce00000
	s_cselect_b32 s0, s23, 0xd000
	s_add_u32 s1, s16, s1
	s_addc_u32 s20, s17, 0
	s_mul_hi_i32 s28, s0, s50
	s_mul_i32 s0, s0, s50
	s_add_u32 s0, s1, s0
	s_addc_u32 s1, s20, s28
	v_ashrrev_i32_e32 v5, 31, v4
	v_mul_f32_e32 v136, 0x3c010204, v0
	v_lshl_add_u64 v[4:5], v[4:5], 2, s[0:1]
	global_store_dword v[4:5], v136, off
	s_branch .LBB0_34
